# kernel-wide static s_setprio 1 for waves 4-7; all per-cluster setprio toggles in the GEMM loops deleted
# speedup vs baseline: 1.0165x; 1.0165x over previous
; #define LAS __attribute__((address_space(3)))
; DI unsigned xb_add(unsigned* p, unsigned v) { return __hip_atomic_fetch_add(p, v, __ATOMIC_RELAXED, __HIP_MEMORY_SCOPE_AGENT); }
; DI unsigned xb_xcc_id() { return (unsigned)__builtin_amdgcn_s_getreg((3 << 11) | 20) & 0xFu; }
; #define PG8_LAS __attribute__((address_space(3)))
; DI XcdBarrier xcd_barrier_post(unsigned* bar, volatile LAS unsigned* st) {
;     XcdBarrier b; b.bar = bar; b.x = xb_xcc_id(); b.st = st;
;     if (threadIdx.x == 0) (void)xb_add(&bar[XB_XCNT(b.x)], 1u);
;     return b;
; __global__ void __launch_bounds__(NTHREADS, 2) fwd_megakernel(Args a) {
;     extern __shared__ __attribute__((aligned(16))) unsigned char lds[];
;     cg::grid_group grid = cg::this_grid();
;     PG8_LAS unsigned char* ldsg = (PG8_LAS unsigned char*)lds;
;     const int G = gridDim.x, bx = blockIdx.x;
;     bf16_t* wt = (bf16_t*)(a.ws + OFF_WT);
;     bf16_t* hbuf = (bf16_t*)(a.ws + OFF_H);
;     bf16_t* r1 = (bf16_t*)(a.ws + OFF_R1); bf16_t* r2 = (bf16_t*)(a.ws + OFF_R2); bf16_t* r3 = (bf16_t*)(a.ws + OFF_R3); bf16_t* r4 = (bf16_t*)(a.ws + OFF_R4);
;     { volatile LAS unsigned* bst = (volatile LAS unsigned*)((LAS unsigned char*)lds + LDS_MAIN);
;       if (threadIdx.x < 4) bst[threadIdx.x] = 0u;
;       __syncthreads();
;       (void)xcd_barrier_post((unsigned*)(a.ws + OFF_BAR), bst); }
_Z14fwd_megakernel4Args:
	s_mov_b32 s68, s2
	s_load_dwordx8 s[24:31], s[0:1], 0x80
	s_load_dword s2, s[0:1], 0xa0
	v_and_b32_e32 v252, 0x3ff, v0
	v_cmp_gt_u32_e32 vcc, 4, v252
	s_waitcnt lgkmcnt(0)
	v_writelane_b32 v253, s2, 0
	s_add_u32 s2, s0, 0x98
	s_addc_u32 s3, s1, 0
	v_writelane_b32 v253, s2, 1
	s_nop 1
	v_writelane_b32 v253, s3, 2
	s_and_saveexec_b64 s[4:5], vcc
	v_lshl_add_u32 v1, v252, 2, 0
	v_add_u32_e32 v1, 0x20000, v1
	v_mov_b32_e32 v2, 0
	ds_write_b32 v1, v2
	s_or_b64 exec, exec, s[4:5]
	v_readfirstlane_b32 s100, v252
	s_nop 3
	s_lshr_b32 s100, s100, 6
	s_cmp_ge_u32 s100, 4
	s_cbranch_scc0 .Lk_prio_done
	s_setprio 1
.Lk_prio_done:
	s_add_u32 s2, s28, 0x1f690000
	s_addc_u32 s3, s29, 0
	v_writelane_b32 v253, s2, 3
	s_waitcnt lgkmcnt(0)
	s_barrier
	v_writelane_b32 v253, s3, 4
	s_getreg_b32 s2, hwreg(HW_REG_XCC_ID, 0, 4)
	v_cmp_eq_u32_e64 s[6:7], 0, v252
	s_mov_b64 s[4:5], exec
	s_nop 0
	v_writelane_b32 v253, s6, 5
	s_nop 1
	v_writelane_b32 v253, s7, 6
	s_and_b64 s[6:7], s[4:5], s[6:7]
	s_mov_b64 exec, s[6:7]
	s_cbranch_execz .LBB0_5
	s_mov_b64 s[6:7], exec
	v_mbcnt_lo_u32_b32 v1, s6, 0
	v_mbcnt_hi_u32_b32 v1, s7, v1
	v_cmp_eq_u32_e32 vcc, 0, v1
	s_and_b64 s[8:9], exec, vcc
	s_mov_b64 exec, s[8:9]
	s_cbranch_execz .LBB0_5
	s_lshl_b32 s2, s2, 8
	s_and_b32 s2, s2, 0xf00
	s_bcnt1_i32_b64 s3, s[6:7]
	v_mov_b32_e32 v1, s2
	v_mov_b32_e32 v2, s3
	v_readlane_b32 s2, v253, 3
	v_readlane_b32 s3, v253, 4
	s_nop 4
	global_atomic_add v1, v2, s[2:3] offset:1024

; #define PG8_STAGE(bufoff, gbase, voff) do { _Pragma("unroll") for (int _i = 0; _i < 2; ++_i) \
;         __builtin_amdgcn_global_load_lds((const unsigned*)((const char*)(gbase) + (voff)[_i]), (PG8_LAS unsigned*)(lds + (bufoff) + ldsw + _i * 8192), 16, 0, 0); } while (0)
; #define PG8_LDA(dst, b, h) do { _Pragma("unroll") for (int m = 0; m < 4; ++m) _Pragma("unroll") for (int k = 0; k < 2; ++k) dst[m][k] = *(const PG8_LAS bf16x8*)(lds + PG8_SA(b, h) + aoff + m * 2048 + k * 1024); } while (0)
; #define PG8_LDB(dst, b, h) do { _Pragma("unroll") for (int n = 0; n < 2; ++n) _Pragma("unroll") for (int k = 0; k < 2; ++k) dst[n][k] = *(const PG8_LAS bf16x8*)(lds + PG8_SB(b, h) + boff + n * 2048 + k * 1024); } while (0)
; #define PG8_MMA(ai, bj, At, Bt) do { __builtin_amdgcn_s_setprio(1); _Pragma("unroll") for (int m = 0; m < 4; ++m) _Pragma("unroll") for (int n = 0; n < 2; ++n) _Pragma("unroll") for (int k = 0; k < 2; ++k) \
;         acc[ai][bj][m][n] = __builtin_amdgcn_mfma_f32_16x16x32_bf16(Bt[n][k], At[m][k], acc[ai][bj][m][n], 0, 0, 0); __builtin_amdgcn_s_setprio(0); } while (0)
; #define PG8_WAIT_V(n) asm volatile("s_waitcnt vmcnt(" #n ")" ::: "memory")
; #define PG8_WAIT_L(n) asm volatile("s_waitcnt lgkmcnt(" #n ")" ::: "memory")
; #define PG8_BAR __builtin_amdgcn_s_barrier()
; #define PG8_SCHED __builtin_amdgcn_sched_barrier(0)
; template <class Epi, class Sched>
; __device__ __forceinline__ void gemm_phase(PG8_LAS unsigned char* lds, const Gemm g, const Sched& S, const Epi& E) {
;     ...
;             PG8_LDB(B0, 0, 0); PG8_SCHED; PG8_LDA(At, 0, 0); PG8_STAGE(PG8_SA(1, 1), a1 + hstep, voffA);
;             PG8_WAIT_L(8); PG8_BAR; PG8_WAIT_L(0); PG8_MMA(0, 0, At, B0); PG8_BAR; PG8_SCHED;
;             PG8_LDB(B1, 0, 1); PG8_STAGE(PG8_SB(0, 0), b2, voffB);
;             PG8_BAR; PG8_WAIT_L(0); PG8_MMA(0, 1, At, B1); PG8_BAR;
;             PG8_LDA(At, 0, 1); PG8_STAGE(PG8_SA(0, 0), a2, voffA);
;             PG8_BAR; PG8_WAIT_L(0); PG8_MMA(1, 0, At, B0); PG8_BAR; PG8_SCHED;
;             PG8_STAGE(PG8_SB(0, 1), b2 + hstep, voffB);
;             PG8_WAIT_V(6); PG8_BAR; PG8_MMA(1, 1, At, B1); PG8_BAR;
.LBB0_185:
	s_add_u32 s16, s14, 0xfffc0080
	s_addc_u32 s17, s15, -1
	s_add_i32 s80, 0, 0x10000
	v_add_u32_e32 v140, s80, v231
	ds_read_b128 v[128:131], v140
	ds_read_b128 v[132:135], v140 offset:1024
	ds_read_b128 v[136:139], v140 offset:2048
	ds_read_b128 v[140:143], v140 offset:3072
	s_cmp_eq_u32 s79, 12
	s_cselect_b32 s19, s7, s17
	s_cselect_b32 s18, s13, s16
	s_cselect_b32 s17, s1, s78
	s_cselect_b32 s16, s76, s77
	v_lshl_add_u64 v[176:177], s[14:15], 0, v[200:201]
	s_add_i32 m0, s46, 0xc000
	ds_read_b128 v[144:147], v232
	ds_read_b128 v[148:151], v232 offset:1024
	ds_read_b128 v[152:155], v232 offset:2048
	ds_read_b128 v[156:159], v232 offset:3072
	ds_read_b128 v[160:163], v232 offset:4096
	ds_read_b128 v[164:167], v232 offset:5120
	ds_read_b128 v[168:171], v232 offset:6144
	ds_read_b128 v[172:175], v232 offset:7168
	global_load_lds_dwordx4 v[176:177], off
	v_lshl_add_u64 v[176:177], s[14:15], 0, v[202:203]
	s_add_i32 m0, s46, 0xe000
	s_nop 0
	global_load_lds_dwordx4 v[176:177], off
	s_waitcnt lgkmcnt(8)
	s_barrier
	s_waitcnt lgkmcnt(0)
	s_waitcnt lgkmcnt(0)
	v_mfma_f32_16x16x32_bf16 v[124:127], v[128:131], v[144:147], v[124:127]
	v_mfma_f32_16x16x32_bf16 v[116:119], v[136:139], v[144:147], v[116:119]
	v_mfma_f32_16x16x32_bf16 v[108:111], v[128:131], v[152:155], v[108:111]
	v_mfma_f32_16x16x32_bf16 v[100:103], v[136:139], v[152:155], v[100:103]
	v_mfma_f32_16x16x32_bf16 v[92:95], v[128:131], v[160:163], v[92:95]
	v_mfma_f32_16x16x32_bf16 v[84:87], v[136:139], v[160:163], v[84:87]
	v_mfma_f32_16x16x32_bf16 v[76:79], v[128:131], v[168:171], v[76:79]
	v_mfma_f32_16x16x32_bf16 v[68:71], v[136:139], v[168:171], v[68:71]
	v_mfma_f32_16x16x32_bf16 v[124:127], v[132:135], v[148:151], v[124:127]
	v_mfma_f32_16x16x32_bf16 v[116:119], v[140:143], v[148:151], v[116:119]
	v_mfma_f32_16x16x32_bf16 v[108:111], v[132:135], v[156:159], v[108:111]
	v_mfma_f32_16x16x32_bf16 v[100:103], v[140:143], v[156:159], v[100:103]
	v_mfma_f32_16x16x32_bf16 v[92:95], v[132:135], v[164:167], v[92:95]
	v_mfma_f32_16x16x32_bf16 v[84:87], v[140:143], v[164:167], v[84:87]
	v_mfma_f32_16x16x32_bf16 v[76:79], v[132:135], v[172:175], v[76:79]
	v_mfma_f32_16x16x32_bf16 v[68:71], v[140:143], v[172:175], v[68:71]
	s_barrier
	s_add_i32 s82, 0, 0x14000
	s_add_i32 s80, s80, s21
	v_add_u32_e32 v180, s82, v231
	v_lshl_add_u64 v[218:219], s[16:17], 0, v[188:189]
	s_mov_b32 m0, s80
	ds_read_b128 v[176:179], v180
	ds_read_b128 v[206:209], v180 offset:1024
	ds_read_b128 v[210:213], v180 offset:2048
	ds_read_b128 v[214:217], v180 offset:3072
	global_load_lds_dwordx4 v[218:219], off
	v_lshl_add_u64 v[220:221], s[16:17], 0, v[184:185]
	s_add_i32 m0, s80, 0x2000
	s_nop 0
	global_load_lds_dwordx4 v[220:221], off
	s_barrier
	s_waitcnt lgkmcnt(0)
	s_waitcnt lgkmcnt(0)
	v_mfma_f32_16x16x32_bf16 v[120:123], v[176:179], v[144:147], v[120:123]
	v_mfma_f32_16x16x32_bf16 v[112:115], v[210:213], v[144:147], v[112:115]
	v_mfma_f32_16x16x32_bf16 v[104:107], v[176:179], v[152:155], v[104:107]
	v_mfma_f32_16x16x32_bf16 v[96:99], v[210:213], v[152:155], v[96:99]
	v_mfma_f32_16x16x32_bf16 v[88:91], v[176:179], v[160:163], v[88:91]
	v_mfma_f32_16x16x32_bf16 v[80:83], v[210:213], v[160:163], v[80:83]
	v_mfma_f32_16x16x32_bf16 v[72:75], v[176:179], v[168:171], v[72:75]
	v_mfma_f32_16x16x32_bf16 v[64:67], v[210:213], v[168:171], v[64:67]
	v_mfma_f32_16x16x32_bf16 v[120:123], v[206:209], v[148:151], v[120:123]
	v_mfma_f32_16x16x32_bf16 v[112:115], v[214:217], v[148:151], v[112:115]
	v_mfma_f32_16x16x32_bf16 v[104:107], v[206:209], v[156:159], v[104:107]
	v_mfma_f32_16x16x32_bf16 v[96:99], v[214:217], v[156:159], v[96:99]
	v_mfma_f32_16x16x32_bf16 v[88:91], v[206:209], v[164:167], v[88:91]
	v_mfma_f32_16x16x32_bf16 v[80:83], v[214:217], v[164:167], v[80:83]
	v_mfma_f32_16x16x32_bf16 v[72:75], v[206:209], v[172:175], v[72:75]
	v_mfma_f32_16x16x32_bf16 v[64:67], v[214:217], v[172:175], v[64:67]
	s_mov_b32 m0, s46
	v_lshl_add_u64 v[222:223], s[18:19], 0, v[190:191]
	s_barrier
	ds_read_b128 v[144:147], v232 offset:16384
	ds_read_b128 v[148:151], v232 offset:17408
	ds_read_b128 v[152:155], v232 offset:18432
	ds_read_b128 v[156:159], v232 offset:19456
	ds_read_b128 v[160:163], v232 offset:20480
	ds_read_b128 v[164:167], v232 offset:21504
	ds_read_b128 v[168:171], v232 offset:22528
	ds_read_b128 v[172:175], v232 offset:23552
	global_load_lds_dwordx4 v[222:223], off
	v_lshl_add_u64 v[224:225], s[18:19], 0, v[186:187]
	s_mov_b32 m0, s47
	s_nop 0
	global_load_lds_dwordx4 v[224:225], off
	s_barrier
	s_waitcnt lgkmcnt(0)
	s_waitcnt lgkmcnt(0)
	v_mfma_f32_16x16x32_bf16 v[60:63], v[128:131], v[144:147], v[60:63]
	v_mfma_f32_16x16x32_bf16 v[52:55], v[136:139], v[144:147], v[52:55]
	v_mfma_f32_16x16x32_bf16 v[44:47], v[128:131], v[152:155], v[44:47]
	v_mfma_f32_16x16x32_bf16 v[36:39], v[136:139], v[152:155], v[36:39]
	v_mfma_f32_16x16x32_bf16 v[28:31], v[128:131], v[160:163], v[28:31]
	v_mfma_f32_16x16x32_bf16 v[20:23], v[136:139], v[160:163], v[20:23]
	v_mfma_f32_16x16x32_bf16 v[12:15], v[128:131], v[168:171], v[12:15]
	v_mfma_f32_16x16x32_bf16 v[4:7], v[136:139], v[168:171], v[4:7]
	v_mfma_f32_16x16x32_bf16 v[60:63], v[132:135], v[148:151], v[60:63]
	v_mfma_f32_16x16x32_bf16 v[52:55], v[140:143], v[148:151], v[52:55]
	v_mfma_f32_16x16x32_bf16 v[44:47], v[132:135], v[156:159], v[44:47]
	v_mfma_f32_16x16x32_bf16 v[36:39], v[140:143], v[156:159], v[36:39]
	v_mfma_f32_16x16x32_bf16 v[28:31], v[132:135], v[164:167], v[28:31]
	v_mfma_f32_16x16x32_bf16 v[20:23], v[140:143], v[164:167], v[20:23]
	v_mfma_f32_16x16x32_bf16 v[12:15], v[132:135], v[172:175], v[12:15]
	v_mfma_f32_16x16x32_bf16 v[4:7], v[140:143], v[172:175], v[4:7]
	s_barrier
; #define PG8_STAGE(bufoff, gbase, voff) do { _Pragma("unroll") for (int _i = 0; _i < 2; ++_i) \
;         __builtin_amdgcn_global_load_lds((const unsigned*)((const char*)(gbase) + (voff)[_i]), (PG8_LAS unsigned*)(lds + (bufoff) + ldsw + _i * 8192), 16, 0, 0); } while (0)
; #define PG8_LDA(dst, b, h) do { _Pragma("unroll") for (int m = 0; m < 4; ++m) _Pragma("unroll") for (int k = 0; k < 2; ++k) dst[m][k] = *(const PG8_LAS bf16x8*)(lds + PG8_SA(b, h) + aoff + m * 2048 + k * 1024); } while (0)
; #define PG8_LDB(dst, b, h) do { _Pragma("unroll") for (int n = 0; n < 2; ++n) _Pragma("unroll") for (int k = 0; k < 2; ++k) dst[n][k] = *(const PG8_LAS bf16x8*)(lds + PG8_SB(b, h) + boff + n * 2048 + k * 1024); } while (0)
; #define PG8_MMA(ai, bj, At, Bt) do { __builtin_amdgcn_s_setprio(1); _Pragma("unroll") for (int m = 0; m < 4; ++m) _Pragma("unroll") for (int n = 0; n < 2; ++n) _Pragma("unroll") for (int k = 0; k < 2; ++k) \
;         acc[ai][bj][m][n] = __builtin_amdgcn_mfma_f32_16x16x32_bf16(Bt[n][k], At[m][k], acc[ai][bj][m][n], 0, 0, 0); __builtin_amdgcn_s_setprio(0); } while (0)
; #define PG8_WAIT_V(n) asm volatile("s_waitcnt vmcnt(" #n ")" ::: "memory")
; #define PG8_WAIT_L(n) asm volatile("s_waitcnt lgkmcnt(" #n ")" ::: "memory")
; #define PG8_BAR __builtin_amdgcn_s_barrier()
; #define PG8_SCHED __builtin_amdgcn_sched_barrier(0)
; template <class Epi, class Sched>
; __device__ __forceinline__ void gemm_phase(PG8_LAS unsigned char* lds, const Gemm g, const Sched& S, const Epi& E) {
;     ...
;             PG8_WAIT_V(6); PG8_BAR; PG8_MMA(1, 1, At, B1); PG8_BAR;
;             PG8_LDB(B0, 1, 0); PG8_SCHED; PG8_LDA(At, 1, 0); PG8_STAGE(PG8_SA(0, 1), a2 + hstep, voffA);
;             PG8_WAIT_L(8); PG8_BAR; PG8_WAIT_L(0); PG8_MMA(0, 0, At, B0); PG8_BAR; PG8_SCHED;
;             PG8_LDB(B1, 1, 1); PG8_STAGE(PG8_SB(1, 0), b3, voffB);
;             PG8_BAR; PG8_WAIT_L(0); PG8_MMA(0, 1, At, B1); PG8_BAR;
;             PG8_LDA(At, 1, 1); PG8_STAGE(PG8_SA(1, 0), a3, voffA);
;             PG8_BAR; PG8_WAIT_L(0); PG8_MMA(1, 0, At, B0); PG8_BAR; PG8_SCHED;
	s_add_u32 s80, s16, 0x40000
	s_addc_u32 s81, s17, 0
	s_add_i32 s82, s82, s21
	v_lshl_add_u64 v[128:129], s[80:81], 0, v[188:189]
	s_mov_b32 m0, s82
	s_nop 0
	global_load_lds_dwordx4 v[128:129], off
	v_lshl_add_u64 v[128:129], s[80:81], 0, v[184:185]
	s_add_i32 m0, s82, 0x2000
	s_nop 0
	global_load_lds_dwordx4 v[128:129], off
	s_waitcnt vmcnt(6)
	s_barrier
	v_mfma_f32_16x16x32_bf16 v[56:59], v[176:179], v[144:147], v[56:59]
	v_mfma_f32_16x16x32_bf16 v[48:51], v[210:213], v[144:147], v[48:51]
	v_mfma_f32_16x16x32_bf16 v[40:43], v[176:179], v[152:155], v[40:43]
	v_mfma_f32_16x16x32_bf16 v[32:35], v[210:213], v[152:155], v[32:35]
	v_mfma_f32_16x16x32_bf16 v[24:27], v[176:179], v[160:163], v[24:27]
	v_mfma_f32_16x16x32_bf16 v[16:19], v[210:213], v[160:163], v[16:19]
	v_mfma_f32_16x16x32_bf16 v[8:11], v[176:179], v[168:171], v[8:11]
	v_mfma_f32_16x16x32_bf16 v[0:3], v[210:213], v[168:171], v[0:3]
	v_mfma_f32_16x16x32_bf16 v[56:59], v[206:209], v[148:151], v[56:59]
	v_mfma_f32_16x16x32_bf16 v[48:51], v[214:217], v[148:151], v[48:51]
	v_mfma_f32_16x16x32_bf16 v[40:43], v[206:209], v[156:159], v[40:43]
	v_mfma_f32_16x16x32_bf16 v[32:35], v[214:217], v[156:159], v[32:35]
	v_mfma_f32_16x16x32_bf16 v[24:27], v[206:209], v[164:167], v[24:27]
	v_mfma_f32_16x16x32_bf16 v[16:19], v[214:217], v[164:167], v[16:19]
	v_mfma_f32_16x16x32_bf16 v[8:11], v[206:209], v[172:175], v[8:11]
	v_mfma_f32_16x16x32_bf16 v[0:3], v[214:217], v[172:175], v[0:3]
	s_add_i32 s80, 0, 0x18000
	v_add_u32_e32 v140, s80, v231
	s_barrier
	ds_read_b128 v[128:131], v140
	ds_read_b128 v[132:135], v140 offset:1024
	ds_read_b128 v[136:139], v140 offset:2048
	ds_read_b128 v[140:143], v140 offset:3072
	s_add_u32 s18, s18, 0x40000
	s_addc_u32 s19, s19, 0
	s_mov_b32 m0, s70
	v_lshl_add_u64 v[176:177], s[18:19], 0, v[190:191]
	ds_read_b128 v[144:147], v232 offset:32768
	ds_read_b128 v[148:151], v232 offset:33792
	ds_read_b128 v[152:155], v232 offset:34816
	ds_read_b128 v[156:159], v232 offset:35840
	ds_read_b128 v[160:163], v232 offset:36864
	ds_read_b128 v[164:167], v232 offset:37888
	ds_read_b128 v[168:171], v232 offset:38912
	ds_read_b128 v[172:175], v232 offset:39936
	global_load_lds_dwordx4 v[176:177], off
	v_lshl_add_u64 v[176:177], s[18:19], 0, v[186:187]
	s_mov_b32 m0, s71
	s_nop 0
	global_load_lds_dwordx4 v[176:177], off
	s_waitcnt lgkmcnt(8)
	s_barrier
	s_waitcnt lgkmcnt(0)
	s_waitcnt lgkmcnt(0)
	v_mfma_f32_16x16x32_bf16 v[124:127], v[128:131], v[144:147], v[124:127]
	v_mfma_f32_16x16x32_bf16 v[116:119], v[136:139], v[144:147], v[116:119]
	v_mfma_f32_16x16x32_bf16 v[108:111], v[128:131], v[152:155], v[108:111]
	v_mfma_f32_16x16x32_bf16 v[100:103], v[136:139], v[152:155], v[100:103]
	v_mfma_f32_16x16x32_bf16 v[92:95], v[128:131], v[160:163], v[92:95]
	v_mfma_f32_16x16x32_bf16 v[84:87], v[136:139], v[160:163], v[84:87]
	v_mfma_f32_16x16x32_bf16 v[76:79], v[128:131], v[168:171], v[76:79]
	v_mfma_f32_16x16x32_bf16 v[68:71], v[136:139], v[168:171], v[68:71]
	v_mfma_f32_16x16x32_bf16 v[124:127], v[132:135], v[148:151], v[124:127]
	v_mfma_f32_16x16x32_bf16 v[116:119], v[140:143], v[148:151], v[116:119]
	v_mfma_f32_16x16x32_bf16 v[108:111], v[132:135], v[156:159], v[108:111]
	v_mfma_f32_16x16x32_bf16 v[100:103], v[140:143], v[156:159], v[100:103]
	v_mfma_f32_16x16x32_bf16 v[92:95], v[132:135], v[164:167], v[92:95]
	v_mfma_f32_16x16x32_bf16 v[84:87], v[140:143], v[164:167], v[84:87]
	v_mfma_f32_16x16x32_bf16 v[76:79], v[132:135], v[172:175], v[76:79]
	v_mfma_f32_16x16x32_bf16 v[68:71], v[140:143], v[172:175], v[68:71]
	s_barrier
	s_add_i32 s18, 0, 0x1c000
	s_add_i32 s19, s80, s21
	v_add_u32_e32 v180, s18, v231
	v_lshl_add_u64 v[218:219], v[218:219], 0, s[38:39]
	s_mov_b32 m0, s19
	ds_read_b128 v[176:179], v180
	ds_read_b128 v[206:209], v180 offset:1024
	ds_read_b128 v[210:213], v180 offset:2048
	ds_read_b128 v[214:217], v180 offset:3072
	global_load_lds_dwordx4 v[218:219], off
	v_lshl_add_u64 v[218:219], v[220:221], 0, s[38:39]
	s_add_i32 m0, s19, 0x2000
	s_nop 0
	global_load_lds_dwordx4 v[218:219], off
	s_barrier
	s_waitcnt lgkmcnt(0)
	s_waitcnt lgkmcnt(0)
	v_mfma_f32_16x16x32_bf16 v[120:123], v[176:179], v[144:147], v[120:123]
	v_mfma_f32_16x16x32_bf16 v[112:115], v[210:213], v[144:147], v[112:115]
	v_mfma_f32_16x16x32_bf16 v[104:107], v[176:179], v[152:155], v[104:107]
	v_mfma_f32_16x16x32_bf16 v[96:99], v[210:213], v[152:155], v[96:99]
	v_mfma_f32_16x16x32_bf16 v[88:91], v[176:179], v[160:163], v[88:91]
	v_mfma_f32_16x16x32_bf16 v[80:83], v[210:213], v[160:163], v[80:83]
	v_mfma_f32_16x16x32_bf16 v[72:75], v[176:179], v[168:171], v[72:75]
	v_mfma_f32_16x16x32_bf16 v[64:67], v[210:213], v[168:171], v[64:67]
	v_mfma_f32_16x16x32_bf16 v[120:123], v[206:209], v[148:151], v[120:123]
	v_mfma_f32_16x16x32_bf16 v[112:115], v[214:217], v[148:151], v[112:115]
	v_mfma_f32_16x16x32_bf16 v[104:107], v[206:209], v[156:159], v[104:107]
	v_mfma_f32_16x16x32_bf16 v[96:99], v[214:217], v[156:159], v[96:99]
	v_mfma_f32_16x16x32_bf16 v[88:91], v[206:209], v[164:167], v[88:91]
	v_mfma_f32_16x16x32_bf16 v[80:83], v[214:217], v[164:167], v[80:83]
	v_mfma_f32_16x16x32_bf16 v[72:75], v[206:209], v[172:175], v[72:75]
	v_mfma_f32_16x16x32_bf16 v[64:67], v[214:217], v[172:175], v[64:67]
	s_mov_b32 m0, s72
	v_lshl_add_u64 v[218:219], v[222:223], 0, s[38:39]
	s_barrier
	ds_read_b128 v[144:147], v232 offset:49152
	ds_read_b128 v[148:151], v232 offset:50176
	ds_read_b128 v[152:155], v232 offset:51200
	ds_read_b128 v[156:159], v232 offset:52224
	ds_read_b128 v[160:163], v232 offset:53248
	ds_read_b128 v[164:167], v232 offset:54272
	ds_read_b128 v[168:171], v232 offset:55296
	ds_read_b128 v[172:175], v232 offset:56320
	global_load_lds_dwordx4 v[218:219], off
	v_lshl_add_u64 v[218:219], v[224:225], 0, s[38:39]
	s_mov_b32 m0, s73
	s_nop 0
	global_load_lds_dwordx4 v[218:219], off
	s_barrier
; #define PG8_STAGE(bufoff, gbase, voff) do { _Pragma("unroll") for (int _i = 0; _i < 2; ++_i) \
;         __builtin_amdgcn_global_load_lds((const unsigned*)((const char*)(gbase) + (voff)[_i]), (PG8_LAS unsigned*)(lds + (bufoff) + ldsw + _i * 8192), 16, 0, 0); } while (0)
; #define PG8_MMA(ai, bj, At, Bt) do { __builtin_amdgcn_s_setprio(1); _Pragma("unroll") for (int m = 0; m < 4; ++m) _Pragma("unroll") for (int n = 0; n < 2; ++n) _Pragma("unroll") for (int k = 0; k < 2; ++k) \
;         acc[ai][bj][m][n] = __builtin_amdgcn_mfma_f32_16x16x32_bf16(Bt[n][k], At[m][k], acc[ai][bj][m][n], 0, 0, 0); __builtin_amdgcn_s_setprio(0); } while (0)
; #define PG8_WAIT_V(n) asm volatile("s_waitcnt vmcnt(" #n ")" ::: "memory")
; #define PG8_WAIT_L(n) asm volatile("s_waitcnt lgkmcnt(" #n ")" ::: "memory")
; #define PG8_BAR __builtin_amdgcn_s_barrier()
; #define PG8_SCHED __builtin_amdgcn_sched_barrier(0)
; template <class Epi, class Sched>
; __device__ __forceinline__ void gemm_phase(PG8_LAS unsigned char* lds, const Gemm g, const Sched& S, const Epi& E) {
;     ...
;             PG8_BAR; PG8_WAIT_L(0); PG8_MMA(1, 0, At, B0); PG8_BAR; PG8_SCHED;
;             PG8_STAGE(PG8_SB(1, 1), b3 + hstep, voffB);
;             PG8_WAIT_V(6); PG8_BAR; PG8_MMA(1, 1, At, B1); PG8_BAR;
;         }
	s_waitcnt lgkmcnt(0)
	s_waitcnt lgkmcnt(0)
	v_mfma_f32_16x16x32_bf16 v[60:63], v[128:131], v[144:147], v[60:63]
	v_mfma_f32_16x16x32_bf16 v[52:55], v[136:139], v[144:147], v[52:55]
	v_mfma_f32_16x16x32_bf16 v[44:47], v[128:131], v[152:155], v[44:47]
	v_mfma_f32_16x16x32_bf16 v[36:39], v[136:139], v[152:155], v[36:39]
	v_mfma_f32_16x16x32_bf16 v[28:31], v[128:131], v[160:163], v[28:31]
	v_mfma_f32_16x16x32_bf16 v[20:23], v[136:139], v[160:163], v[20:23]
	v_mfma_f32_16x16x32_bf16 v[12:15], v[128:131], v[168:171], v[12:15]
	v_mfma_f32_16x16x32_bf16 v[4:7], v[136:139], v[168:171], v[4:7]
	v_mfma_f32_16x16x32_bf16 v[60:63], v[132:135], v[148:151], v[60:63]
	v_mfma_f32_16x16x32_bf16 v[52:55], v[140:143], v[148:151], v[52:55]
	v_mfma_f32_16x16x32_bf16 v[44:47], v[132:135], v[156:159], v[44:47]
	v_mfma_f32_16x16x32_bf16 v[36:39], v[140:143], v[156:159], v[36:39]
	v_mfma_f32_16x16x32_bf16 v[28:31], v[132:135], v[164:167], v[28:31]
	v_mfma_f32_16x16x32_bf16 v[20:23], v[140:143], v[164:167], v[20:23]
	v_mfma_f32_16x16x32_bf16 v[12:15], v[132:135], v[172:175], v[12:15]
	v_mfma_f32_16x16x32_bf16 v[4:7], v[140:143], v[172:175], v[4:7]
	s_barrier
	s_add_u32 s16, s16, 0x40080
	s_addc_u32 s17, s17, 0
	s_add_i32 s18, s18, s21
	v_lshl_add_u64 v[128:129], s[16:17], 0, v[188:189]
	s_mov_b32 m0, s18
	s_nop 0
	global_load_lds_dwordx4 v[128:129], off
	v_lshl_add_u64 v[128:129], s[16:17], 0, v[184:185]
	s_add_i32 m0, s18, 0x2000
	s_nop 0
	global_load_lds_dwordx4 v[128:129], off
	s_waitcnt vmcnt(6)
	s_barrier
	v_mfma_f32_16x16x32_bf16 v[56:59], v[176:179], v[144:147], v[56:59]
	v_mfma_f32_16x16x32_bf16 v[48:51], v[210:213], v[144:147], v[48:51]
	v_mfma_f32_16x16x32_bf16 v[40:43], v[176:179], v[152:155], v[40:43]
	v_mfma_f32_16x16x32_bf16 v[32:35], v[210:213], v[152:155], v[32:35]
	v_mfma_f32_16x16x32_bf16 v[24:27], v[176:179], v[160:163], v[24:27]
	v_mfma_f32_16x16x32_bf16 v[16:19], v[210:213], v[160:163], v[16:19]
	v_mfma_f32_16x16x32_bf16 v[8:11], v[176:179], v[168:171], v[8:11]
	v_mfma_f32_16x16x32_bf16 v[0:3], v[210:213], v[168:171], v[0:3]
	v_mfma_f32_16x16x32_bf16 v[56:59], v[206:209], v[148:151], v[56:59]
	v_mfma_f32_16x16x32_bf16 v[48:51], v[214:217], v[148:151], v[48:51]
	v_mfma_f32_16x16x32_bf16 v[40:43], v[206:209], v[156:159], v[40:43]
	v_mfma_f32_16x16x32_bf16 v[32:35], v[214:217], v[156:159], v[32:35]
	v_mfma_f32_16x16x32_bf16 v[24:27], v[206:209], v[164:167], v[24:27]
	v_mfma_f32_16x16x32_bf16 v[16:19], v[214:217], v[164:167], v[16:19]
	v_mfma_f32_16x16x32_bf16 v[8:11], v[206:209], v[172:175], v[8:11]
	v_mfma_f32_16x16x32_bf16 v[0:3], v[214:217], v[172:175], v[0:3]
	s_add_i32 s79, s79, 2
	s_add_u32 s14, s14, 0x100
	s_addc_u32 s15, s15, 0
	s_add_u32 s77, s77, 0x100
	s_addc_u32 s78, s78, 0
	s_cmp_gt_u32 s79, 13
	s_barrier
	s_cbranch_scc0 .LBB0_185
	s_cmp_gt_i32 s75, 7
	s_mov_b64 s[14:15], -1
	s_cbranch_scc0 .LBB0_188
; DI void store8(bf16_t* p, f32x4 a, f32x4 b) { u32x4 w = {cvt_pk_bf16(a[0], a[1]), cvt_pk_bf16(a[2], a[3]), cvt_pk_bf16(b[0], b[1]), cvt_pk_bf16(b[2], b[3])}; *(u32x4*)p = w; }
;     DI void operator()(const AccT& acc, const pg8::Unit& u, int wr, int wc, int fr, int fq) const {
;     ...
;         } else {
;             bf16_t* dst = v + (pn - 8) * 256 + cl;
; #pragma unroll
;             for (int ai = 0; ai < 2; ++ai)
; #pragma unroll
;                 for (int m = 0; m < 4; ++m) { const size_t row = (size_t)pm * 256 + lrow0 + ai * 128 + m * 16;
; #pragma unroll
;                     for (int bj = 0; bj < 2; ++bj) store8(dst + row * 2048 + bj * 128, acc[ai][bj][m][0], acc[ai][bj][m][1]); }
;         }
	s_lshl_b32 s14, s75, 9
	s_mov_b32 s15, s68
	s_ashr_i32 s13, s12, 31
	v_lshl_add_u64 v[128:129], v[196:197], 0, s[14:15]
	s_lshl_b64 s[14:15], s[12:13], 20
	v_lshl_add_u64 v[128:129], v[128:129], 0, s[14:15]
	v_lshl_add_u64 v[128:129], v[128:129], 0, v[194:195]
	v_cvt_pk_bf16_f32 v130, v124, v125
	v_cvt_pk_bf16_f32 v131, v126, v127
	v_cvt_pk_bf16_f32 v132, v116, v117
	v_cvt_pk_bf16_f32 v133, v118, v119
	s_mov_b32 s1, 0xf000
	global_store_dwordx4 v[128:129], v[130:133], off offset:-4096
	v_add_co_u32_e32 v134, vcc, s1, v128
	s_nop 0
	v_cvt_pk_bf16_f32 v130, v120, v121
	v_cvt_pk_bf16_f32 v131, v122, v123
	v_cvt_pk_bf16_f32 v132, v112, v113
	v_cvt_pk_bf16_f32 v133, v114, v115
	global_store_dwordx4 v[128:129], v[130:133], off offset:-3840
	v_addc_co_u32_e32 v135, vcc, 0, v129, vcc
	s_nop 0
	v_cvt_pk_bf16_f32 v130, v108, v109
	v_cvt_pk_bf16_f32 v131, v110, v111
	v_cvt_pk_bf16_f32 v132, v100, v101
	v_cvt_pk_bf16_f32 v133, v102, v103
	s_mov_b32 s1, 0x1f000
	global_store_dwordx4 v[134:135], v[130:133], off
	s_mov_b64 s[14:15], 0
	s_nop 0
	v_cvt_pk_bf16_f32 v130, v104, v105
	v_cvt_pk_bf16_f32 v131, v106, v107
	v_cvt_pk_bf16_f32 v132, v96, v97
	v_cvt_pk_bf16_f32 v133, v98, v99
	global_store_dwordx4 v[134:135], v[130:133], off offset:256
	v_add_co_u32_e32 v134, vcc, s1, v128
	s_nop 0
	v_cvt_pk_bf16_f32 v130, v92, v93
	v_cvt_pk_bf16_f32 v131, v94, v95
	v_cvt_pk_bf16_f32 v132, v84, v85
	v_cvt_pk_bf16_f32 v133, v86, v87
	s_nop 0
	v_addc_co_u32_e32 v135, vcc, 0, v129, vcc
	s_mov_b32 s1, 0x2f000
	global_store_dwordx4 v[134:135], v[130:133], off
	s_nop 1
	v_cvt_pk_bf16_f32 v130, v88, v89
	v_cvt_pk_bf16_f32 v131, v90, v91
	v_cvt_pk_bf16_f32 v132, v80, v81
	v_cvt_pk_bf16_f32 v133, v82, v83
	global_store_dwordx4 v[134:135], v[130:133], off offset:256
	v_add_co_u32_e32 v134, vcc, s1, v128
	s_nop 0
	v_cvt_pk_bf16_f32 v130, v76, v77
	v_cvt_pk_bf16_f32 v131, v78, v79
	v_cvt_pk_bf16_f32 v132, v68, v69
	v_cvt_pk_bf16_f32 v133, v70, v71
	s_nop 0
	v_addc_co_u32_e32 v135, vcc, 0, v129, vcc
	s_mov_b32 s1, 0x7f000
	global_store_dwordx4 v[134:135], v[130:133], off
	s_nop 1
	v_cvt_pk_bf16_f32 v130, v72, v73
	v_cvt_pk_bf16_f32 v131, v74, v75
	v_cvt_pk_bf16_f32 v132, v64, v65
	v_cvt_pk_bf16_f32 v133, v66, v67
	global_store_dwordx4 v[134:135], v[130:133], off offset:256
	v_add_co_u32_e32 v134, vcc, s1, v128
	s_nop 0
	v_cvt_pk_bf16_f32 v130, v60, v61
	v_cvt_pk_bf16_f32 v131, v62, v63
	v_cvt_pk_bf16_f32 v132, v52, v53
	v_cvt_pk_bf16_f32 v133, v54, v55
	s_nop 0
	v_addc_co_u32_e32 v135, vcc, 0, v129, vcc
	s_mov_b32 s1, 0x8f000
	global_store_dwordx4 v[134:135], v[130:133], off
	s_nop 1
	v_cvt_pk_bf16_f32 v130, v56, v57
	v_cvt_pk_bf16_f32 v131, v58, v59
	v_cvt_pk_bf16_f32 v132, v48, v49
	v_cvt_pk_bf16_f32 v133, v50, v51
	global_store_dwordx4 v[134:135], v[130:133], off offset:256
	v_add_co_u32_e32 v134, vcc, s1, v128
	s_nop 0
	v_cvt_pk_bf16_f32 v130, v44, v45
	v_cvt_pk_bf16_f32 v131, v46, v47
	v_cvt_pk_bf16_f32 v132, v36, v37
	v_cvt_pk_bf16_f32 v133, v38, v39
	s_nop 0
	v_addc_co_u32_e32 v135, vcc, 0, v129, vcc
	s_mov_b32 s1, 0x9f000
	global_store_dwordx4 v[134:135], v[130:133], off
	s_nop 1
	v_cvt_pk_bf16_f32 v130, v40, v41
	v_cvt_pk_bf16_f32 v131, v42, v43
	v_cvt_pk_bf16_f32 v132, v32, v33
	v_cvt_pk_bf16_f32 v133, v34, v35
	global_store_dwordx4 v[134:135], v[130:133], off offset:256
	v_add_co_u32_e32 v134, vcc, s1, v128
	s_nop 0
	v_cvt_pk_bf16_f32 v130, v28, v29
	v_cvt_pk_bf16_f32 v131, v30, v31
	v_cvt_pk_bf16_f32 v132, v20, v21
	v_cvt_pk_bf16_f32 v133, v22, v23
	s_nop 0
	v_addc_co_u32_e32 v135, vcc, 0, v129, vcc
	s_mov_b32 s1, 0xaf000
	global_store_dwordx4 v[134:135], v[130:133], off
	s_nop 1
	v_cvt_pk_bf16_f32 v130, v24, v25
	v_cvt_pk_bf16_f32 v131, v26, v27
	v_cvt_pk_bf16_f32 v132, v16, v17
	v_cvt_pk_bf16_f32 v133, v18, v19
	global_store_dwordx4 v[134:135], v[130:133], off offset:256
	v_add_co_u32_e32 v134, vcc, s1, v128
	s_nop 0
	v_cvt_pk_bf16_f32 v130, v12, v13
	v_cvt_pk_bf16_f32 v131, v14, v15
	v_cvt_pk_bf16_f32 v132, v4, v5
	v_cvt_pk_bf16_f32 v133, v6, v7
	s_nop 0
	v_addc_co_u32_e32 v135, vcc, 0, v129, vcc
	global_store_dwordx4 v[134:135], v[130:133], off
	v_cvt_pk_bf16_f32 v128, v8, v9
	v_cvt_pk_bf16_f32 v129, v10, v11
	s_nop 1
	v_cvt_pk_bf16_f32 v130, v0, v1
	v_cvt_pk_bf16_f32 v131, v2, v3
	global_store_dwordx4 v[134:135], v[128:131], off offset:256

; #define PG8_STAGE(bufoff, gbase, voff) do { _Pragma("unroll") for (int _i = 0; _i < 2; ++_i) \
;         __builtin_amdgcn_global_load_lds((const unsigned*)((const char*)(gbase) + (voff)[_i]), (PG8_LAS unsigned*)(lds + (bufoff) + ldsw + _i * 8192), 16, 0, 0); } while (0)
; #define PG8_LDA(dst, b, h) do { _Pragma("unroll") for (int m = 0; m < 4; ++m) _Pragma("unroll") for (int k = 0; k < 2; ++k) dst[m][k] = *(const PG8_LAS bf16x8*)(lds + PG8_SA(b, h) + aoff + m * 2048 + k * 1024); } while (0)
; #define PG8_LDB(dst, b, h) do { _Pragma("unroll") for (int n = 0; n < 2; ++n) _Pragma("unroll") for (int k = 0; k < 2; ++k) dst[n][k] = *(const PG8_LAS bf16x8*)(lds + PG8_SB(b, h) + boff + n * 2048 + k * 1024); } while (0)
; #define PG8_MMA(ai, bj, At, Bt) do { __builtin_amdgcn_s_setprio(1); _Pragma("unroll") for (int m = 0; m < 4; ++m) _Pragma("unroll") for (int n = 0; n < 2; ++n) _Pragma("unroll") for (int k = 0; k < 2; ++k) \
;         acc[ai][bj][m][n] = __builtin_amdgcn_mfma_f32_16x16x32_bf16(Bt[n][k], At[m][k], acc[ai][bj][m][n], 0, 0, 0); __builtin_amdgcn_s_setprio(0); } while (0)
; #define PG8_WAIT_V(n) asm volatile("s_waitcnt vmcnt(" #n ")" ::: "memory")
; #define PG8_WAIT_L(n) asm volatile("s_waitcnt lgkmcnt(" #n ")" ::: "memory")
; #define PG8_BAR __builtin_amdgcn_s_barrier()
; #define PG8_SCHED __builtin_amdgcn_sched_barrier(0)
; template <class Epi, class Sched>
; __device__ __forceinline__ void gemm_phase(PG8_LAS unsigned char* lds, const Gemm g, const Sched& S, const Epi& E) {
;     ...
;             PG8_LDB(B0, 0, 0); PG8_SCHED; PG8_LDA(At, 0, 0); PG8_STAGE(PG8_SA(1, 1), a1 + hstep, voffA);
;             PG8_WAIT_L(8); PG8_BAR; PG8_WAIT_L(0); PG8_MMA(0, 0, At, B0); PG8_BAR; PG8_SCHED;
;             PG8_LDB(B1, 0, 1); PG8_STAGE(PG8_SB(0, 0), b2, voffB);
;             PG8_BAR; PG8_WAIT_L(0); PG8_MMA(0, 1, At, B1); PG8_BAR;
;             PG8_LDA(At, 0, 1); PG8_STAGE(PG8_SA(0, 0), a2, voffA);
;             PG8_BAR; PG8_WAIT_L(0); PG8_MMA(1, 0, At, B0); PG8_BAR; PG8_SCHED;
;             PG8_STAGE(PG8_SB(0, 1), b2 + hstep, voffB);
;             PG8_WAIT_V(6); PG8_BAR; PG8_MMA(1, 1, At, B1); PG8_BAR;
.LBB0_516:
	s_add_u32 s70, s20, 0xfffc0080
	s_addc_u32 s71, s21, -1
	s_add_i32 vcc_lo, 0, 0x10000
	v_add_u32_e32 v68, vcc_lo, v206
	ds_read_b128 v[48:51], v68
	ds_read_b128 v[56:59], v68 offset:1024
	ds_read_b128 v[60:63], v68 offset:2048
	ds_read_b128 v[68:71], v68 offset:3072
	s_cmp_eq_u32 s89, 12
	s_cselect_b32 s73, s11, s71
	s_cselect_b32 s72, s17, s70
	s_cselect_b32 s71, s9, s88
	s_cselect_b32 s70, s82, s83
	v_lshl_add_u64 v[192:193], s[20:21], 0, v[176:177]
	s_add_i32 m0, s19, 0xc000
	ds_read_b128 v[128:131], v208
	ds_read_b128 v[140:143], v208 offset:1024
	ds_read_b128 v[148:151], v208 offset:2048
	ds_read_b128 v[156:159], v208 offset:3072
	ds_read_b128 v[160:163], v208 offset:4096
	ds_read_b128 v[164:167], v208 offset:5120
	ds_read_b128 v[184:187], v208 offset:6144
	ds_read_b128 v[188:191], v208 offset:7168
	global_load_lds_dwordx4 v[192:193], off
	v_lshl_add_u64 v[192:193], s[20:21], 0, v[178:179]
	s_add_i32 m0, s19, 0xe000
	s_nop 0
	global_load_lds_dwordx4 v[192:193], off
	s_waitcnt lgkmcnt(8)
	s_barrier
	s_waitcnt lgkmcnt(0)
	s_waitcnt lgkmcnt(0)
	v_mfma_f32_16x16x32_bf16 v[152:155], v[48:51], v[128:131], v[152:155]
	v_mfma_f32_16x16x32_bf16 v[144:147], v[60:63], v[128:131], v[144:147]
	v_mfma_f32_16x16x32_bf16 v[124:127], v[48:51], v[148:151], v[124:127]
	v_mfma_f32_16x16x32_bf16 v[120:123], v[60:63], v[148:151], v[120:123]
	v_mfma_f32_16x16x32_bf16 v[108:111], v[48:51], v[160:163], v[108:111]
	v_mfma_f32_16x16x32_bf16 v[104:107], v[60:63], v[160:163], v[104:107]
	v_mfma_f32_16x16x32_bf16 v[92:95], v[48:51], v[184:187], v[92:95]
	v_mfma_f32_16x16x32_bf16 v[88:91], v[60:63], v[184:187], v[88:91]
	v_mfma_f32_16x16x32_bf16 v[152:155], v[56:59], v[140:143], v[152:155]
	v_mfma_f32_16x16x32_bf16 v[144:147], v[68:71], v[140:143], v[144:147]
	v_mfma_f32_16x16x32_bf16 v[124:127], v[56:59], v[156:159], v[124:127]
	v_mfma_f32_16x16x32_bf16 v[120:123], v[68:71], v[156:159], v[120:123]
	v_mfma_f32_16x16x32_bf16 v[108:111], v[56:59], v[164:167], v[108:111]
	v_mfma_f32_16x16x32_bf16 v[104:107], v[68:71], v[164:167], v[104:107]
	v_mfma_f32_16x16x32_bf16 v[92:95], v[56:59], v[188:191], v[92:95]
	v_mfma_f32_16x16x32_bf16 v[88:91], v[68:71], v[188:191], v[88:91]
	s_barrier
	s_add_i32 s69, 0, 0x14000
	v_add_u32_e32 v204, s69, v206
	s_add_i32 vcc_lo, vcc_lo, s74
	ds_read_b128 v[192:195], v204
	ds_read_b128 v[196:199], v204 offset:1024
	ds_read_b128 v[200:203], v204 offset:2048
	ds_read_b128 v[210:213], v204 offset:3072
	v_lshl_add_u64 v[204:205], s[70:71], 0, v[180:181]
	s_mov_b32 m0, vcc_lo
	v_lshl_add_u64 v[214:215], s[70:71], 0, v[168:169]
	global_load_lds_dwordx4 v[204:205], off
	s_add_i32 m0, vcc_lo, 0x2000
	s_nop 0
	global_load_lds_dwordx4 v[214:215], off
	s_barrier
	s_waitcnt lgkmcnt(0)
	s_waitcnt lgkmcnt(0)
	v_mfma_f32_16x16x32_bf16 v[136:139], v[192:195], v[128:131], v[136:139]
	v_mfma_f32_16x16x32_bf16 v[116:119], v[192:195], v[148:151], v[116:119]
	v_mfma_f32_16x16x32_bf16 v[112:115], v[200:203], v[148:151], v[112:115]
	v_mfma_f32_16x16x32_bf16 v[100:103], v[192:195], v[160:163], v[100:103]
	v_mfma_f32_16x16x32_bf16 v[96:99], v[200:203], v[160:163], v[96:99]
	v_mfma_f32_16x16x32_bf16 v[84:87], v[192:195], v[184:187], v[84:87]
	v_mfma_f32_16x16x32_bf16 v[80:83], v[200:203], v[184:187], v[80:83]
	v_mfma_f32_16x16x32_bf16 v[136:139], v[196:199], v[140:143], v[136:139]
	v_mfma_f32_16x16x32_bf16 v[128:131], v[200:203], v[128:131], v[132:135]
	v_mfma_f32_16x16x32_bf16 v[116:119], v[196:199], v[156:159], v[116:119]
	v_mfma_f32_16x16x32_bf16 v[112:115], v[210:213], v[156:159], v[112:115]
	v_mfma_f32_16x16x32_bf16 v[100:103], v[196:199], v[164:167], v[100:103]
	v_mfma_f32_16x16x32_bf16 v[96:99], v[210:213], v[164:167], v[96:99]
	v_mfma_f32_16x16x32_bf16 v[84:87], v[196:199], v[188:191], v[84:87]
	v_mfma_f32_16x16x32_bf16 v[80:83], v[210:213], v[188:191], v[80:83]
	v_mfma_f32_16x16x32_bf16 v[128:131], v[210:213], v[140:143], v[128:131]
	s_mov_b32 m0, s19
	v_lshl_add_u64 v[216:217], s[72:73], 0, v[172:173]
	s_barrier
	ds_read_b128 v[132:135], v208 offset:16384
	ds_read_b128 v[140:143], v208 offset:17408
	ds_read_b128 v[148:151], v208 offset:18432
	ds_read_b128 v[156:159], v208 offset:19456
	ds_read_b128 v[160:163], v208 offset:20480
	ds_read_b128 v[164:167], v208 offset:21504
	ds_read_b128 v[184:187], v208 offset:22528
	ds_read_b128 v[188:191], v208 offset:23552
	global_load_lds_dwordx4 v[216:217], off
	v_lshl_add_u64 v[218:219], s[72:73], 0, v[170:171]
	s_mov_b32 m0, s76
	s_nop 0
	global_load_lds_dwordx4 v[218:219], off
	s_barrier
	s_waitcnt lgkmcnt(0)
	s_waitcnt lgkmcnt(0)
	v_mfma_f32_16x16x32_bf16 v[76:79], v[48:51], v[132:135], v[76:79]
	v_mfma_f32_16x16x32_bf16 v[72:75], v[60:63], v[132:135], v[72:75]
	v_mfma_f32_16x16x32_bf16 v[44:47], v[48:51], v[148:151], v[44:47]
	v_mfma_f32_16x16x32_bf16 v[40:43], v[60:63], v[148:151], v[40:43]
	v_mfma_f32_16x16x32_bf16 v[28:31], v[48:51], v[160:163], v[28:31]
	v_mfma_f32_16x16x32_bf16 v[24:27], v[60:63], v[160:163], v[24:27]
	v_mfma_f32_16x16x32_bf16 v[12:15], v[48:51], v[184:187], v[12:15]
	v_mfma_f32_16x16x32_bf16 v[8:11], v[60:63], v[184:187], v[8:11]
	v_mfma_f32_16x16x32_bf16 v[76:79], v[56:59], v[140:143], v[76:79]
	v_mfma_f32_16x16x32_bf16 v[72:75], v[68:71], v[140:143], v[72:75]
	v_mfma_f32_16x16x32_bf16 v[44:47], v[56:59], v[156:159], v[44:47]
	v_mfma_f32_16x16x32_bf16 v[40:43], v[68:71], v[156:159], v[40:43]
	v_mfma_f32_16x16x32_bf16 v[28:31], v[56:59], v[164:167], v[28:31]
	v_mfma_f32_16x16x32_bf16 v[24:27], v[68:71], v[164:167], v[24:27]
	v_mfma_f32_16x16x32_bf16 v[12:15], v[56:59], v[188:191], v[12:15]
	v_mfma_f32_16x16x32_bf16 v[8:11], v[68:71], v[188:191], v[8:11]
	s_barrier
; #define PG8_STAGE(bufoff, gbase, voff) do { _Pragma("unroll") for (int _i = 0; _i < 2; ++_i) \
;         __builtin_amdgcn_global_load_lds((const unsigned*)((const char*)(gbase) + (voff)[_i]), (PG8_LAS unsigned*)(lds + (bufoff) + ldsw + _i * 8192), 16, 0, 0); } while (0)
; #define PG8_LDA(dst, b, h) do { _Pragma("unroll") for (int m = 0; m < 4; ++m) _Pragma("unroll") for (int k = 0; k < 2; ++k) dst[m][k] = *(const PG8_LAS bf16x8*)(lds + PG8_SA(b, h) + aoff + m * 2048 + k * 1024); } while (0)
; #define PG8_LDB(dst, b, h) do { _Pragma("unroll") for (int n = 0; n < 2; ++n) _Pragma("unroll") for (int k = 0; k < 2; ++k) dst[n][k] = *(const PG8_LAS bf16x8*)(lds + PG8_SB(b, h) + boff + n * 2048 + k * 1024); } while (0)
; #define PG8_MMA(ai, bj, At, Bt) do { __builtin_amdgcn_s_setprio(1); _Pragma("unroll") for (int m = 0; m < 4; ++m) _Pragma("unroll") for (int n = 0; n < 2; ++n) _Pragma("unroll") for (int k = 0; k < 2; ++k) \
;         acc[ai][bj][m][n] = __builtin_amdgcn_mfma_f32_16x16x32_bf16(Bt[n][k], At[m][k], acc[ai][bj][m][n], 0, 0, 0); __builtin_amdgcn_s_setprio(0); } while (0)
; #define PG8_WAIT_V(n) asm volatile("s_waitcnt vmcnt(" #n ")" ::: "memory")
; #define PG8_WAIT_L(n) asm volatile("s_waitcnt lgkmcnt(" #n ")" ::: "memory")
; #define PG8_BAR __builtin_amdgcn_s_barrier()
; #define PG8_SCHED __builtin_amdgcn_sched_barrier(0)
; template <class Epi, class Sched>
; __device__ __forceinline__ void gemm_phase(PG8_LAS unsigned char* lds, const Gemm g, const Sched& S, const Epi& E) {
;     ...
;             PG8_WAIT_V(6); PG8_BAR; PG8_MMA(1, 1, At, B1); PG8_BAR;
;             PG8_LDB(B0, 1, 0); PG8_SCHED; PG8_LDA(At, 1, 0); PG8_STAGE(PG8_SA(0, 1), a2 + hstep, voffA);
;             PG8_WAIT_L(8); PG8_BAR; PG8_WAIT_L(0); PG8_MMA(0, 0, At, B0); PG8_BAR; PG8_SCHED;
;             PG8_LDB(B1, 1, 1); PG8_STAGE(PG8_SB(1, 0), b3, voffB);
;             PG8_BAR; PG8_WAIT_L(0); PG8_MMA(0, 1, At, B1); PG8_BAR;
;             PG8_LDA(At, 1, 1); PG8_STAGE(PG8_SA(1, 0), a3, voffA);
;             PG8_BAR; PG8_WAIT_L(0); PG8_MMA(1, 0, At, B0); PG8_BAR; PG8_SCHED;
	s_add_u32 vcc_lo, s70, 0x40000
	s_addc_u32 vcc_hi, s71, 0
	s_add_i32 s69, s69, s74
	v_lshl_add_u64 v[48:49], vcc, 0, v[180:181]
	s_mov_b32 m0, s69
	s_nop 0
	global_load_lds_dwordx4 v[48:49], off
	v_lshl_add_u64 v[48:49], vcc, 0, v[168:169]
	s_add_i32 m0, s69, 0x2000
	s_nop 0
	global_load_lds_dwordx4 v[48:49], off
	s_waitcnt vmcnt(6)
	s_barrier
	v_mfma_f32_16x16x32_bf16 v[52:55], v[200:203], v[132:135], v[52:55]
	v_mfma_f32_16x16x32_bf16 v[36:39], v[192:195], v[148:151], v[36:39]
	v_mfma_f32_16x16x32_bf16 v[32:35], v[200:203], v[148:151], v[32:35]
	v_mfma_f32_16x16x32_bf16 v[20:23], v[192:195], v[160:163], v[20:23]
	v_mfma_f32_16x16x32_bf16 v[16:19], v[200:203], v[160:163], v[16:19]
	v_mfma_f32_16x16x32_bf16 v[4:7], v[192:195], v[184:187], v[4:7]
	v_mfma_f32_16x16x32_bf16 v[0:3], v[200:203], v[184:187], v[0:3]
	v_mfma_f32_16x16x32_bf16 v[48:51], v[192:195], v[132:135], v[64:67]
	v_mfma_f32_16x16x32_bf16 v[52:55], v[210:213], v[140:143], v[52:55]
	v_mfma_f32_16x16x32_bf16 v[36:39], v[196:199], v[156:159], v[36:39]
	v_mfma_f32_16x16x32_bf16 v[32:35], v[210:213], v[156:159], v[32:35]
	v_mfma_f32_16x16x32_bf16 v[20:23], v[196:199], v[164:167], v[20:23]
	v_mfma_f32_16x16x32_bf16 v[16:19], v[210:213], v[164:167], v[16:19]
	v_mfma_f32_16x16x32_bf16 v[4:7], v[196:199], v[188:191], v[4:7]
	v_mfma_f32_16x16x32_bf16 v[0:3], v[210:213], v[188:191], v[0:3]
	v_mfma_f32_16x16x32_bf16 v[48:51], v[196:199], v[140:143], v[48:51]
	s_add_i32 s69, 0, 0x18000
	v_add_u32_e32 v68, s69, v206
	s_barrier
	ds_read_b128 v[56:59], v68
	ds_read_b128 v[60:63], v68 offset:1024
	ds_read_b128 v[64:67], v68 offset:2048
	ds_read_b128 v[68:71], v68 offset:3072
	s_add_u32 s72, s72, 0x40000
	s_addc_u32 s73, s73, 0
	s_mov_b32 m0, s77
	v_lshl_add_u64 v[192:193], s[72:73], 0, v[172:173]
	ds_read_b128 v[132:135], v208 offset:32768
	ds_read_b128 v[140:143], v208 offset:33792
	ds_read_b128 v[148:151], v208 offset:34816
	ds_read_b128 v[156:159], v208 offset:35840
	ds_read_b128 v[160:163], v208 offset:36864
	ds_read_b128 v[164:167], v208 offset:37888
	ds_read_b128 v[184:187], v208 offset:38912
	ds_read_b128 v[188:191], v208 offset:39936
	global_load_lds_dwordx4 v[192:193], off
	v_lshl_add_u64 v[192:193], s[72:73], 0, v[170:171]
	s_mov_b32 m0, s78
	s_nop 0
	global_load_lds_dwordx4 v[192:193], off
	s_waitcnt lgkmcnt(8)
	s_barrier
	s_waitcnt lgkmcnt(0)
	s_waitcnt lgkmcnt(0)
	v_mfma_f32_16x16x32_bf16 v[152:155], v[56:59], v[132:135], v[152:155]
	v_mfma_f32_16x16x32_bf16 v[144:147], v[64:67], v[132:135], v[144:147]
	v_mfma_f32_16x16x32_bf16 v[124:127], v[56:59], v[148:151], v[124:127]
	v_mfma_f32_16x16x32_bf16 v[120:123], v[64:67], v[148:151], v[120:123]
	v_mfma_f32_16x16x32_bf16 v[108:111], v[56:59], v[160:163], v[108:111]
	v_mfma_f32_16x16x32_bf16 v[104:107], v[64:67], v[160:163], v[104:107]
	v_mfma_f32_16x16x32_bf16 v[92:95], v[56:59], v[184:187], v[92:95]
	v_mfma_f32_16x16x32_bf16 v[88:91], v[64:67], v[184:187], v[88:91]
	v_mfma_f32_16x16x32_bf16 v[152:155], v[60:63], v[140:143], v[152:155]
	v_mfma_f32_16x16x32_bf16 v[144:147], v[68:71], v[140:143], v[144:147]
	v_mfma_f32_16x16x32_bf16 v[124:127], v[60:63], v[156:159], v[124:127]
	v_mfma_f32_16x16x32_bf16 v[120:123], v[68:71], v[156:159], v[120:123]
	v_mfma_f32_16x16x32_bf16 v[108:111], v[60:63], v[164:167], v[108:111]
	v_mfma_f32_16x16x32_bf16 v[104:107], v[68:71], v[164:167], v[104:107]
	v_mfma_f32_16x16x32_bf16 v[92:95], v[60:63], v[188:191], v[92:95]
	v_mfma_f32_16x16x32_bf16 v[88:91], v[68:71], v[188:191], v[88:91]
	s_barrier
	s_add_i32 s72, 0, 0x1c000
	s_add_i32 s69, s69, s74
	v_add_u32_e32 v209, s72, v206
	v_lshl_add_u64 v[204:205], v[204:205], 0, s[38:39]
	s_mov_b32 m0, s69
	ds_read_b128 v[192:195], v209
	ds_read_b128 v[196:199], v209 offset:1024
	ds_read_b128 v[200:203], v209 offset:2048
	ds_read_b128 v[210:213], v209 offset:3072
	global_load_lds_dwordx4 v[204:205], off
	v_lshl_add_u64 v[204:205], v[214:215], 0, s[38:39]
	s_add_i32 m0, s69, 0x2000
	s_nop 0
	global_load_lds_dwordx4 v[204:205], off
	s_barrier
	s_waitcnt lgkmcnt(0)
	s_waitcnt lgkmcnt(0)
	v_mfma_f32_16x16x32_bf16 v[136:139], v[192:195], v[132:135], v[136:139]
	v_mfma_f32_16x16x32_bf16 v[128:131], v[200:203], v[132:135], v[128:131]
	v_mfma_f32_16x16x32_bf16 v[116:119], v[192:195], v[148:151], v[116:119]
	v_mfma_f32_16x16x32_bf16 v[112:115], v[200:203], v[148:151], v[112:115]
	v_mfma_f32_16x16x32_bf16 v[100:103], v[192:195], v[160:163], v[100:103]
	v_mfma_f32_16x16x32_bf16 v[96:99], v[200:203], v[160:163], v[96:99]
	v_mfma_f32_16x16x32_bf16 v[84:87], v[192:195], v[184:187], v[84:87]
	v_mfma_f32_16x16x32_bf16 v[80:83], v[200:203], v[184:187], v[80:83]
	v_mfma_f32_16x16x32_bf16 v[136:139], v[196:199], v[140:143], v[136:139]
	v_mfma_f32_16x16x32_bf16 v[132:135], v[210:213], v[140:143], v[128:131]
	v_mfma_f32_16x16x32_bf16 v[116:119], v[196:199], v[156:159], v[116:119]
	v_mfma_f32_16x16x32_bf16 v[112:115], v[210:213], v[156:159], v[112:115]
	v_mfma_f32_16x16x32_bf16 v[100:103], v[196:199], v[164:167], v[100:103]
	v_mfma_f32_16x16x32_bf16 v[96:99], v[210:213], v[164:167], v[96:99]
	v_mfma_f32_16x16x32_bf16 v[84:87], v[196:199], v[188:191], v[84:87]
	v_mfma_f32_16x16x32_bf16 v[80:83], v[210:213], v[188:191], v[80:83]
	s_mov_b32 m0, s79
	v_lshl_add_u64 v[204:205], v[216:217], 0, s[38:39]
	s_barrier
	ds_read_b128 v[128:131], v208 offset:49152
	ds_read_b128 v[140:143], v208 offset:50176
	ds_read_b128 v[148:151], v208 offset:51200
	ds_read_b128 v[156:159], v208 offset:52224
	ds_read_b128 v[160:163], v208 offset:53248
	ds_read_b128 v[164:167], v208 offset:54272
	ds_read_b128 v[184:187], v208 offset:55296
	ds_read_b128 v[188:191], v208 offset:56320
	global_load_lds_dwordx4 v[204:205], off
	v_lshl_add_u64 v[204:205], v[218:219], 0, s[38:39]
	s_mov_b32 m0, s80
	s_nop 0
	global_load_lds_dwordx4 v[204:205], off
	s_barrier
; #define PG8_STAGE(bufoff, gbase, voff) do { _Pragma("unroll") for (int _i = 0; _i < 2; ++_i) \
;         __builtin_amdgcn_global_load_lds((const unsigned*)((const char*)(gbase) + (voff)[_i]), (PG8_LAS unsigned*)(lds + (bufoff) + ldsw + _i * 8192), 16, 0, 0); } while (0)
; #define PG8_MMA(ai, bj, At, Bt) do { __builtin_amdgcn_s_setprio(1); _Pragma("unroll") for (int m = 0; m < 4; ++m) _Pragma("unroll") for (int n = 0; n < 2; ++n) _Pragma("unroll") for (int k = 0; k < 2; ++k) \
;         acc[ai][bj][m][n] = __builtin_amdgcn_mfma_f32_16x16x32_bf16(Bt[n][k], At[m][k], acc[ai][bj][m][n], 0, 0, 0); __builtin_amdgcn_s_setprio(0); } while (0)
; #define PG8_WAIT_V(n) asm volatile("s_waitcnt vmcnt(" #n ")" ::: "memory")
; #define PG8_WAIT_L(n) asm volatile("s_waitcnt lgkmcnt(" #n ")" ::: "memory")
; #define PG8_BAR __builtin_amdgcn_s_barrier()
; template <class Epi, class Sched>
; __device__ __forceinline__ void gemm_phase(PG8_LAS unsigned char* lds, const Gemm g, const Sched& S, const Epi& E) {
;     ...
;             PG8_BAR; PG8_WAIT_L(0); PG8_MMA(1, 0, At, B0); PG8_BAR; PG8_SCHED;
;             PG8_STAGE(PG8_SB(1, 1), b3 + hstep, voffB);
;             PG8_WAIT_V(6); PG8_BAR; PG8_MMA(1, 1, At, B1); PG8_BAR;
;         }
;         E(acc, cur, wr, wc, fr, fq); S.done(cur);
;     DI void operator()(const AccT& acc, const pg8::Unit& u, int wr, int wc, int fr, int fq) const {
;         const int col0 = u.pn * 256 + wc * 32 + 8 * fq, head = u.pn >> 1;
;         f32x4 g0[2], g1[2];
; #pragma unroll
;         for (int bj = 0; bj < 2; ++bj) { g0[bj] = *(const f32x4*)(gn + col0 + bj * 128); g1[bj] = *(const f32x4*)(gn + col0 + bj * 128 + 4); }
; #pragma unroll
;         for (int ai = 0; ai < 2; ++ai) {
;             float2 st[4]; u32x4 ov[4][2];
; #pragma unroll
;             for (int m = 0; m < 4; ++m) { const size_t row = (size_t)u.pm * 256 + wr * 64 + fr + ai * 128 + m * 16;
;                 st[m] = *(const float2*)(stats + (row * 4 + head) * 2);
; #pragma unroll
;                 for (int bj = 0; bj < 2; ++bj) ov[m][bj] = *(const u32x4*)(o + row * 2048 + col0 + bj * 128); }
; #pragma unroll
;             for (int m = 0; m < 4; ++m) { const size_t row = (size_t)u.pm * 256 + wr * 64 + fr + ai * 128 + m * 16;
;                 const float mean = st[m].x * (1.f / 512.f), var = fmaxf(st[m].y * (1.f / 512.f) - mean * mean, 0.f), rstd = rsqrtf(var + 1e-5f);
	s_waitcnt lgkmcnt(0)
	s_waitcnt lgkmcnt(0)
	v_mfma_f32_16x16x32_bf16 v[76:79], v[56:59], v[128:131], v[76:79]
	v_mfma_f32_16x16x32_bf16 v[72:75], v[64:67], v[128:131], v[72:75]
	v_mfma_f32_16x16x32_bf16 v[44:47], v[56:59], v[148:151], v[44:47]
	v_mfma_f32_16x16x32_bf16 v[40:43], v[64:67], v[148:151], v[40:43]
	v_mfma_f32_16x16x32_bf16 v[28:31], v[56:59], v[160:163], v[28:31]
	v_mfma_f32_16x16x32_bf16 v[24:27], v[64:67], v[160:163], v[24:27]
	v_mfma_f32_16x16x32_bf16 v[12:15], v[56:59], v[184:187], v[12:15]
	v_mfma_f32_16x16x32_bf16 v[8:11], v[64:67], v[184:187], v[8:11]
	v_mfma_f32_16x16x32_bf16 v[76:79], v[60:63], v[140:143], v[76:79]
	v_mfma_f32_16x16x32_bf16 v[72:75], v[68:71], v[140:143], v[72:75]
	v_mfma_f32_16x16x32_bf16 v[44:47], v[60:63], v[156:159], v[44:47]
	v_mfma_f32_16x16x32_bf16 v[40:43], v[68:71], v[156:159], v[40:43]
	v_mfma_f32_16x16x32_bf16 v[28:31], v[60:63], v[164:167], v[28:31]
	v_mfma_f32_16x16x32_bf16 v[24:27], v[68:71], v[164:167], v[24:27]
	v_mfma_f32_16x16x32_bf16 v[12:15], v[60:63], v[188:191], v[12:15]
	v_mfma_f32_16x16x32_bf16 v[8:11], v[68:71], v[188:191], v[8:11]
	s_barrier
	s_add_u32 s70, s70, 0x40080
	s_addc_u32 s71, s71, 0
	s_add_i32 s69, s72, s74
	v_lshl_add_u64 v[56:57], s[70:71], 0, v[180:181]
	s_mov_b32 m0, s69
	s_nop 0
	global_load_lds_dwordx4 v[56:57], off
	v_lshl_add_u64 v[56:57], s[70:71], 0, v[168:169]
	s_add_i32 m0, s69, 0x2000
	s_nop 0
	global_load_lds_dwordx4 v[56:57], off
	s_waitcnt vmcnt(6)
	s_barrier
	v_mfma_f32_16x16x32_bf16 v[48:51], v[192:195], v[128:131], v[48:51]
	v_mfma_f32_16x16x32_bf16 v[64:67], v[196:199], v[140:143], v[48:51]
	v_mfma_f32_16x16x32_bf16 v[48:51], v[200:203], v[128:131], v[52:55]
	v_mfma_f32_16x16x32_bf16 v[36:39], v[192:195], v[148:151], v[36:39]
	v_mfma_f32_16x16x32_bf16 v[32:35], v[200:203], v[148:151], v[32:35]
	v_mfma_f32_16x16x32_bf16 v[20:23], v[192:195], v[160:163], v[20:23]
	v_mfma_f32_16x16x32_bf16 v[16:19], v[200:203], v[160:163], v[16:19]
	v_mfma_f32_16x16x32_bf16 v[4:7], v[192:195], v[184:187], v[4:7]
	v_mfma_f32_16x16x32_bf16 v[0:3], v[200:203], v[184:187], v[0:3]
	v_mfma_f32_16x16x32_bf16 v[52:55], v[210:213], v[140:143], v[48:51]
	v_mfma_f32_16x16x32_bf16 v[36:39], v[196:199], v[156:159], v[36:39]
	v_mfma_f32_16x16x32_bf16 v[32:35], v[210:213], v[156:159], v[32:35]
	v_mfma_f32_16x16x32_bf16 v[20:23], v[196:199], v[164:167], v[20:23]
	v_mfma_f32_16x16x32_bf16 v[16:19], v[210:213], v[164:167], v[16:19]
	v_mfma_f32_16x16x32_bf16 v[4:7], v[196:199], v[188:191], v[4:7]
	v_mfma_f32_16x16x32_bf16 v[0:3], v[210:213], v[188:191], v[0:3]
	s_add_i32 s89, s89, 2
	s_add_u32 s20, s20, 0x100
	s_addc_u32 s21, s21, 0
	s_add_u32 s83, s83, 0x100
	s_addc_u32 s88, s88, 0
	s_cmp_gt_u32 s89, 13
	s_barrier
	s_cbranch_scc0 .LBB0_516
	v_lshl_or_b32 v48, s18, 8, v207
	s_ashr_i32 s20, s18, 1
	s_ashr_i32 s17, s16, 31
	v_ashrrev_i32_e32 v49, 31, v48
	s_lshl_b64 s[16:17], s[16:17], 8
	s_ashr_i32 s21, s20, 31
	v_lshl_add_u64 v[188:189], s[16:17], 0, v[174:175]
	s_lshl_b64 s[16:17], s[20:21], 3
	v_lshlrev_b64 v[184:185], 1, v[48:49]
	s_add_u32 s16, s60, s16
	v_lshl_add_u64 v[186:187], s[96:97], 0, v[184:185]
	v_lshlrev_b64 v[128:129], 12, v[188:189]
	v_lshl_add_u64 v[56:57], v[48:49], 2, s[6:7]
	s_addc_u32 s17, s61, s17
	v_lshlrev_b64 v[48:49], 5, v[188:189]
	v_lshl_add_u64 v[130:131], v[186:187], 0, v[128:129]
	global_load_dwordx4 v[60:63], v[56:57], off
	v_lshl_add_u64 v[48:49], s[16:17], 0, v[48:49]
	global_load_dwordx4 v[210:213], v[130:131], off
	global_load_dwordx2 v[204:205], v[48:49], off
	v_mul_f32_e32 v48, 0xbfb8aa3b, v152
	v_mul_f32_e32 v49, 0xbfb8aa3b, v153
	v_mul_f32_e32 v50, 0xbfb8aa3b, v154
	v_mul_f32_e32 v51, 0xbfb8aa3b, v155
	v_mul_f32_e32 v58, 0xbfb8aa3b, v144
	v_mul_f32_e32 v59, 0xbfb8aa3b, v145
	v_mul_f32_e32 v68, 0xbfb8aa3b, v146
	v_mul_f32_e32 v69, 0xbfb8aa3b, v147
	v_mov_b32_e32 v214, v152
	v_exp_f32_e32 v152, v48
	v_exp_f32_e32 v156, v49
	v_exp_f32_e32 v157, v50
	v_exp_f32_e32 v158, v51
	v_exp_f32_e32 v159, v58
	v_exp_f32_e32 v160, v59
	v_exp_f32_e32 v161, v68
	v_exp_f32_e32 v162, v69
	global_load_dwordx4 v[68:71], v[56:57], off offset:16
	global_load_dwordx4 v[48:51], v[56:57], off offset:528
	s_nop 0
	global_load_dwordx4 v[56:59], v[56:57], off offset:512
	v_add_f32_e32 v209, 1.0, v156
	global_load_dwordx4 v[164:167], v[130:131], off offset:256
	v_rcp_f32_e32 v220, v209
	v_or_b32_e32 v140, 16, v188
	v_mov_b32_e32 v141, v189
	v_or_b32_e32 v148, 48, v188
	v_mov_b32_e32 v149, v189
	v_or_b32_e32 v142, 32, v188
	v_mov_b32_e32 v143, v189
	v_lshlrev_b64 v[202:203], 12, v[140:141]
	v_lshlrev_b64 v[190:191], 12, v[148:149]
	v_lshlrev_b64 v[150:151], 5, v[140:141]
	v_lshlrev_b64 v[140:141], 5, v[142:143]
	v_lshlrev_b64 v[196:197], 12, v[142:143]
	v_lshlrev_b64 v[142:143], 5, v[148:149]
	v_lshl_add_u64 v[128:129], s[96:97], 0, v[128:129]
	v_lshl_add_u64 v[130:131], v[186:187], 0, v[202:203]
	v_lshl_add_u64 v[218:219], v[186:187], 0, v[190:191]
	v_add_f32_e32 v152, 1.0, v152
	v_lshl_add_u64 v[216:217], s[16:17], 0, v[150:151]
	v_lshl_add_u64 v[198:199], s[16:17], 0, v[140:141]
	v_lshl_add_u64 v[200:201], v[186:187], 0, v[196:197]
	v_lshl_add_u64 v[194:195], s[16:17], 0, v[142:143]
	v_lshl_add_u64 v[192:193], v[128:129], 0, v[184:185]
	v_add_f32_e32 v215, 1.0, v157
	v_add_f32_e32 v221, 1.0, v158
	v_add_f32_e32 v223, 1.0, v159
	v_add_f32_e32 v225, 1.0, v160
	v_add_f32_e32 v227, 1.0, v161
	v_add_f32_e32 v229, 1.0, v162
	global_load_dwordx4 v[160:163], v[130:131], off
	global_load_dwordx4 v[156:159], v[130:131], off offset:256
	global_load_dwordx4 v[148:151], v[200:201], off offset:256
	global_load_dwordx4 v[140:143], v[218:219], off
	s_nop 0
	global_load_dwordx4 v[128:131], v[218:219], off offset:256
	v_rcp_f32_e32 v218, v152
	v_rcp_f32_e32 v224, v221
	v_rcp_f32_e32 v226, v223
	v_rcp_f32_e32 v228, v225
	v_rcp_f32_e32 v232, v227
	v_rcp_f32_e32 v234, v229
	v_rcp_f32_e32 v222, v215
	s_mov_b64 s[20:21], 0x90
	s_mov_b32 s18, s8
	s_mov_b64 s[70:71], s[14:15]
	s_waitcnt vmcnt(0)
; DI float bflo(unsigned w) { return __uint_as_float(w << 16); }
; DI float bfhi(unsigned w) { return __uint_as_float(w & 0xffff0000u); }
; DI void store8(bf16_t* p, f32x4 a, f32x4 b) { u32x4 w = {cvt_pk_bf16(a[0], a[1]), cvt_pk_bf16(a[2], a[3]), cvt_pk_bf16(b[0], b[1]), cvt_pk_bf16(b[2], b[3])}; *(u32x4*)p = w; }
; DI f32x4 silu4(f32x4 v) { f32x4 r; r[0] = silu_f(v[0]); r[1] = silu_f(v[1]); r[2] = silu_f(v[2]); r[3] = silu_f(v[3]); return r; }
;     DI void operator()(const AccT& acc, const pg8::Unit& u, int wr, int wc, int fr, int fq) const {
;     ...
;             for (int m = 0; m < 4; ++m) { const size_t row = (size_t)u.pm * 256 + wr * 64 + fr + ai * 128 + m * 16;
;                 st[m] = *(const float2*)(stats + (row * 4 + head) * 2);
; #pragma unroll
;                 for (int bj = 0; bj < 2; ++bj) ov[m][bj] = *(const u32x4*)(o + row * 2048 + col0 + bj * 128); }
; #pragma unroll
;             for (int m = 0; m < 4; ++m) { const size_t row = (size_t)u.pm * 256 + wr * 64 + fr + ai * 128 + m * 16;
;                 const float mean = st[m].x * (1.f / 512.f), var = fmaxf(st[m].y * (1.f / 512.f) - mean * mean, 0.f), rstd = rsqrtf(var + 1e-5f);
; #pragma unroll
;                 for (int bj = 0; bj < 2; ++bj) { bf16_t* op = o + row * 2048 + col0 + bj * 128; const u32x4 w = ov[m][bj];
;                     const f32x4 s0 = silu4(acc[ai][bj][m][0]), s1 = silu4(acc[ai][bj][m][1]);
;                     f32x4 y0, y1;
;                     y0[0] = (bflo(w[0]) - mean) * rstd * g0[bj][0] * s0[0]; y0[1] = (bfhi(w[0]) - mean) * rstd * g0[bj][1] * s0[1];
;                     y0[2] = (bflo(w[1]) - mean) * rstd * g0[bj][2] * s0[2]; y0[3] = (bfhi(w[1]) - mean) * rstd * g0[bj][3] * s0[3];
;                     y1[0] = (bflo(w[2]) - mean) * rstd * g1[bj][0] * s1[0]; y1[1] = (bfhi(w[2]) - mean) * rstd * g1[bj][1] * s1[1];
;                     y1[2] = (bflo(w[3]) - mean) * rstd * g1[bj][2] * s1[2]; y1[3] = (bfhi(w[3]) - mean) * rstd * g1[bj][3] * s1[3];
;                     store8(op, y0, y1); } } }
	v_mov_b32_e32 v215, v60
	v_lshlrev_b32_e32 v152, 16, v210
	v_pk_mul_f32 v[204:205], v[204:205], s[54:55] op_sel_hi:[1,0]
	s_nop 0
	v_fma_f32 v205, -v204, v204, v205
	v_max_f32_e32 v205, 0, v205
	v_add_f32_e32 v205, 0x3727c5ac, v205
	v_mul_f32_e32 v209, 0x4b800000, v205
	v_cmp_gt_f32_e32 vcc, s94, v205
	v_sub_f32_e32 v152, v152, v204
	s_nop 0
	v_cndmask_b32_e32 v205, v205, v209, vcc
	v_rsq_f32_e32 v205, v205
	v_and_b32_e32 v209, 0xffff0000, v210
	v_sub_f32_e32 v209, v209, v204
	v_mul_f32_e32 v210, 0x45800000, v205
	v_cndmask_b32_e32 v205, v205, v210, vcc
	v_mul_f32_e32 v221, v209, v205
	v_lshlrev_b32_e32 v209, 16, v211
	v_sub_f32_e32 v209, v209, v204
	v_mul_f32_e32 v223, v209, v205
	v_and_b32_e32 v209, 0xffff0000, v211
	v_sub_f32_e32 v209, v209, v204
	v_mul_f32_e32 v225, v209, v205
	v_lshlrev_b32_e32 v209, 16, v212
	v_sub_f32_e32 v209, v209, v204
	v_mul_f32_e32 v227, v209, v205
	v_and_b32_e32 v209, 0xffff0000, v212
	v_sub_f32_e32 v209, v209, v204
	v_mul_f32_e32 v229, v209, v205
	v_lshlrev_b32_e32 v209, 16, v213
	v_sub_f32_e32 v209, v209, v204
	v_mul_f32_e32 v233, v209, v205
	v_and_b32_e32 v209, 0xffff0000, v213
	global_load_dwordx2 v[212:213], v[216:217], off
	v_mov_b32_e32 v210, v155
	v_mov_b32_e32 v211, v63
	v_pk_mul_f32 v[210:211], v[210:211], v[224:225]
	v_sub_f32_e32 v209, v209, v204
	v_mul_f32_e32 v155, v210, v211
	v_mov_b32_e32 v210, v144
	v_mov_b32_e32 v211, v68
	v_pk_mul_f32 v[210:211], v[210:211], v[226:227]
	v_mul_f32_e32 v235, v209, v205
	v_mul_f32_e32 v144, v210, v211
	v_mov_b32_e32 v210, v145
	v_mov_b32_e32 v211, v69
	v_pk_mul_f32 v[210:211], v[210:211], v[228:229]
	v_mul_f32_e32 v219, v152, v205
	v_mul_f32_e32 v145, v210, v211
	v_mov_b32_e32 v210, v146
	v_mov_b32_e32 v211, v70
	v_pk_mul_f32 v[210:211], v[210:211], v[232:233]
	v_pk_mul_f32 v[214:215], v[214:215], v[218:219]
	v_mul_f32_e32 v146, v210, v211
	v_mov_b32_e32 v210, v147
	v_mov_b32_e32 v211, v71
	v_pk_mul_f32 v[210:211], v[210:211], v[234:235]
	v_mul_f32_e32 v147, 0xbfb8aa3b, v136
	v_exp_f32_e32 v209, v147
	v_mul_f32_e32 v147, v210, v211
	v_mul_f32_e32 v210, 0xbfb8aa3b, v137
	v_exp_f32_e32 v211, v210
	v_mul_f32_e32 v152, v214, v215
	v_mov_b32_e32 v214, v153
	v_mov_b32_e32 v215, v61
	v_pk_mul_f32 v[214:215], v[214:215], v[220:221]
	v_add_f32_e32 v209, 1.0, v209
	v_mul_f32_e32 v153, v214, v215
	v_mov_b32_e32 v214, v154
	v_mov_b32_e32 v215, v62
	v_pk_mul_f32 v[214:215], v[214:215], v[222:223]
	v_rcp_f32_e32 v210, v209
	v_add_f32_e32 v209, 1.0, v211
	v_mul_f32_e32 v211, 0xbfb8aa3b, v138
	v_mul_f32_e32 v154, v214, v215
	v_exp_f32_e32 v211, v211
	v_mul_f32_e32 v214, 0xbfb8aa3b, v139
	v_exp_f32_e32 v215, v214
	v_rcp_f32_e32 v214, v209
	v_add_f32_e32 v209, 1.0, v211
	v_mul_f32_e32 v211, 0xbfb8aa3b, v132
	v_rcp_f32_e32 v216, v209
	v_add_f32_e32 v209, 1.0, v215
	v_exp_f32_e32 v211, v211
	v_mul_f32_e32 v215, 0xbfb8aa3b, v133
	v_exp_f32_e32 v215, v215
	v_rcp_f32_e32 v218, v209
	v_add_f32_e32 v209, 1.0, v211
	v_mul_f32_e32 v211, 0xbfb8aa3b, v134
	v_rcp_f32_e32 v220, v209
	v_add_f32_e32 v209, 1.0, v215
	v_exp_f32_e32 v211, v211
	v_mul_f32_e32 v215, 0xbfb8aa3b, v135
	v_exp_f32_e32 v215, v215
	v_rcp_f32_e32 v222, v209
	v_add_f32_e32 v209, 1.0, v211
	v_rcp_f32_e32 v224, v209
	v_add_f32_e32 v209, 1.0, v215
	v_rcp_f32_e32 v226, v209
	v_lshlrev_b32_e32 v209, 16, v164
	v_and_b32_e32 v164, 0xffff0000, v164
	v_sub_f32_e32 v164, v164, v204
	v_mul_f32_e32 v215, v164, v205
	v_lshlrev_b32_e32 v164, 16, v165
	v_sub_f32_e32 v164, v164, v204
	v_mul_f32_e32 v217, v164, v205
	v_and_b32_e32 v164, 0xffff0000, v165
	v_sub_f32_e32 v164, v164, v204
	v_mul_f32_e32 v219, v164, v205
	v_mov_b32_e32 v164, v139
	v_mov_b32_e32 v165, v59
	v_pk_mul_f32 v[164:165], v[164:165], v[218:219]
	v_sub_f32_e32 v209, v209, v204
	v_mul_f32_e32 v139, v164, v165
	v_lshlrev_b32_e32 v164, 16, v166
	v_sub_f32_e32 v164, v164, v204
	v_mul_f32_e32 v221, v164, v205
	v_mov_b32_e32 v164, v132
	v_and_b32_e32 v132, 0xffff0000, v166
	v_sub_f32_e32 v132, v132, v204
	v_mov_b32_e32 v165, v48
	v_mul_f32_e32 v223, v132, v205
	v_mov_b32_e32 v132, v133
	v_mov_b32_e32 v133, v49
	v_pk_mul_f32 v[164:165], v[164:165], v[220:221]
	v_pk_mul_f32 v[132:133], v[132:133], v[222:223]
	v_mul_f32_e32 v164, v164, v165
	v_mul_f32_e32 v165, v132, v133
	v_lshlrev_b32_e32 v132, 16, v167
	v_sub_f32_e32 v132, v132, v204
	v_mul_f32_e32 v225, v132, v205
	v_mov_b32_e32 v132, v134
	v_mov_b32_e32 v133, v50
	v_pk_mul_f32 v[132:133], v[132:133], v[224:225]
	v_mul_f32_e32 v211, v209, v205
	v_mul_f32_e32 v166, v132, v133
	v_and_b32_e32 v132, 0xffff0000, v167
	v_sub_f32_e32 v132, v132, v204
	v_mul_f32_e32 v227, v132, v205
	v_mov_b32_e32 v132, v135
	s_waitcnt vmcnt(0)
; DI float bflo(unsigned w) { return __uint_as_float(w << 16); }
; DI float bfhi(unsigned w) { return __uint_as_float(w & 0xffff0000u); }
; DI void store8(bf16_t* p, f32x4 a, f32x4 b) { u32x4 w = {cvt_pk_bf16(a[0], a[1]), cvt_pk_bf16(a[2], a[3]), cvt_pk_bf16(b[0], b[1]), cvt_pk_bf16(b[2], b[3])}; *(u32x4*)p = w; }
; DI f32x4 silu4(f32x4 v) { f32x4 r; r[0] = silu_f(v[0]); r[1] = silu_f(v[1]); r[2] = silu_f(v[2]); r[3] = silu_f(v[3]); return r; }
;     DI void operator()(const AccT& acc, const pg8::Unit& u, int wr, int wc, int fr, int fq) const {
;     ...
;             for (int m = 0; m < 4; ++m) { const size_t row = (size_t)u.pm * 256 + wr * 64 + fr + ai * 128 + m * 16;
;                 st[m] = *(const float2*)(stats + (row * 4 + head) * 2);
; #pragma unroll
;                 for (int bj = 0; bj < 2; ++bj) ov[m][bj] = *(const u32x4*)(o + row * 2048 + col0 + bj * 128); }
; #pragma unroll
;             for (int m = 0; m < 4; ++m) { const size_t row = (size_t)u.pm * 256 + wr * 64 + fr + ai * 128 + m * 16;
;                 const float mean = st[m].x * (1.f / 512.f), var = fmaxf(st[m].y * (1.f / 512.f) - mean * mean, 0.f), rstd = rsqrtf(var + 1e-5f);
; #pragma unroll
;                 for (int bj = 0; bj < 2; ++bj) { bf16_t* op = o + row * 2048 + col0 + bj * 128; const u32x4 w = ov[m][bj];
;                     const f32x4 s0 = silu4(acc[ai][bj][m][0]), s1 = silu4(acc[ai][bj][m][1]);
;                     f32x4 y0, y1;
;                     y0[0] = (bflo(w[0]) - mean) * rstd * g0[bj][0] * s0[0]; y0[1] = (bfhi(w[0]) - mean) * rstd * g0[bj][1] * s0[1];
;                     y0[2] = (bflo(w[1]) - mean) * rstd * g0[bj][2] * s0[2]; y0[3] = (bfhi(w[1]) - mean) * rstd * g0[bj][3] * s0[3];
;                     y1[0] = (bflo(w[2]) - mean) * rstd * g1[bj][0] * s1[0]; y1[1] = (bfhi(w[2]) - mean) * rstd * g1[bj][1] * s1[1];
;                     y1[2] = (bflo(w[3]) - mean) * rstd * g1[bj][2] * s1[2]; y1[3] = (bfhi(w[3]) - mean) * rstd * g1[bj][3] * s1[3];
;                     store8(op, y0, y1); } } }
	v_pk_mul_f32 v[134:135], v[212:213], s[54:55] op_sel_hi:[1,0]
	v_mov_b32_e32 v228, v136
	v_fma_f32 v133, -v134, v134, v135
	v_max_f32_e32 v133, 0, v133
	v_add_f32_e32 v133, 0x3727c5ac, v133
	v_mul_f32_e32 v135, 0x4b800000, v133
	v_cmp_gt_f32_e32 vcc, s94, v133
	v_mov_b32_e32 v229, v56
	v_mul_f32_e32 v204, 0xbfb8aa3b, v126
	v_cndmask_b32_e32 v133, v133, v135, vcc
	v_rsq_f32_e32 v167, v133
	v_mov_b32_e32 v133, v51
	v_pk_mul_f32 v[132:133], v[132:133], v[226:227]
	v_pk_mul_f32 v[210:211], v[228:229], v[210:211]
	v_mul_f32_e32 v135, v132, v133
	v_mul_f32_e32 v132, 0x45800000, v167
	v_cndmask_b32_e32 v167, v167, v132, vcc
	v_lshl_add_u64 v[132:133], s[96:97], 0, v[202:203]
	v_mul_f32_e32 v203, 0xbfb8aa3b, v125
	v_exp_f32_e32 v203, v203
	v_exp_f32_e32 v205, v204
	v_mul_f32_e32 v204, 0xbfb8aa3b, v127
	v_mul_f32_e32 v136, v210, v211
	v_mov_b32_e32 v210, v137
	v_mov_b32_e32 v211, v57
	v_exp_f32_e32 v209, v204
	v_pk_mul_f32 v[210:211], v[210:211], v[214:215]
	v_add_f32_e32 v203, 1.0, v203
	v_mul_f32_e32 v137, v210, v211
	v_mov_b32_e32 v210, v138
	v_mov_b32_e32 v211, v58
	v_pk_mul_f32 v[210:211], v[210:211], v[216:217]
	v_rcp_f32_e32 v204, v203
	v_add_f32_e32 v203, 1.0, v205
	v_mul_f32_e32 v205, 0xbfb8aa3b, v120
	v_mul_f32_e32 v138, v210, v211
	v_rcp_f32_e32 v210, v203
	v_add_f32_e32 v203, 1.0, v209
	v_exp_f32_e32 v205, v205
	v_mul_f32_e32 v209, 0xbfb8aa3b, v121
	v_exp_f32_e32 v209, v209
	v_rcp_f32_e32 v212, v203
	v_add_f32_e32 v203, 1.0, v205
	v_mul_f32_e32 v205, 0xbfb8aa3b, v122
	v_rcp_f32_e32 v214, v203
	v_add_f32_e32 v203, 1.0, v209
	v_exp_f32_e32 v205, v205
	v_mul_f32_e32 v209, 0xbfb8aa3b, v123
	v_exp_f32_e32 v209, v209
	v_rcp_f32_e32 v216, v203
	v_add_f32_e32 v203, 1.0, v205
	v_rcp_f32_e32 v218, v203
	v_add_f32_e32 v203, 1.0, v209
	v_rcp_f32_e32 v220, v203
	v_lshlrev_b32_e32 v203, 16, v160
	v_and_b32_e32 v160, 0xffff0000, v160
	v_sub_f32_e32 v160, v160, v134
	v_mul_f32_e32 v205, v160, v167
	v_lshlrev_b32_e32 v160, 16, v161
	v_sub_f32_e32 v160, v160, v134
	v_mul_f32_e32 v211, v160, v167
	v_and_b32_e32 v160, 0xffff0000, v161
	v_sub_f32_e32 v160, v160, v134
	v_mul_f32_e32 v213, v160, v167
	v_mov_b32_e32 v160, v127
	v_mov_b32_e32 v161, v63
	v_pk_mul_f32 v[160:161], v[160:161], v[212:213]
	v_mul_f32_e32 v202, 0xbfb8aa3b, v124
	v_mul_f32_e32 v127, v160, v161
	v_lshlrev_b32_e32 v160, 16, v162
	v_sub_f32_e32 v160, v160, v134
	v_exp_f32_e32 v202, v202
	v_mul_f32_e32 v215, v160, v167
	v_mov_b32_e32 v160, v120
	v_and_b32_e32 v120, 0xffff0000, v162
	v_sub_f32_e32 v120, v120, v134
	v_mov_b32_e32 v161, v68
	v_mul_f32_e32 v217, v120, v167
	v_mov_b32_e32 v120, v121
	v_mov_b32_e32 v121, v69
	v_pk_mul_f32 v[160:161], v[160:161], v[214:215]
	v_pk_mul_f32 v[120:121], v[120:121], v[216:217]
	v_add_f32_e32 v202, 1.0, v202
	v_mul_f32_e32 v160, v160, v161
	v_mul_f32_e32 v161, v120, v121
	v_lshlrev_b32_e32 v120, 16, v163
	v_rcp_f32_e32 v202, v202
	v_sub_f32_e32 v120, v120, v134
	v_mul_f32_e32 v219, v120, v167
	v_mov_b32_e32 v120, v122
	v_mov_b32_e32 v121, v70
	v_sub_f32_e32 v203, v203, v134
	v_pk_mul_f32 v[120:121], v[120:121], v[218:219]
	v_mul_f32_e32 v203, v203, v167
	v_mov_b32_e32 v222, v124
	v_mov_b32_e32 v223, v60
	v_mul_f32_e32 v162, v120, v121
	v_mul_f32_e32 v121, 0xbfb8aa3b, v116
	v_pk_mul_f32 v[202:203], v[222:223], v[202:203]
	v_and_b32_e32 v120, 0xffff0000, v163
	v_exp_f32_e32 v122, v121
	v_mul_f32_e32 v124, v202, v203
	v_mov_b32_e32 v202, v125
	v_mov_b32_e32 v203, v61
	v_sub_f32_e32 v120, v120, v134
	v_pk_mul_f32 v[202:203], v[202:203], v[204:205]
	v_mul_f32_e32 v221, v120, v167
	v_mov_b32_e32 v120, v123
	v_mov_b32_e32 v121, v71
	v_mul_f32_e32 v125, v202, v203
	v_mov_b32_e32 v202, v126
	v_mov_b32_e32 v203, v62
	v_pk_mul_f32 v[120:121], v[120:121], v[220:221]
	v_pk_mul_f32 v[202:203], v[202:203], v[210:211]
	v_mul_f32_e32 v163, v120, v121
	v_add_f32_e32 v120, 1.0, v122
	v_mul_f32_e32 v121, 0xbfb8aa3b, v117
	v_mul_f32_e32 v126, v202, v203
	v_exp_f32_e32 v203, v121
	v_rcp_f32_e32 v202, v120
	global_load_dwordx4 v[120:123], v[200:201], off
	s_nop 0
	global_load_dwordx2 v[198:199], v[198:199], off
	v_mul_f32_e32 v201, 0xbfb8aa3b, v118
	v_add_f32_e32 v200, 1.0, v203
	v_exp_f32_e32 v201, v201
	v_mul_f32_e32 v203, 0xbfb8aa3b, v119
	v_exp_f32_e32 v203, v203
	v_mul_f32_e32 v205, 0xbfb8aa3b, v113
	v_add_f32_e32 v201, 1.0, v201
	v_rcp_f32_e32 v204, v201
	v_add_f32_e32 v201, 1.0, v203
	v_mul_f32_e32 v203, 0xbfb8aa3b, v112
	v_exp_f32_e32 v203, v203
	v_exp_f32_e32 v205, v205
	v_rcp_f32_e32 v210, v201
	v_rcp_f32_e32 v200, v200
	v_add_f32_e32 v201, 1.0, v203
	v_mul_f32_e32 v203, 0xbfb8aa3b, v114
	v_rcp_f32_e32 v212, v201
	v_add_f32_e32 v201, 1.0, v205
	v_exp_f32_e32 v203, v203
	v_mul_f32_e32 v205, 0xbfb8aa3b, v115
	v_exp_f32_e32 v205, v205
	v_rcp_f32_e32 v214, v201
	v_add_f32_e32 v201, 1.0, v203
	v_rcp_f32_e32 v216, v201
	v_add_f32_e32 v201, 1.0, v205
	v_rcp_f32_e32 v218, v201
	v_lshlrev_b32_e32 v201, 16, v156
	v_mov_b32_e32 v220, v116
	v_and_b32_e32 v116, 0xffff0000, v156
	v_sub_f32_e32 v201, v201, v134
	v_sub_f32_e32 v116, v116, v134
	v_mul_f32_e32 v203, v201, v167
	v_mul_f32_e32 v201, v116, v167
	v_mov_b32_e32 v116, v117
	v_mov_b32_e32 v117, v57
	v_mov_b32_e32 v221, v56
	v_pk_mul_f32 v[116:117], v[116:117], v[200:201]
	v_pk_mul_f32 v[202:203], v[220:221], v[202:203]
	v_mul_f32_e32 v220, v116, v117
	v_lshlrev_b32_e32 v116, 16, v157
	v_sub_f32_e32 v116, v116, v134
	v_mul_f32_e32 v205, v116, v167
	v_mov_b32_e32 v116, v118
	v_mov_b32_e32 v117, v58
	v_pk_mul_f32 v[116:117], v[116:117], v[204:205]
	v_mul_f32_e32 v118, 0xbfb8aa3b, v110
	v_mul_f32_e32 v221, v116, v117
	v_and_b32_e32 v116, 0xffff0000, v157
	v_sub_f32_e32 v116, v116, v134
	v_mul_f32_e32 v211, v116, v167
	v_mov_b32_e32 v116, v119
	v_mov_b32_e32 v117, v59
	v_pk_mul_f32 v[116:117], v[116:117], v[210:211]
	v_exp_f32_e32 v119, v118
	v_mul_f32_e32 v210, v116, v117
	v_lshlrev_b32_e32 v116, 16, v158
	v_sub_f32_e32 v116, v116, v134
	v_mul_f32_e32 v213, v116, v167
	v_mov_b32_e32 v116, v112
	v_and_b32_e32 v112, 0xffff0000, v158
	v_sub_f32_e32 v112, v112, v134
	v_mul_f32_e32 v215, v112, v167
	v_mov_b32_e32 v112, v113
	v_mov_b32_e32 v113, v49
	v_mov_b32_e32 v117, v48
	v_pk_mul_f32 v[112:113], v[112:113], v[214:215]
	v_pk_mul_f32 v[116:117], v[116:117], v[212:213]
	v_mul_f32_e32 v212, v112, v113
	v_lshlrev_b32_e32 v112, 16, v159
	v_sub_f32_e32 v112, v112, v134
	v_mul_f32_e32 v217, v112, v167
	v_mov_b32_e32 v112, v114
	v_mov_b32_e32 v113, v50
	v_pk_mul_f32 v[112:113], v[112:113], v[216:217]
	v_mul_f32_e32 v211, v116, v117
	v_mul_f32_e32 v213, v112, v113
	v_and_b32_e32 v112, 0xffff0000, v159
	v_sub_f32_e32 v112, v112, v134
	v_mul_f32_e32 v117, 0xbfb8aa3b, v109
	v_mul_f32_e32 v219, v112, v167
	v_mov_b32_e32 v112, v115
	s_waitcnt vmcnt(0)
; DI float bflo(unsigned w) { return __uint_as_float(w << 16); }
; DI float bfhi(unsigned w) { return __uint_as_float(w & 0xffff0000u); }
; DI void store8(bf16_t* p, f32x4 a, f32x4 b) { u32x4 w = {cvt_pk_bf16(a[0], a[1]), cvt_pk_bf16(a[2], a[3]), cvt_pk_bf16(b[0], b[1]), cvt_pk_bf16(b[2], b[3])}; *(u32x4*)p = w; }
; DI f32x4 silu4(f32x4 v) { f32x4 r; r[0] = silu_f(v[0]); r[1] = silu_f(v[1]); r[2] = silu_f(v[2]); r[3] = silu_f(v[3]); return r; }
;     DI void operator()(const AccT& acc, const pg8::Unit& u, int wr, int wc, int fr, int fq) const {
;     ...
;             for (int m = 0; m < 4; ++m) { const size_t row = (size_t)u.pm * 256 + wr * 64 + fr + ai * 128 + m * 16;
;                 st[m] = *(const float2*)(stats + (row * 4 + head) * 2);
; #pragma unroll
;                 for (int bj = 0; bj < 2; ++bj) ov[m][bj] = *(const u32x4*)(o + row * 2048 + col0 + bj * 128); }
; #pragma unroll
;             for (int m = 0; m < 4; ++m) { const size_t row = (size_t)u.pm * 256 + wr * 64 + fr + ai * 128 + m * 16;
;                 const float mean = st[m].x * (1.f / 512.f), var = fmaxf(st[m].y * (1.f / 512.f) - mean * mean, 0.f), rstd = rsqrtf(var + 1e-5f);
; #pragma unroll
;                 for (int bj = 0; bj < 2; ++bj) { bf16_t* op = o + row * 2048 + col0 + bj * 128; const u32x4 w = ov[m][bj];
;                     const f32x4 s0 = silu4(acc[ai][bj][m][0]), s1 = silu4(acc[ai][bj][m][1]);
;                     f32x4 y0, y1;
;                     y0[0] = (bflo(w[0]) - mean) * rstd * g0[bj][0] * s0[0]; y0[1] = (bfhi(w[0]) - mean) * rstd * g0[bj][1] * s0[1];
;                     y0[2] = (bflo(w[1]) - mean) * rstd * g0[bj][2] * s0[2]; y0[3] = (bfhi(w[1]) - mean) * rstd * g0[bj][3] * s0[3];
;                     y1[0] = (bflo(w[2]) - mean) * rstd * g1[bj][0] * s1[0]; y1[1] = (bfhi(w[2]) - mean) * rstd * g1[bj][1] * s1[1];
;                     y1[2] = (bflo(w[3]) - mean) * rstd * g1[bj][2] * s1[2]; y1[3] = (bfhi(w[3]) - mean) * rstd * g1[bj][3] * s1[3];
;                     store8(op, y0, y1); } } }
	v_pk_mul_f32 v[114:115], v[198:199], s[54:55] op_sel_hi:[1,0]
	v_exp_f32_e32 v117, v117
	v_fma_f32 v113, -v114, v114, v115
	v_mul_f32_e32 v118, 0xbfb8aa3b, v111
	v_max_f32_e32 v113, 0, v113
	v_exp_f32_e32 v157, v118
	v_add_f32_e32 v113, 0x3727c5ac, v113
	v_mul_f32_e32 v115, 0x4b800000, v113
	v_cmp_gt_f32_e32 vcc, s94, v113
	v_add_f32_e32 v117, 1.0, v117
	v_rcp_f32_e32 v118, v117
	v_cndmask_b32_e32 v113, v113, v115, vcc
	v_add_f32_e32 v117, 1.0, v119
	v_mul_f32_e32 v119, 0xbfb8aa3b, v104
	v_rsq_f32_e32 v115, v113
	v_rcp_f32_e32 v156, v117
	v_add_f32_e32 v117, 1.0, v157
	v_exp_f32_e32 v119, v119
	v_mul_f32_e32 v157, 0xbfb8aa3b, v105
	v_exp_f32_e32 v157, v157
	v_mov_b32_e32 v113, v51
	v_pk_mul_f32 v[112:113], v[112:113], v[218:219]
	v_mul_f32_e32 v116, 0xbfb8aa3b, v108
	v_mul_f32_e32 v134, v112, v113
	v_mul_f32_e32 v112, 0x45800000, v115
	v_rcp_f32_e32 v158, v117
	v_add_f32_e32 v117, 1.0, v119
	v_mul_f32_e32 v119, 0xbfb8aa3b, v106
	v_cndmask_b32_e32 v115, v115, v112, vcc
	v_lshl_add_u64 v[112:113], s[96:97], 0, v[196:197]
	v_exp_f32_e32 v116, v116
	v_rcp_f32_e32 v196, v117
	v_add_f32_e32 v117, 1.0, v157
	v_exp_f32_e32 v119, v119
	v_mul_f32_e32 v157, 0xbfb8aa3b, v107
	v_exp_f32_e32 v157, v157
	v_add_f32_e32 v116, 1.0, v116
	v_rcp_f32_e32 v198, v117
	v_add_f32_e32 v117, 1.0, v119
	v_rcp_f32_e32 v116, v116
	v_rcp_f32_e32 v200, v117
	v_add_f32_e32 v117, 1.0, v157
	v_mov_b32_e32 v204, v108
	v_and_b32_e32 v108, 0xffff0000, v120
	v_mul_f32_e32 v209, v202, v203
	v_rcp_f32_e32 v202, v117
	v_lshlrev_b32_e32 v117, 16, v120
	v_sub_f32_e32 v108, v108, v114
	v_sub_f32_e32 v117, v117, v114
	v_mul_f32_e32 v119, v108, v115
	v_mov_b32_e32 v108, v109
	v_mov_b32_e32 v109, v61
	v_mul_f32_e32 v117, v117, v115
	v_mov_b32_e32 v205, v60
	v_pk_mul_f32 v[108:109], v[108:109], v[118:119]
	v_pk_mul_f32 v[116:117], v[204:205], v[116:117]
	v_mul_f32_e32 v204, v108, v109
	v_lshlrev_b32_e32 v108, 16, v121
	v_sub_f32_e32 v108, v108, v114
	v_mul_f32_e32 v157, v108, v115
	v_mov_b32_e32 v108, v110
	v_mov_b32_e32 v109, v62
	v_pk_mul_f32 v[108:109], v[108:109], v[156:157]
	global_load_dwordx2 v[156:157], v[194:195], off
	v_mul_f32_e32 v205, v108, v109
	v_and_b32_e32 v108, 0xffff0000, v121
	v_sub_f32_e32 v108, v108, v114
	v_mul_f32_e32 v159, v108, v115
	v_mov_b32_e32 v108, v111
	v_mov_b32_e32 v109, v63
	v_pk_mul_f32 v[108:109], v[108:109], v[158:159]
	v_mul_f32_e32 v167, v116, v117
	v_mul_f32_e32 v214, v108, v109
	v_lshlrev_b32_e32 v108, 16, v122
	v_sub_f32_e32 v108, v108, v114
	v_mul_f32_e32 v197, v108, v115
	v_mov_b32_e32 v108, v104
	v_and_b32_e32 v104, 0xffff0000, v122
	v_sub_f32_e32 v104, v104, v114
	v_mul_f32_e32 v199, v104, v115
	v_mov_b32_e32 v104, v105
	v_mov_b32_e32 v105, v69
	v_mov_b32_e32 v109, v68
	v_pk_mul_f32 v[104:105], v[104:105], v[198:199]
	v_pk_mul_f32 v[108:109], v[108:109], v[196:197]
	v_mul_f32_e32 v197, v104, v105
	v_lshlrev_b32_e32 v104, 16, v123
	v_sub_f32_e32 v104, v104, v114
	v_mul_f32_e32 v201, v104, v115
	v_mov_b32_e32 v104, v106
	v_mov_b32_e32 v105, v70
	v_pk_mul_f32 v[104:105], v[104:105], v[200:201]
	v_mul_f32_e32 v106, 0xbfb8aa3b, v100
	v_mul_f32_e32 v198, v104, v105
	v_and_b32_e32 v104, 0xffff0000, v123
	v_sub_f32_e32 v104, v104, v114
	v_mul_f32_e32 v203, v104, v115
	v_mov_b32_e32 v104, v107
	v_exp_f32_e32 v106, v106
	v_mul_f32_e32 v107, 0xbfb8aa3b, v101
	v_exp_f32_e32 v107, v107
	v_mov_b32_e32 v105, v71
	v_pk_mul_f32 v[104:105], v[104:105], v[202:203]
	v_mul_f32_e32 v196, v108, v109
	v_mul_f32_e32 v199, v104, v105
	v_add_f32_e32 v104, 1.0, v106
	v_mul_f32_e32 v106, 0xbfb8aa3b, v102
	v_add_f32_e32 v105, 1.0, v107
	v_exp_f32_e32 v107, v106
	v_mul_f32_e32 v106, 0xbfb8aa3b, v103
	v_exp_f32_e32 v109, v106
	v_rcp_f32_e32 v106, v105
	v_add_f32_e32 v105, 1.0, v107
	v_mul_f32_e32 v107, 0xbfb8aa3b, v96
	v_rcp_f32_e32 v108, v105
	v_add_f32_e32 v105, 1.0, v109
	v_exp_f32_e32 v107, v107
	v_mul_f32_e32 v109, 0xbfb8aa3b, v97
	v_exp_f32_e32 v109, v109
	v_rcp_f32_e32 v110, v105
	v_add_f32_e32 v105, 1.0, v107
	v_mul_f32_e32 v107, 0xbfb8aa3b, v98
	v_rcp_f32_e32 v116, v105
	v_add_f32_e32 v105, 1.0, v109
	v_exp_f32_e32 v107, v107
	v_mul_f32_e32 v109, 0xbfb8aa3b, v99
	v_exp_f32_e32 v109, v109
	v_rcp_f32_e32 v118, v105
	v_add_f32_e32 v105, 1.0, v107
	v_rcp_f32_e32 v104, v104
	v_rcp_f32_e32 v120, v105
	v_add_f32_e32 v105, 1.0, v109
	v_rcp_f32_e32 v122, v105
	v_lshlrev_b32_e32 v105, 16, v148
	v_mov_b32_e32 v158, v100
	v_and_b32_e32 v100, 0xffff0000, v148
	v_sub_f32_e32 v105, v105, v114
	v_sub_f32_e32 v100, v100, v114
	v_mul_f32_e32 v105, v105, v115
	v_mov_b32_e32 v159, v56
	v_mul_f32_e32 v107, v100, v115
	v_mov_b32_e32 v100, v101
	v_mov_b32_e32 v101, v57
	v_pk_mul_f32 v[104:105], v[158:159], v[104:105]
	v_pk_mul_f32 v[100:101], v[100:101], v[106:107]
	v_mul_f32_e32 v104, v104, v105
	v_mul_f32_e32 v105, v100, v101
	v_lshlrev_b32_e32 v100, 16, v149
	v_sub_f32_e32 v100, v100, v114
	v_mul_f32_e32 v109, v100, v115
	v_mov_b32_e32 v100, v102
	v_mov_b32_e32 v101, v58
	v_pk_mul_f32 v[100:101], v[100:101], v[108:109]
	v_lshl_add_u64 v[132:133], v[132:133], 0, v[184:185]
	v_mul_f32_e32 v102, v100, v101
	v_and_b32_e32 v100, 0xffff0000, v149
	v_sub_f32_e32 v100, v100, v114
	v_mul_f32_e32 v111, v100, v115
	v_mov_b32_e32 v100, v103
	v_mov_b32_e32 v101, v59
	v_pk_mul_f32 v[100:101], v[100:101], v[110:111]
	v_lshl_add_u64 v[112:113], v[112:113], 0, v[184:185]
	v_mul_f32_e32 v103, v100, v101
	v_lshlrev_b32_e32 v100, 16, v150
	v_sub_f32_e32 v100, v100, v114
	v_mul_f32_e32 v117, v100, v115
	v_mov_b32_e32 v100, v96
	v_and_b32_e32 v96, 0xffff0000, v150
	v_sub_f32_e32 v96, v96, v114
	v_mov_b32_e32 v101, v48
	v_mul_f32_e32 v119, v96, v115
	v_mov_b32_e32 v96, v97
	v_mov_b32_e32 v97, v49
; DI float bflo(unsigned w) { return __uint_as_float(w << 16); }
; DI float bfhi(unsigned w) { return __uint_as_float(w & 0xffff0000u); }
; DI void store8(bf16_t* p, f32x4 a, f32x4 b) { u32x4 w = {cvt_pk_bf16(a[0], a[1]), cvt_pk_bf16(a[2], a[3]), cvt_pk_bf16(b[0], b[1]), cvt_pk_bf16(b[2], b[3])}; *(u32x4*)p = w; }
; DI f32x4 silu4(f32x4 v) { f32x4 r; r[0] = silu_f(v[0]); r[1] = silu_f(v[1]); r[2] = silu_f(v[2]); r[3] = silu_f(v[3]); return r; }
;     DI void operator()(const AccT& acc, const pg8::Unit& u, int wr, int wc, int fr, int fq) const {
;     ...
;             for (int m = 0; m < 4; ++m) { const size_t row = (size_t)u.pm * 256 + wr * 64 + fr + ai * 128 + m * 16;
;                 st[m] = *(const float2*)(stats + (row * 4 + head) * 2);
; #pragma unroll
;                 for (int bj = 0; bj < 2; ++bj) ov[m][bj] = *(const u32x4*)(o + row * 2048 + col0 + bj * 128); }
; #pragma unroll
;             for (int m = 0; m < 4; ++m) { const size_t row = (size_t)u.pm * 256 + wr * 64 + fr + ai * 128 + m * 16;
;                 const float mean = st[m].x * (1.f / 512.f), var = fmaxf(st[m].y * (1.f / 512.f) - mean * mean, 0.f), rstd = rsqrtf(var + 1e-5f);
; #pragma unroll
;                 for (int bj = 0; bj < 2; ++bj) { bf16_t* op = o + row * 2048 + col0 + bj * 128; const u32x4 w = ov[m][bj];
;                     const f32x4 s0 = silu4(acc[ai][bj][m][0]), s1 = silu4(acc[ai][bj][m][1]);
;                     f32x4 y0, y1;
;                     y0[0] = (bflo(w[0]) - mean) * rstd * g0[bj][0] * s0[0]; y0[1] = (bfhi(w[0]) - mean) * rstd * g0[bj][1] * s0[1];
;                     y0[2] = (bflo(w[1]) - mean) * rstd * g0[bj][2] * s0[2]; y0[3] = (bfhi(w[1]) - mean) * rstd * g0[bj][3] * s0[3];
;                     y1[0] = (bflo(w[2]) - mean) * rstd * g1[bj][0] * s1[0]; y1[1] = (bfhi(w[2]) - mean) * rstd * g1[bj][1] * s1[1];
;                     y1[2] = (bflo(w[3]) - mean) * rstd * g1[bj][2] * s1[2]; y1[3] = (bfhi(w[3]) - mean) * rstd * g1[bj][3] * s1[3];
;                     store8(op, y0, y1); } } }
	v_pk_mul_f32 v[100:101], v[100:101], v[116:117]
	v_pk_mul_f32 v[96:97], v[96:97], v[118:119]
	v_mul_f32_e32 v100, v100, v101
	v_mul_f32_e32 v101, v96, v97
	v_lshlrev_b32_e32 v96, 16, v151
	v_sub_f32_e32 v96, v96, v114
	v_mul_f32_e32 v121, v96, v115
	v_mov_b32_e32 v96, v98
	v_mov_b32_e32 v97, v50
	v_pk_mul_f32 v[96:97], v[96:97], v[120:121]
	v_mov_b32_e32 v116, v92
	v_mul_f32_e32 v106, v96, v97
	v_and_b32_e32 v96, 0xffff0000, v151
	v_sub_f32_e32 v96, v96, v114
	v_mul_f32_e32 v123, v96, v115
	v_mov_b32_e32 v96, v99
	v_mov_b32_e32 v97, v51
	v_pk_mul_f32 v[96:97], v[96:97], v[122:123]
	v_mov_b32_e32 v117, v60
	v_mul_f32_e32 v107, v96, v97
	v_cvt_pk_bf16_f32 v96, v152, v153
	v_cvt_pk_bf16_f32 v97, v154, v155
	v_cvt_pk_bf16_f32 v98, v144, v145
	v_cvt_pk_bf16_f32 v99, v146, v147
	global_store_dwordx4 v[192:193], v[96:99], off
	s_nop 1
	v_cvt_pk_bf16_f32 v96, v136, v137
	v_cvt_pk_bf16_f32 v97, v138, v139
	v_cvt_pk_bf16_f32 v98, v164, v165
	v_cvt_pk_bf16_f32 v99, v166, v135
	global_store_dwordx4 v[192:193], v[96:99], off offset:256
	s_nop 1
	v_cvt_pk_bf16_f32 v96, v124, v125
	v_cvt_pk_bf16_f32 v97, v126, v127
	v_cvt_pk_bf16_f32 v98, v160, v161
	v_cvt_pk_bf16_f32 v99, v162, v163
	global_store_dwordx4 v[132:133], v[96:99], off
	v_mul_f32_e32 v127, 0xbfb8aa3b, v77
	v_exp_f32_e32 v127, v127
	v_cvt_pk_bf16_f32 v96, v209, v220
	v_cvt_pk_bf16_f32 v97, v221, v210
	v_cvt_pk_bf16_f32 v98, v211, v212
	v_cvt_pk_bf16_f32 v99, v213, v134
	global_store_dwordx4 v[132:133], v[96:99], off offset:256
	v_add_f32_e32 v127, 1.0, v127
	s_nop 0
	v_cvt_pk_bf16_f32 v96, v167, v204
	v_cvt_pk_bf16_f32 v97, v205, v214
	v_cvt_pk_bf16_f32 v98, v196, v197
	v_cvt_pk_bf16_f32 v99, v198, v199
	global_store_dwordx4 v[112:113], v[96:99], off
	s_waitcnt vmcnt(0)
	s_nop 0
	v_pk_mul_f32 v[96:97], v[156:157], s[54:55] op_sel_hi:[1,0]
	v_cvt_pk_bf16_f32 v98, v104, v105
	v_cvt_pk_bf16_f32 v99, v102, v103
	v_cvt_pk_bf16_f32 v100, v100, v101
	v_cvt_pk_bf16_f32 v101, v106, v107
	global_store_dwordx4 v[112:113], v[98:101], off offset:256
	v_fma_f32 v97, -v96, v96, v97
	v_max_f32_e32 v97, 0, v97
	v_add_f32_e32 v97, 0x3727c5ac, v97
	v_mul_f32_e32 v102, 0x4b800000, v97
	v_cmp_gt_f32_e32 vcc, s94, v97
	v_mul_f32_e32 v101, 0xbfb8aa3b, v93
	v_exp_f32_e32 v101, v101
	v_cndmask_b32_e32 v97, v97, v102, vcc
	v_mul_f32_e32 v102, 0xbfb8aa3b, v94
	v_exp_f32_e32 v103, v102
	v_mul_f32_e32 v102, 0xbfb8aa3b, v95
	v_exp_f32_e32 v105, v102
	v_add_f32_e32 v101, 1.0, v101
	v_rcp_f32_e32 v102, v101
	v_add_f32_e32 v101, 1.0, v103
	v_mul_f32_e32 v103, 0xbfb8aa3b, v88
	v_rcp_f32_e32 v104, v101
	v_add_f32_e32 v101, 1.0, v105
	v_exp_f32_e32 v103, v103
	v_mul_f32_e32 v105, 0xbfb8aa3b, v89
	v_exp_f32_e32 v105, v105
	v_mul_f32_e32 v100, 0xbfb8aa3b, v92
	v_rcp_f32_e32 v106, v101
	v_add_f32_e32 v101, 1.0, v103
	v_mul_f32_e32 v103, 0xbfb8aa3b, v90
	v_exp_f32_e32 v100, v100
	v_rcp_f32_e32 v108, v101
	v_add_f32_e32 v101, 1.0, v105
	v_exp_f32_e32 v103, v103
	v_mul_f32_e32 v105, 0xbfb8aa3b, v91
	v_exp_f32_e32 v105, v105
	v_rsq_f32_e32 v97, v97
	v_add_f32_e32 v100, 1.0, v100
	v_rcp_f32_e32 v110, v101
	v_add_f32_e32 v101, 1.0, v103
	v_rcp_f32_e32 v100, v100
	v_rcp_f32_e32 v112, v101
	v_add_f32_e32 v101, 1.0, v105
	v_mul_f32_e32 v98, 0x45800000, v97
	v_rcp_f32_e32 v114, v101
	v_lshlrev_b32_e32 v101, 16, v140
	v_and_b32_e32 v92, 0xffff0000, v140
	v_cndmask_b32_e32 v97, v97, v98, vcc
	v_sub_f32_e32 v101, v101, v96
	v_sub_f32_e32 v92, v92, v96
	v_mul_f32_e32 v101, v101, v97
	v_mul_f32_e32 v103, v92, v97
	v_mov_b32_e32 v92, v93
	v_mov_b32_e32 v93, v61
	v_pk_mul_f32 v[100:101], v[116:117], v[100:101]
	v_pk_mul_f32 v[92:93], v[92:93], v[102:103]
	v_mul_f32_e32 v100, v100, v101
	v_mul_f32_e32 v101, v92, v93
	v_lshlrev_b32_e32 v92, 16, v141
	v_sub_f32_e32 v92, v92, v96
	v_mul_f32_e32 v105, v92, v97
	v_mov_b32_e32 v92, v94
	v_mov_b32_e32 v93, v62
	v_pk_mul_f32 v[92:93], v[92:93], v[104:105]
	v_lshl_add_u64 v[98:99], s[96:97], 0, v[190:191]
	v_mul_f32_e32 v94, v92, v93
	v_and_b32_e32 v92, 0xffff0000, v141
	v_sub_f32_e32 v92, v92, v96
	v_mul_f32_e32 v107, v92, v97
	v_mov_b32_e32 v92, v95
	v_mov_b32_e32 v93, v63
	v_pk_mul_f32 v[92:93], v[92:93], v[106:107]
	v_lshl_add_u64 v[98:99], v[98:99], 0, v[184:185]
	v_mul_f32_e32 v95, v92, v93
	v_lshlrev_b32_e32 v92, 16, v142
	v_sub_f32_e32 v92, v92, v96
	v_mul_f32_e32 v109, v92, v97
	v_mov_b32_e32 v92, v88
	v_and_b32_e32 v88, 0xffff0000, v142
	v_sub_f32_e32 v88, v88, v96
	v_mov_b32_e32 v93, v68
	v_mul_f32_e32 v111, v88, v97
	v_mov_b32_e32 v88, v89
	v_mov_b32_e32 v89, v69
	v_pk_mul_f32 v[92:93], v[92:93], v[108:109]
	v_pk_mul_f32 v[88:89], v[88:89], v[110:111]
	v_mul_f32_e32 v92, v92, v93
	v_mul_f32_e32 v93, v88, v89
	v_lshlrev_b32_e32 v88, 16, v143
	v_sub_f32_e32 v88, v88, v96
	v_mul_f32_e32 v113, v88, v97
	v_mov_b32_e32 v88, v90
	v_mov_b32_e32 v89, v70
	v_pk_mul_f32 v[88:89], v[88:89], v[112:113]
	v_mov_b32_e32 v108, v84
	v_mul_f32_e32 v102, v88, v89
	v_and_b32_e32 v88, 0xffff0000, v143
	v_sub_f32_e32 v88, v88, v96
	v_mul_f32_e32 v115, v88, v97
	v_mov_b32_e32 v88, v91
	v_mov_b32_e32 v89, v71
	v_pk_mul_f32 v[88:89], v[88:89], v[114:115]
	v_mov_b32_e32 v109, v56
	v_mul_f32_e32 v91, v88, v89
	v_cvt_pk_bf16_f32 v88, v100, v101
	v_cvt_pk_bf16_f32 v89, v94, v95
	v_cvt_pk_bf16_f32 v90, v92, v93
	v_mul_f32_e32 v93, 0xbfb8aa3b, v85
	v_exp_f32_e32 v93, v93
	v_cvt_pk_bf16_f32 v91, v102, v91
	global_store_dwordx4 v[98:99], v[88:91], off
	v_mul_f32_e32 v92, 0xbfb8aa3b, v84
	v_exp_f32_e32 v92, v92
	v_mul_f32_e32 v90, 0xbfb8aa3b, v86
	v_exp_f32_e32 v91, v90
	v_mul_f32_e32 v90, 0xbfb8aa3b, v87
	v_add_f32_e32 v89, 1.0, v93
	v_exp_f32_e32 v93, v90
	v_rcp_f32_e32 v90, v89
	v_add_f32_e32 v89, 1.0, v91
; DI float bflo(unsigned w) { return __uint_as_float(w << 16); }
; DI float bfhi(unsigned w) { return __uint_as_float(w & 0xffff0000u); }
; DI void store8(bf16_t* p, f32x4 a, f32x4 b) { u32x4 w = {cvt_pk_bf16(a[0], a[1]), cvt_pk_bf16(a[2], a[3]), cvt_pk_bf16(b[0], b[1]), cvt_pk_bf16(b[2], b[3])}; *(u32x4*)p = w; }
; DI f32x4 silu4(f32x4 v) { f32x4 r; r[0] = silu_f(v[0]); r[1] = silu_f(v[1]); r[2] = silu_f(v[2]); r[3] = silu_f(v[3]); return r; }
;     DI void operator()(const AccT& acc, const pg8::Unit& u, int wr, int wc, int fr, int fq) const {
;     ...
; #pragma unroll
;         for (int ai = 0; ai < 2; ++ai) {
;             float2 st[4]; u32x4 ov[4][2];
; #pragma unroll
;             for (int m = 0; m < 4; ++m) { const size_t row = (size_t)u.pm * 256 + wr * 64 + fr + ai * 128 + m * 16;
;                 st[m] = *(const float2*)(stats + (row * 4 + head) * 2);
; #pragma unroll
;                 for (int bj = 0; bj < 2; ++bj) ov[m][bj] = *(const u32x4*)(o + row * 2048 + col0 + bj * 128); }
; #pragma unroll
;             for (int m = 0; m < 4; ++m) { const size_t row = (size_t)u.pm * 256 + wr * 64 + fr + ai * 128 + m * 16;
;                 const float mean = st[m].x * (1.f / 512.f), var = fmaxf(st[m].y * (1.f / 512.f) - mean * mean, 0.f), rstd = rsqrtf(var + 1e-5f);
; #pragma unroll
;                 for (int bj = 0; bj < 2; ++bj) { bf16_t* op = o + row * 2048 + col0 + bj * 128; const u32x4 w = ov[m][bj];
;                     const f32x4 s0 = silu4(acc[ai][bj][m][0]), s1 = silu4(acc[ai][bj][m][1]);
;                     f32x4 y0, y1;
;                     y0[0] = (bflo(w[0]) - mean) * rstd * g0[bj][0] * s0[0]; y0[1] = (bfhi(w[0]) - mean) * rstd * g0[bj][1] * s0[1];
;                     y0[2] = (bflo(w[1]) - mean) * rstd * g0[bj][2] * s0[2]; y0[3] = (bfhi(w[1]) - mean) * rstd * g0[bj][3] * s0[3];
;                     y1[0] = (bflo(w[2]) - mean) * rstd * g1[bj][0] * s1[0]; y1[1] = (bfhi(w[2]) - mean) * rstd * g1[bj][1] * s1[1];
;                     y1[2] = (bflo(w[3]) - mean) * rstd * g1[bj][2] * s1[2]; y1[3] = (bfhi(w[3]) - mean) * rstd * g1[bj][3] * s1[3];
;                     store8(op, y0, y1); } } }
	v_mul_f32_e32 v91, 0xbfb8aa3b, v80
	v_add_f32_e32 v88, 1.0, v92
	v_rcp_f32_e32 v92, v89
	v_add_f32_e32 v89, 1.0, v93
	v_exp_f32_e32 v91, v91
	v_mul_f32_e32 v93, 0xbfb8aa3b, v81
	v_exp_f32_e32 v93, v93
	v_rcp_f32_e32 v94, v89
	v_add_f32_e32 v89, 1.0, v91
	v_mul_f32_e32 v91, 0xbfb8aa3b, v82
	v_rcp_f32_e32 v100, v89
	v_add_f32_e32 v89, 1.0, v93
	v_exp_f32_e32 v91, v91
	v_mul_f32_e32 v93, 0xbfb8aa3b, v83
	v_exp_f32_e32 v93, v93
	v_rcp_f32_e32 v102, v89
	v_add_f32_e32 v89, 1.0, v91
	v_rcp_f32_e32 v88, v88
	v_rcp_f32_e32 v104, v89
	v_add_f32_e32 v89, 1.0, v93
	v_rcp_f32_e32 v106, v89
	v_lshlrev_b32_e32 v89, 16, v128
	v_and_b32_e32 v84, 0xffff0000, v128
	v_sub_f32_e32 v89, v89, v96
	v_sub_f32_e32 v84, v84, v96
	v_mul_f32_e32 v89, v89, v97
	v_mul_f32_e32 v91, v84, v97
	v_mov_b32_e32 v84, v85
	v_mov_b32_e32 v85, v57
	v_pk_mul_f32 v[88:89], v[108:109], v[88:89]
	v_pk_mul_f32 v[84:85], v[84:85], v[90:91]
	v_mul_f32_e32 v88, v88, v89
	v_mul_f32_e32 v89, v84, v85
	v_lshlrev_b32_e32 v84, 16, v129
	v_sub_f32_e32 v84, v84, v96
	v_mul_f32_e32 v93, v84, v97
	v_mov_b32_e32 v84, v86
	v_mov_b32_e32 v85, v58
	v_pk_mul_f32 v[84:85], v[84:85], v[92:93]
	v_mul_f32_e32 v128, 0xbfb8aa3b, v78
	v_mul_f32_e32 v86, v84, v85
	v_and_b32_e32 v84, 0xffff0000, v129
	v_sub_f32_e32 v84, v84, v96
	v_mul_f32_e32 v95, v84, v97
	v_mov_b32_e32 v84, v87
	v_mov_b32_e32 v85, v59
	v_pk_mul_f32 v[84:85], v[84:85], v[94:95]
	v_exp_f32_e32 v129, v128
	v_mul_f32_e32 v87, v84, v85
	v_lshlrev_b32_e32 v84, 16, v130
	v_sub_f32_e32 v84, v84, v96
	v_mul_f32_e32 v101, v84, v97
	v_mov_b32_e32 v84, v80
	v_and_b32_e32 v80, 0xffff0000, v130
	v_sub_f32_e32 v80, v80, v96
	v_mov_b32_e32 v85, v48
	v_mul_f32_e32 v103, v80, v97
	v_mov_b32_e32 v80, v81
	v_mov_b32_e32 v81, v49
	v_pk_mul_f32 v[84:85], v[84:85], v[100:101]
	v_pk_mul_f32 v[80:81], v[80:81], v[102:103]
	v_mul_f32_e32 v84, v84, v85
	v_mul_f32_e32 v85, v80, v81
	v_lshlrev_b32_e32 v80, 16, v131
	v_sub_f32_e32 v80, v80, v96
	v_mul_f32_e32 v105, v80, v97
	v_mov_b32_e32 v80, v82
	v_mov_b32_e32 v81, v50
	v_pk_mul_f32 v[80:81], v[80:81], v[104:105]
	v_mul_f32_e32 v128, 0xbfb8aa3b, v79
	v_mul_f32_e32 v90, v80, v81
	v_and_b32_e32 v80, 0xffff0000, v131
	v_sub_f32_e32 v80, v80, v96
	v_mul_f32_e32 v107, v80, v97
	v_mov_b32_e32 v80, v83
	v_mov_b32_e32 v81, v51
	v_pk_mul_f32 v[80:81], v[80:81], v[106:107]
	v_exp_f32_e32 v131, v128
	v_mul_f32_e32 v83, v80, v81
	v_cvt_pk_bf16_f32 v80, v88, v89
	v_cvt_pk_bf16_f32 v81, v86, v87
	v_cvt_pk_bf16_f32 v82, v84, v85
	v_cvt_pk_bf16_f32 v83, v90, v83
	global_store_dwordx4 v[98:99], v[80:83], off offset:256
	v_rcp_f32_e32 v128, v127
	v_add_f32_e32 v127, 1.0, v129
	v_lshl_add_u64 v[80:81], v[188:189], 0, s[38:39]
	v_lshlrev_b64 v[82:83], 5, v[80:81]
	v_lshl_add_u64 v[82:83], s[16:17], 0, v[82:83]
	global_load_dwordx2 v[82:83], v[82:83], off
	v_lshlrev_b64 v[106:107], 12, v[80:81]
	v_lshl_add_u64 v[80:81], v[186:187], 0, v[106:107]
	global_load_dwordx4 v[122:125], v[80:81], off
	global_load_dwordx4 v[100:103], v[80:81], off offset:256
	v_lshl_add_u64 v[80:81], v[188:189], 0, s[20:21]
	v_lshlrev_b64 v[116:117], 12, v[80:81]
	v_lshlrev_b64 v[84:85], 5, v[80:81]
	v_lshl_add_u64 v[80:81], v[186:187], 0, v[116:117]
	s_mov_b64 s[20:21], 0xa0
	global_load_dwordx4 v[96:99], v[80:81], off
	global_load_dwordx4 v[92:95], v[80:81], off offset:256
	v_lshl_add_u64 v[80:81], v[188:189], 0, s[20:21]
	s_mov_b64 s[20:21], 0xb0
	v_lshl_add_u64 v[120:121], s[16:17], 0, v[84:85]
	v_lshlrev_b64 v[84:85], 5, v[80:81]
	v_lshlrev_b64 v[110:111], 12, v[80:81]
	v_lshl_add_u64 v[80:81], v[188:189], 0, s[20:21]
	v_lshl_add_u64 v[112:113], s[16:17], 0, v[84:85]
	v_lshlrev_b64 v[84:85], 5, v[80:81]
	v_lshlrev_b64 v[104:105], 12, v[80:81]
	v_lshl_add_u64 v[114:115], v[186:187], 0, v[110:111]
	global_load_dwordx4 v[88:91], v[114:115], off offset:256
	v_lshl_add_u64 v[108:109], s[16:17], 0, v[84:85]
	v_mul_f32_e32 v129, 0xbfb8aa3b, v72
	v_rcp_f32_e32 v130, v127
	v_add_f32_e32 v127, 1.0, v131
	v_exp_f32_e32 v129, v129
	v_mul_f32_e32 v131, 0xbfb8aa3b, v73
	v_exp_f32_e32 v131, v131
	v_rcp_f32_e32 v132, v127
	v_add_f32_e32 v127, 1.0, v129
	v_mul_f32_e32 v129, 0xbfb8aa3b, v74
	v_rcp_f32_e32 v134, v127
	v_add_f32_e32 v127, 1.0, v131
	v_exp_f32_e32 v129, v129
	v_mul_f32_e32 v131, 0xbfb8aa3b, v75
	v_exp_f32_e32 v131, v131
	v_rcp_f32_e32 v136, v127
	v_add_f32_e32 v127, 1.0, v129
	v_rcp_f32_e32 v138, v127
	v_add_f32_e32 v127, 1.0, v131
	v_rcp_f32_e32 v140, v127
	v_mov_b32_e32 v142, v76
	v_mov_b32_e32 v143, v60
	v_lshl_add_u64 v[106:107], s[96:97], 0, v[106:107]
	v_lshl_add_u64 v[106:107], v[106:107], 0, v[184:185]
	s_mov_b32 s16, s10
	s_mov_b64 s[20:21], s[12:13]
	s_waitcnt vmcnt(0)
; DI float bflo(unsigned w) { return __uint_as_float(w << 16); }
; DI float bfhi(unsigned w) { return __uint_as_float(w & 0xffff0000u); }
; DI void store8(bf16_t* p, f32x4 a, f32x4 b) { u32x4 w = {cvt_pk_bf16(a[0], a[1]), cvt_pk_bf16(a[2], a[3]), cvt_pk_bf16(b[0], b[1]), cvt_pk_bf16(b[2], b[3])}; *(u32x4*)p = w; }
; DI f32x4 silu4(f32x4 v) { f32x4 r; r[0] = silu_f(v[0]); r[1] = silu_f(v[1]); r[2] = silu_f(v[2]); r[3] = silu_f(v[3]); return r; }
;     DI void operator()(const AccT& acc, const pg8::Unit& u, int wr, int wc, int fr, int fq) const {
;     ...
;             for (int m = 0; m < 4; ++m) { const size_t row = (size_t)u.pm * 256 + wr * 64 + fr + ai * 128 + m * 16;
;                 st[m] = *(const float2*)(stats + (row * 4 + head) * 2);
; #pragma unroll
;                 for (int bj = 0; bj < 2; ++bj) ov[m][bj] = *(const u32x4*)(o + row * 2048 + col0 + bj * 128); }
; #pragma unroll
;             for (int m = 0; m < 4; ++m) { const size_t row = (size_t)u.pm * 256 + wr * 64 + fr + ai * 128 + m * 16;
;                 const float mean = st[m].x * (1.f / 512.f), var = fmaxf(st[m].y * (1.f / 512.f) - mean * mean, 0.f), rstd = rsqrtf(var + 1e-5f);
; #pragma unroll
;                 for (int bj = 0; bj < 2; ++bj) { bf16_t* op = o + row * 2048 + col0 + bj * 128; const u32x4 w = ov[m][bj];
;                     const f32x4 s0 = silu4(acc[ai][bj][m][0]), s1 = silu4(acc[ai][bj][m][1]);
;                     f32x4 y0, y1;
;                     y0[0] = (bflo(w[0]) - mean) * rstd * g0[bj][0] * s0[0]; y0[1] = (bfhi(w[0]) - mean) * rstd * g0[bj][1] * s0[1];
;                     y0[2] = (bflo(w[1]) - mean) * rstd * g0[bj][2] * s0[2]; y0[3] = (bfhi(w[1]) - mean) * rstd * g0[bj][3] * s0[3];
;                     y1[0] = (bflo(w[2]) - mean) * rstd * g1[bj][0] * s1[0]; y1[1] = (bfhi(w[2]) - mean) * rstd * g1[bj][1] * s1[1];
;                     y1[2] = (bflo(w[3]) - mean) * rstd * g1[bj][2] * s1[2]; y1[3] = (bfhi(w[3]) - mean) * rstd * g1[bj][3] * s1[3];
;                     store8(op, y0, y1); } } }
	v_pk_mul_f32 v[118:119], v[82:83], s[54:55] op_sel_hi:[1,0]
	s_nop 0
	v_fma_f32 v80, -v118, v118, v119
	v_max_f32_e32 v80, 0, v80
	v_add_f32_e32 v80, 0x3727c5ac, v80
	v_mul_f32_e32 v81, 0x4b800000, v80
	v_cmp_gt_f32_e32 vcc, s94, v80
	v_lshlrev_b32_e32 v127, 16, v122
	v_and_b32_e32 v122, 0xffff0000, v122
	v_cndmask_b32_e32 v80, v80, v81, vcc
	v_rsq_f32_e32 v119, v80
	v_lshl_add_u64 v[80:81], v[186:187], 0, v[104:105]
	global_load_dwordx4 v[84:87], v[80:81], off
	s_nop 0
	global_load_dwordx4 v[80:83], v[80:81], off offset:256
	v_sub_f32_e32 v122, v122, v118
	global_load_dwordx2 v[120:121], v[120:121], off
	v_mul_f32_e32 v126, 0x45800000, v119
	v_cndmask_b32_e32 v119, v119, v126, vcc
	v_mul_f32_e32 v129, v122, v119
	v_lshlrev_b32_e32 v122, 16, v123
	v_sub_f32_e32 v122, v122, v118
	v_mul_f32_e32 v131, v122, v119
	v_and_b32_e32 v122, 0xffff0000, v123
	v_sub_f32_e32 v122, v122, v118
	v_mul_f32_e32 v133, v122, v119
	v_mov_b32_e32 v122, v79
	v_mov_b32_e32 v123, v63
	v_pk_mul_f32 v[122:123], v[122:123], v[132:133]
	v_mul_f32_e32 v126, 0xbfb8aa3b, v76
	v_mul_f32_e32 v79, v122, v123
	v_lshlrev_b32_e32 v122, 16, v124
	v_sub_f32_e32 v122, v122, v118
	v_mul_f32_e32 v135, v122, v119
	v_mov_b32_e32 v122, v72
	v_mov_b32_e32 v123, v68
	v_pk_mul_f32 v[122:123], v[122:123], v[134:135]
	v_exp_f32_e32 v126, v126
	v_mul_f32_e32 v72, v122, v123
	v_and_b32_e32 v122, 0xffff0000, v124
	v_sub_f32_e32 v122, v122, v118
	v_mul_f32_e32 v137, v122, v119
	v_mov_b32_e32 v122, v73
	v_mov_b32_e32 v123, v69
	v_pk_mul_f32 v[122:123], v[122:123], v[136:137]
	v_add_f32_e32 v126, 1.0, v126
	v_mul_f32_e32 v73, v122, v123
	v_lshlrev_b32_e32 v122, 16, v125
	v_sub_f32_e32 v122, v122, v118
	v_mul_f32_e32 v139, v122, v119
	v_mov_b32_e32 v122, v74
	v_mov_b32_e32 v123, v70
	v_pk_mul_f32 v[122:123], v[122:123], v[138:139]
	v_rcp_f32_e32 v126, v126
	v_mul_f32_e32 v74, v122, v123
	v_and_b32_e32 v122, 0xffff0000, v125
	v_sub_f32_e32 v122, v122, v118
	v_sub_f32_e32 v127, v127, v118
	v_mul_f32_e32 v141, v122, v119
	v_mov_b32_e32 v122, v75
	v_mul_f32_e32 v75, 0xbfb8aa3b, v64
	v_mul_f32_e32 v127, v127, v119
	v_exp_f32_e32 v124, v75
	v_pk_mul_f32 v[126:127], v[142:143], v[126:127]
	v_mov_b32_e32 v123, v71
	v_mul_f32_e32 v76, v126, v127
	v_mov_b32_e32 v126, v77
	v_mov_b32_e32 v127, v61
	v_pk_mul_f32 v[122:123], v[122:123], v[140:141]
	v_pk_mul_f32 v[126:127], v[126:127], v[128:129]
	v_mul_f32_e32 v75, v122, v123
	v_mul_f32_e32 v122, 0xbfb8aa3b, v65
	v_mul_f32_e32 v77, v126, v127
	v_mov_b32_e32 v126, v78
	v_mov_b32_e32 v127, v62
	v_exp_f32_e32 v123, v122
	v_add_f32_e32 v122, 1.0, v124
	v_mul_f32_e32 v124, 0xbfb8aa3b, v66
	v_pk_mul_f32 v[126:127], v[126:127], v[130:131]
	v_exp_f32_e32 v125, v124
	v_mul_f32_e32 v124, 0xbfb8aa3b, v67
	v_mul_f32_e32 v78, v126, v127
	v_exp_f32_e32 v127, v124
	v_add_f32_e32 v123, 1.0, v123
	v_rcp_f32_e32 v124, v123
	v_add_f32_e32 v123, 1.0, v125
	v_mul_f32_e32 v125, 0xbfb8aa3b, v52
	v_rcp_f32_e32 v126, v123
	v_add_f32_e32 v123, 1.0, v127
	v_exp_f32_e32 v125, v125
	v_mul_f32_e32 v127, 0xbfb8aa3b, v53
	v_exp_f32_e32 v127, v127
	v_rcp_f32_e32 v128, v123
	v_add_f32_e32 v123, 1.0, v125
	v_mul_f32_e32 v125, 0xbfb8aa3b, v54
	v_rcp_f32_e32 v130, v123
	v_add_f32_e32 v123, 1.0, v127
	v_exp_f32_e32 v125, v125
	v_mul_f32_e32 v127, 0xbfb8aa3b, v55
	v_exp_f32_e32 v127, v127
	v_rcp_f32_e32 v132, v123
	v_add_f32_e32 v123, 1.0, v125
	v_rcp_f32_e32 v134, v123
	v_add_f32_e32 v123, 1.0, v127
	v_rcp_f32_e32 v136, v123
	v_lshlrev_b32_e32 v123, 16, v100
	v_and_b32_e32 v100, 0xffff0000, v100
	v_sub_f32_e32 v100, v100, v118
	v_mul_f32_e32 v125, v100, v119
	v_lshlrev_b32_e32 v100, 16, v101
	v_sub_f32_e32 v100, v100, v118
	v_mul_f32_e32 v127, v100, v119
	v_and_b32_e32 v100, 0xffff0000, v101
	v_sub_f32_e32 v100, v100, v118
	v_mul_f32_e32 v129, v100, v119
	v_mov_b32_e32 v100, v67
	v_mov_b32_e32 v101, v59
	v_pk_mul_f32 v[100:101], v[100:101], v[128:129]
	v_sub_f32_e32 v123, v123, v118
	v_mul_f32_e32 v67, v100, v101
	v_lshlrev_b32_e32 v100, 16, v102
	v_sub_f32_e32 v100, v100, v118
	v_mul_f32_e32 v131, v100, v119
	v_mov_b32_e32 v100, v52
	v_and_b32_e32 v52, 0xffff0000, v102
	v_sub_f32_e32 v52, v52, v118
	v_mov_b32_e32 v101, v48
	v_mul_f32_e32 v133, v52, v119
	v_mov_b32_e32 v52, v53
	v_mov_b32_e32 v53, v49
	v_pk_mul_f32 v[100:101], v[100:101], v[130:131]
	v_pk_mul_f32 v[52:53], v[52:53], v[132:133]
	v_mul_f32_e32 v100, v100, v101
	v_mul_f32_e32 v101, v52, v53
	v_lshlrev_b32_e32 v52, 16, v103
	v_sub_f32_e32 v52, v52, v118
	v_mul_f32_e32 v135, v52, v119
	v_mov_b32_e32 v52, v54
	v_mov_b32_e32 v53, v50
	v_pk_mul_f32 v[52:53], v[52:53], v[134:135]
	v_rcp_f32_e32 v122, v122
	v_mul_f32_e32 v102, v52, v53
	v_and_b32_e32 v52, 0xffff0000, v103
	v_sub_f32_e32 v52, v52, v118
	v_mul_f32_e32 v137, v52, v119
	v_mov_b32_e32 v52, v55
	s_waitcnt vmcnt(0)
; DI float bflo(unsigned w) { return __uint_as_float(w << 16); }
; DI float bfhi(unsigned w) { return __uint_as_float(w & 0xffff0000u); }
; DI void store8(bf16_t* p, f32x4 a, f32x4 b) { u32x4 w = {cvt_pk_bf16(a[0], a[1]), cvt_pk_bf16(a[2], a[3]), cvt_pk_bf16(b[0], b[1]), cvt_pk_bf16(b[2], b[3])}; *(u32x4*)p = w; }
; DI f32x4 silu4(f32x4 v) { f32x4 r; r[0] = silu_f(v[0]); r[1] = silu_f(v[1]); r[2] = silu_f(v[2]); r[3] = silu_f(v[3]); return r; }
;     DI void operator()(const AccT& acc, const pg8::Unit& u, int wr, int wc, int fr, int fq) const {
;     ...
;             for (int m = 0; m < 4; ++m) { const size_t row = (size_t)u.pm * 256 + wr * 64 + fr + ai * 128 + m * 16;
;                 st[m] = *(const float2*)(stats + (row * 4 + head) * 2);
; #pragma unroll
;                 for (int bj = 0; bj < 2; ++bj) ov[m][bj] = *(const u32x4*)(o + row * 2048 + col0 + bj * 128); }
; #pragma unroll
;             for (int m = 0; m < 4; ++m) { const size_t row = (size_t)u.pm * 256 + wr * 64 + fr + ai * 128 + m * 16;
;                 const float mean = st[m].x * (1.f / 512.f), var = fmaxf(st[m].y * (1.f / 512.f) - mean * mean, 0.f), rstd = rsqrtf(var + 1e-5f);
; #pragma unroll
;                 for (int bj = 0; bj < 2; ++bj) { bf16_t* op = o + row * 2048 + col0 + bj * 128; const u32x4 w = ov[m][bj];
;                     const f32x4 s0 = silu4(acc[ai][bj][m][0]), s1 = silu4(acc[ai][bj][m][1]);
;                     f32x4 y0, y1;
;                     y0[0] = (bflo(w[0]) - mean) * rstd * g0[bj][0] * s0[0]; y0[1] = (bfhi(w[0]) - mean) * rstd * g0[bj][1] * s0[1];
;                     y0[2] = (bflo(w[1]) - mean) * rstd * g0[bj][2] * s0[2]; y0[3] = (bfhi(w[1]) - mean) * rstd * g0[bj][3] * s0[3];
;                     y1[0] = (bflo(w[2]) - mean) * rstd * g1[bj][0] * s1[0]; y1[1] = (bfhi(w[2]) - mean) * rstd * g1[bj][1] * s1[1];
;                     y1[2] = (bflo(w[3]) - mean) * rstd * g1[bj][2] * s1[2]; y1[3] = (bfhi(w[3]) - mean) * rstd * g1[bj][3] * s1[3];
;                     store8(op, y0, y1); } } }
	v_pk_mul_f32 v[54:55], v[120:121], s[54:55] op_sel_hi:[1,0]
	v_mul_f32_e32 v118, 0xbfb8aa3b, v46
	v_fma_f32 v53, -v54, v54, v55
	v_max_f32_e32 v53, 0, v53
	v_add_f32_e32 v53, 0x3727c5ac, v53
	v_mul_f32_e32 v55, 0x4b800000, v53
	v_cmp_gt_f32_e32 vcc, s94, v53
	v_mul_f32_e32 v123, v123, v119
	v_exp_f32_e32 v119, v118
	v_cndmask_b32_e32 v53, v53, v55, vcc
	v_rsq_f32_e32 v103, v53
	v_mov_b32_e32 v53, v51
	v_pk_mul_f32 v[52:53], v[52:53], v[136:137]
	v_mul_f32_e32 v118, 0xbfb8aa3b, v47
	v_mul_f32_e32 v55, v52, v53
	v_mul_f32_e32 v52, 0x45800000, v103
	v_cndmask_b32_e32 v103, v103, v52, vcc
	v_lshl_add_u64 v[52:53], s[96:97], 0, v[116:117]
	v_mul_f32_e32 v117, 0xbfb8aa3b, v45
	v_exp_f32_e32 v117, v117
	v_exp_f32_e32 v121, v118
	v_mov_b32_e32 v138, v64
	v_mov_b32_e32 v139, v56
	v_add_f32_e32 v117, 1.0, v117
	v_pk_mul_f32 v[122:123], v[138:139], v[122:123]
	v_rcp_f32_e32 v118, v117
	v_add_f32_e32 v117, 1.0, v119
	v_mul_f32_e32 v119, 0xbfb8aa3b, v40
	v_mul_f32_e32 v64, v122, v123
	v_mov_b32_e32 v122, v65
	v_mov_b32_e32 v123, v57
	v_rcp_f32_e32 v120, v117
	v_add_f32_e32 v117, 1.0, v121
	v_exp_f32_e32 v119, v119
	v_mul_f32_e32 v121, 0xbfb8aa3b, v41
	v_pk_mul_f32 v[122:123], v[122:123], v[124:125]
	v_exp_f32_e32 v121, v121
	v_mul_f32_e32 v65, v122, v123
	v_mov_b32_e32 v122, v66
	v_mov_b32_e32 v123, v58
	v_pk_mul_f32 v[122:123], v[122:123], v[126:127]
	v_mul_f32_e32 v116, 0xbfb8aa3b, v44
	v_mul_f32_e32 v66, v122, v123
	v_rcp_f32_e32 v122, v117
	v_add_f32_e32 v117, 1.0, v119
	v_mul_f32_e32 v119, 0xbfb8aa3b, v42
	v_rcp_f32_e32 v124, v117
	v_add_f32_e32 v117, 1.0, v121
	v_exp_f32_e32 v119, v119
	v_mul_f32_e32 v121, 0xbfb8aa3b, v43
	v_exp_f32_e32 v121, v121
	v_rcp_f32_e32 v126, v117
	v_add_f32_e32 v117, 1.0, v119
	v_rcp_f32_e32 v128, v117
	v_add_f32_e32 v117, 1.0, v121
	v_rcp_f32_e32 v130, v117
	v_lshlrev_b32_e32 v117, 16, v96
	v_and_b32_e32 v96, 0xffff0000, v96
	v_sub_f32_e32 v96, v96, v54
	v_mul_f32_e32 v119, v96, v103
	v_lshlrev_b32_e32 v96, 16, v97
	v_sub_f32_e32 v96, v96, v54
	v_mul_f32_e32 v121, v96, v103
	v_and_b32_e32 v96, 0xffff0000, v97
	v_sub_f32_e32 v96, v96, v54
	v_mul_f32_e32 v123, v96, v103
	v_mov_b32_e32 v96, v47
	v_mov_b32_e32 v97, v63
	v_pk_mul_f32 v[96:97], v[96:97], v[122:123]
	v_exp_f32_e32 v116, v116
	v_mul_f32_e32 v47, v96, v97
	v_lshlrev_b32_e32 v96, 16, v98
	v_sub_f32_e32 v96, v96, v54
	v_mul_f32_e32 v125, v96, v103
	v_mov_b32_e32 v96, v40
	v_and_b32_e32 v40, 0xffff0000, v98
	v_sub_f32_e32 v40, v40, v54
	v_mov_b32_e32 v97, v68
	v_mul_f32_e32 v127, v40, v103
	v_mov_b32_e32 v40, v41
	v_mov_b32_e32 v41, v69
	v_pk_mul_f32 v[96:97], v[96:97], v[124:125]
	v_pk_mul_f32 v[40:41], v[40:41], v[126:127]
	v_add_f32_e32 v116, 1.0, v116
	v_mul_f32_e32 v96, v96, v97
	v_mul_f32_e32 v97, v40, v41
	v_lshlrev_b32_e32 v40, 16, v99
	v_rcp_f32_e32 v116, v116
	v_sub_f32_e32 v40, v40, v54
	v_mul_f32_e32 v129, v40, v103
	v_mov_b32_e32 v40, v42
	v_mov_b32_e32 v41, v70
	v_sub_f32_e32 v117, v117, v54
	v_pk_mul_f32 v[40:41], v[40:41], v[128:129]
	v_mul_f32_e32 v117, v117, v103
	v_mov_b32_e32 v132, v44
	v_mov_b32_e32 v133, v60
	v_mul_f32_e32 v98, v40, v41
	v_mul_f32_e32 v41, 0xbfb8aa3b, v36
	v_pk_mul_f32 v[116:117], v[132:133], v[116:117]
	v_and_b32_e32 v40, 0xffff0000, v99
	v_exp_f32_e32 v42, v41
	v_mul_f32_e32 v44, v116, v117
	v_mov_b32_e32 v116, v45
	v_mov_b32_e32 v117, v61
	v_sub_f32_e32 v40, v40, v54
	v_pk_mul_f32 v[116:117], v[116:117], v[118:119]
	v_mul_f32_e32 v131, v40, v103
	v_mov_b32_e32 v40, v43
	v_mov_b32_e32 v41, v71
	v_mul_f32_e32 v45, v116, v117
	v_mov_b32_e32 v116, v46
	v_mov_b32_e32 v117, v62
	v_pk_mul_f32 v[40:41], v[40:41], v[130:131]
	v_pk_mul_f32 v[116:117], v[116:117], v[120:121]
	v_mul_f32_e32 v99, v40, v41
	v_add_f32_e32 v40, 1.0, v42
	v_mul_f32_e32 v41, 0xbfb8aa3b, v37
	v_mul_f32_e32 v46, v116, v117
	v_exp_f32_e32 v117, v41
	v_rcp_f32_e32 v116, v40
	global_load_dwordx4 v[40:43], v[114:115], off
	s_nop 0
	global_load_dwordx2 v[112:113], v[112:113], off
	v_mul_f32_e32 v115, 0xbfb8aa3b, v38
	v_add_f32_e32 v114, 1.0, v117
	v_exp_f32_e32 v115, v115
	v_mul_f32_e32 v117, 0xbfb8aa3b, v39
	v_exp_f32_e32 v117, v117
	v_mul_f32_e32 v119, 0xbfb8aa3b, v33
	v_add_f32_e32 v115, 1.0, v115
	v_rcp_f32_e32 v118, v115
	v_add_f32_e32 v115, 1.0, v117
	v_mul_f32_e32 v117, 0xbfb8aa3b, v32
	v_exp_f32_e32 v117, v117
	v_exp_f32_e32 v119, v119
	v_rcp_f32_e32 v120, v115
	v_rcp_f32_e32 v114, v114
	v_add_f32_e32 v115, 1.0, v117
	v_mul_f32_e32 v117, 0xbfb8aa3b, v34
	v_rcp_f32_e32 v122, v115
	v_add_f32_e32 v115, 1.0, v119
	v_exp_f32_e32 v117, v117
	v_mul_f32_e32 v119, 0xbfb8aa3b, v35
	v_exp_f32_e32 v119, v119
	v_rcp_f32_e32 v124, v115
	v_add_f32_e32 v115, 1.0, v117
	v_rcp_f32_e32 v126, v115
	v_add_f32_e32 v115, 1.0, v119
	v_rcp_f32_e32 v128, v115
	v_lshlrev_b32_e32 v115, 16, v92
	v_mov_b32_e32 v130, v36
	v_and_b32_e32 v36, 0xffff0000, v92
	v_sub_f32_e32 v115, v115, v54
	v_sub_f32_e32 v36, v36, v54
	v_mul_f32_e32 v117, v115, v103
	v_mul_f32_e32 v115, v36, v103
	v_mov_b32_e32 v36, v37
	v_mov_b32_e32 v37, v57
	v_mov_b32_e32 v131, v56
	v_pk_mul_f32 v[36:37], v[36:37], v[114:115]
	v_pk_mul_f32 v[116:117], v[130:131], v[116:117]
	v_mul_f32_e32 v131, v36, v37
	v_lshlrev_b32_e32 v36, 16, v93
	v_sub_f32_e32 v36, v36, v54
	v_mul_f32_e32 v119, v36, v103
	v_mov_b32_e32 v36, v38
	v_mov_b32_e32 v37, v58
	v_pk_mul_f32 v[36:37], v[36:37], v[118:119]
	v_mul_f32_e32 v38, 0xbfb8aa3b, v30
	v_mul_f32_e32 v132, v36, v37
	v_and_b32_e32 v36, 0xffff0000, v93
	v_sub_f32_e32 v36, v36, v54
	v_mul_f32_e32 v121, v36, v103
	v_mov_b32_e32 v36, v39
	v_mov_b32_e32 v37, v59
	v_pk_mul_f32 v[36:37], v[36:37], v[120:121]
	v_exp_f32_e32 v39, v38
	v_mul_f32_e32 v120, v36, v37
	v_lshlrev_b32_e32 v36, 16, v94
	v_sub_f32_e32 v36, v36, v54
	v_mul_f32_e32 v123, v36, v103
	v_mov_b32_e32 v36, v32
	v_and_b32_e32 v32, 0xffff0000, v94
	v_sub_f32_e32 v32, v32, v54
	v_mul_f32_e32 v125, v32, v103
	v_mov_b32_e32 v32, v33
	v_mov_b32_e32 v33, v49
	v_mov_b32_e32 v37, v48
	v_pk_mul_f32 v[32:33], v[32:33], v[124:125]
	v_pk_mul_f32 v[36:37], v[36:37], v[122:123]
	v_mul_f32_e32 v122, v32, v33
	v_lshlrev_b32_e32 v32, 16, v95
	v_sub_f32_e32 v32, v32, v54
	v_mul_f32_e32 v127, v32, v103
	v_mov_b32_e32 v32, v34
	v_mov_b32_e32 v33, v50
	v_pk_mul_f32 v[32:33], v[32:33], v[126:127]
	v_mul_f32_e32 v121, v36, v37
	v_mul_f32_e32 v123, v32, v33
	v_and_b32_e32 v32, 0xffff0000, v95
	v_sub_f32_e32 v32, v32, v54
	v_mul_f32_e32 v37, 0xbfb8aa3b, v29
	v_mul_f32_e32 v129, v32, v103
	v_mov_b32_e32 v32, v35
	s_waitcnt vmcnt(0)
; DI float bflo(unsigned w) { return __uint_as_float(w << 16); }
; DI float bfhi(unsigned w) { return __uint_as_float(w & 0xffff0000u); }
; DI void store8(bf16_t* p, f32x4 a, f32x4 b) { u32x4 w = {cvt_pk_bf16(a[0], a[1]), cvt_pk_bf16(a[2], a[3]), cvt_pk_bf16(b[0], b[1]), cvt_pk_bf16(b[2], b[3])}; *(u32x4*)p = w; }
; DI f32x4 silu4(f32x4 v) { f32x4 r; r[0] = silu_f(v[0]); r[1] = silu_f(v[1]); r[2] = silu_f(v[2]); r[3] = silu_f(v[3]); return r; }
;     DI void operator()(const AccT& acc, const pg8::Unit& u, int wr, int wc, int fr, int fq) const {
;     ...
;             for (int m = 0; m < 4; ++m) { const size_t row = (size_t)u.pm * 256 + wr * 64 + fr + ai * 128 + m * 16;
;                 st[m] = *(const float2*)(stats + (row * 4 + head) * 2);
; #pragma unroll
;                 for (int bj = 0; bj < 2; ++bj) ov[m][bj] = *(const u32x4*)(o + row * 2048 + col0 + bj * 128); }
; #pragma unroll
;             for (int m = 0; m < 4; ++m) { const size_t row = (size_t)u.pm * 256 + wr * 64 + fr + ai * 128 + m * 16;
;                 const float mean = st[m].x * (1.f / 512.f), var = fmaxf(st[m].y * (1.f / 512.f) - mean * mean, 0.f), rstd = rsqrtf(var + 1e-5f);
; #pragma unroll
;                 for (int bj = 0; bj < 2; ++bj) { bf16_t* op = o + row * 2048 + col0 + bj * 128; const u32x4 w = ov[m][bj];
;                     const f32x4 s0 = silu4(acc[ai][bj][m][0]), s1 = silu4(acc[ai][bj][m][1]);
;                     f32x4 y0, y1;
;                     y0[0] = (bflo(w[0]) - mean) * rstd * g0[bj][0] * s0[0]; y0[1] = (bfhi(w[0]) - mean) * rstd * g0[bj][1] * s0[1];
;                     y0[2] = (bflo(w[1]) - mean) * rstd * g0[bj][2] * s0[2]; y0[3] = (bfhi(w[1]) - mean) * rstd * g0[bj][3] * s0[3];
;                     y1[0] = (bflo(w[2]) - mean) * rstd * g1[bj][0] * s1[0]; y1[1] = (bfhi(w[2]) - mean) * rstd * g1[bj][1] * s1[1];
;                     y1[2] = (bflo(w[3]) - mean) * rstd * g1[bj][2] * s1[2]; y1[3] = (bfhi(w[3]) - mean) * rstd * g1[bj][3] * s1[3];
;                     store8(op, y0, y1); } } }
	v_pk_mul_f32 v[34:35], v[112:113], s[54:55] op_sel_hi:[1,0]
	v_exp_f32_e32 v37, v37
	v_fma_f32 v33, -v34, v34, v35
	v_mul_f32_e32 v38, 0xbfb8aa3b, v31
	v_max_f32_e32 v33, 0, v33
	v_exp_f32_e32 v93, v38
	v_add_f32_e32 v33, 0x3727c5ac, v33
	v_mul_f32_e32 v35, 0x4b800000, v33
	v_cmp_gt_f32_e32 vcc, s94, v33
	v_add_f32_e32 v37, 1.0, v37
	v_rcp_f32_e32 v38, v37
	v_cndmask_b32_e32 v33, v33, v35, vcc
	v_add_f32_e32 v37, 1.0, v39
	v_mul_f32_e32 v39, 0xbfb8aa3b, v24
	v_rsq_f32_e32 v35, v33
	v_rcp_f32_e32 v92, v37
	v_add_f32_e32 v37, 1.0, v93
	v_exp_f32_e32 v39, v39
	v_mul_f32_e32 v93, 0xbfb8aa3b, v25
	v_exp_f32_e32 v93, v93
	v_mov_b32_e32 v33, v51
	v_pk_mul_f32 v[32:33], v[32:33], v[128:129]
	v_mul_f32_e32 v36, 0xbfb8aa3b, v28
	v_mul_f32_e32 v54, v32, v33
	v_mul_f32_e32 v32, 0x45800000, v35
	v_rcp_f32_e32 v94, v37
	v_add_f32_e32 v37, 1.0, v39
	v_mul_f32_e32 v39, 0xbfb8aa3b, v26
	v_cndmask_b32_e32 v35, v35, v32, vcc
	v_lshl_add_u64 v[32:33], s[96:97], 0, v[110:111]
	v_exp_f32_e32 v36, v36
	v_rcp_f32_e32 v110, v37
	v_add_f32_e32 v37, 1.0, v93
	v_exp_f32_e32 v39, v39
	v_mul_f32_e32 v93, 0xbfb8aa3b, v27
	v_exp_f32_e32 v93, v93
	v_add_f32_e32 v36, 1.0, v36
	v_rcp_f32_e32 v112, v37
	v_add_f32_e32 v37, 1.0, v39
	v_rcp_f32_e32 v36, v36
	v_rcp_f32_e32 v114, v37
	v_add_f32_e32 v37, 1.0, v93
	v_mov_b32_e32 v118, v28
	v_and_b32_e32 v28, 0xffff0000, v40
	v_mul_f32_e32 v130, v116, v117
	v_rcp_f32_e32 v116, v37
	v_lshlrev_b32_e32 v37, 16, v40
	v_sub_f32_e32 v28, v28, v34
	v_sub_f32_e32 v37, v37, v34
	v_mul_f32_e32 v39, v28, v35
	v_mov_b32_e32 v28, v29
	v_mov_b32_e32 v29, v61
	v_mul_f32_e32 v37, v37, v35
	v_mov_b32_e32 v119, v60
	v_pk_mul_f32 v[28:29], v[28:29], v[38:39]
	v_pk_mul_f32 v[36:37], v[118:119], v[36:37]
	v_mul_f32_e32 v118, v28, v29
	v_lshlrev_b32_e32 v28, 16, v41
	v_sub_f32_e32 v28, v28, v34
	v_mul_f32_e32 v93, v28, v35
	v_mov_b32_e32 v28, v30
	v_mov_b32_e32 v29, v62
	v_pk_mul_f32 v[28:29], v[28:29], v[92:93]
	global_load_dwordx2 v[92:93], v[108:109], off
	v_mul_f32_e32 v119, v28, v29
	v_and_b32_e32 v28, 0xffff0000, v41
	v_sub_f32_e32 v28, v28, v34
	v_mul_f32_e32 v95, v28, v35
	v_mov_b32_e32 v28, v31
	v_mov_b32_e32 v29, v63
	v_pk_mul_f32 v[28:29], v[28:29], v[94:95]
	v_mul_f32_e32 v103, v36, v37
	v_mul_f32_e32 v124, v28, v29
	v_lshlrev_b32_e32 v28, 16, v42
	v_sub_f32_e32 v28, v28, v34
	v_mul_f32_e32 v111, v28, v35
	v_mov_b32_e32 v28, v24
	v_and_b32_e32 v24, 0xffff0000, v42
	v_sub_f32_e32 v24, v24, v34
	v_mul_f32_e32 v113, v24, v35
	v_mov_b32_e32 v24, v25
	v_mov_b32_e32 v25, v69
	v_mov_b32_e32 v29, v68
	v_pk_mul_f32 v[24:25], v[24:25], v[112:113]
	v_pk_mul_f32 v[28:29], v[28:29], v[110:111]
	v_mul_f32_e32 v111, v24, v25
	v_lshlrev_b32_e32 v24, 16, v43
	v_sub_f32_e32 v24, v24, v34
	v_mul_f32_e32 v115, v24, v35
	v_mov_b32_e32 v24, v26
	v_mov_b32_e32 v25, v70
	v_pk_mul_f32 v[24:25], v[24:25], v[114:115]
	v_mul_f32_e32 v26, 0xbfb8aa3b, v20
	v_mul_f32_e32 v112, v24, v25
	v_and_b32_e32 v24, 0xffff0000, v43
	v_sub_f32_e32 v24, v24, v34
	v_mul_f32_e32 v117, v24, v35
	v_mov_b32_e32 v24, v27
	v_exp_f32_e32 v26, v26
	v_mul_f32_e32 v27, 0xbfb8aa3b, v21
	v_exp_f32_e32 v27, v27
	v_mov_b32_e32 v25, v71
	v_pk_mul_f32 v[24:25], v[24:25], v[116:117]
	v_mul_f32_e32 v110, v28, v29
	v_mul_f32_e32 v113, v24, v25
	v_add_f32_e32 v24, 1.0, v26
	v_mul_f32_e32 v26, 0xbfb8aa3b, v22
	v_add_f32_e32 v25, 1.0, v27
	v_exp_f32_e32 v27, v26
	v_mul_f32_e32 v26, 0xbfb8aa3b, v23
	v_exp_f32_e32 v29, v26
	v_rcp_f32_e32 v26, v25
	v_add_f32_e32 v25, 1.0, v27
	v_mul_f32_e32 v27, 0xbfb8aa3b, v16
	v_rcp_f32_e32 v28, v25
	v_add_f32_e32 v25, 1.0, v29
	v_exp_f32_e32 v27, v27
	v_mul_f32_e32 v29, 0xbfb8aa3b, v17
	v_exp_f32_e32 v29, v29
	v_rcp_f32_e32 v30, v25
	v_add_f32_e32 v25, 1.0, v27
	v_mul_f32_e32 v27, 0xbfb8aa3b, v18
	v_rcp_f32_e32 v36, v25
	v_add_f32_e32 v25, 1.0, v29
	v_exp_f32_e32 v27, v27
	v_mul_f32_e32 v29, 0xbfb8aa3b, v19
	v_exp_f32_e32 v29, v29
	v_rcp_f32_e32 v38, v25
	v_add_f32_e32 v25, 1.0, v27
	v_rcp_f32_e32 v24, v24
	v_rcp_f32_e32 v40, v25
	v_add_f32_e32 v25, 1.0, v29
	v_rcp_f32_e32 v42, v25
	v_lshlrev_b32_e32 v25, 16, v88
	v_mov_b32_e32 v94, v20
	v_and_b32_e32 v20, 0xffff0000, v88
	v_sub_f32_e32 v25, v25, v34
	v_sub_f32_e32 v20, v20, v34
	v_mul_f32_e32 v25, v25, v35
	v_mov_b32_e32 v95, v56
	v_mul_f32_e32 v27, v20, v35
	v_mov_b32_e32 v20, v21
	v_mov_b32_e32 v21, v57
	v_pk_mul_f32 v[24:25], v[94:95], v[24:25]
	v_pk_mul_f32 v[20:21], v[20:21], v[26:27]
	v_mul_f32_e32 v24, v24, v25
	v_mul_f32_e32 v25, v20, v21
	v_lshlrev_b32_e32 v20, 16, v89
	v_sub_f32_e32 v20, v20, v34
	v_mul_f32_e32 v29, v20, v35
	v_mov_b32_e32 v20, v22
	v_mov_b32_e32 v21, v58
	v_pk_mul_f32 v[20:21], v[20:21], v[28:29]
	v_lshl_add_u64 v[52:53], v[52:53], 0, v[184:185]
	v_mul_f32_e32 v22, v20, v21
	v_and_b32_e32 v20, 0xffff0000, v89
	v_sub_f32_e32 v20, v20, v34
	v_mul_f32_e32 v31, v20, v35
	v_mov_b32_e32 v20, v23
	v_mov_b32_e32 v21, v59
	v_pk_mul_f32 v[20:21], v[20:21], v[30:31]
	v_lshl_add_u64 v[32:33], v[32:33], 0, v[184:185]
	v_mul_f32_e32 v23, v20, v21
	v_lshlrev_b32_e32 v20, 16, v90
	v_sub_f32_e32 v20, v20, v34
	v_mul_f32_e32 v37, v20, v35
	v_mov_b32_e32 v20, v16
	v_and_b32_e32 v16, 0xffff0000, v90
	v_sub_f32_e32 v16, v16, v34
	v_mov_b32_e32 v21, v48
	v_mul_f32_e32 v39, v16, v35
	v_mov_b32_e32 v16, v17
	v_mov_b32_e32 v17, v49
	v_pk_mul_f32 v[20:21], v[20:21], v[36:37]
	v_pk_mul_f32 v[16:17], v[16:17], v[38:39]
	v_mul_f32_e32 v20, v20, v21
	v_mul_f32_e32 v21, v16, v17
	v_lshlrev_b32_e32 v16, 16, v91
	v_sub_f32_e32 v16, v16, v34
	v_mul_f32_e32 v41, v16, v35
	v_mov_b32_e32 v16, v18
	v_mov_b32_e32 v17, v50
	v_pk_mul_f32 v[16:17], v[16:17], v[40:41]
	v_mov_b32_e32 v36, v12
	v_mul_f32_e32 v26, v16, v17
	v_and_b32_e32 v16, 0xffff0000, v91
	v_sub_f32_e32 v16, v16, v34
	v_mul_f32_e32 v43, v16, v35
	v_mov_b32_e32 v16, v19
	v_mov_b32_e32 v17, v51
	v_pk_mul_f32 v[16:17], v[16:17], v[42:43]
	v_mov_b32_e32 v37, v60
	v_mul_f32_e32 v27, v16, v17
	v_cvt_pk_bf16_f32 v16, v76, v77
	v_cvt_pk_bf16_f32 v17, v78, v79
	v_cvt_pk_bf16_f32 v18, v72, v73
	v_cvt_pk_bf16_f32 v19, v74, v75
	global_store_dwordx4 v[106:107], v[16:19], off
	v_mov_b32_e32 v60, v13
	s_nop 0
	v_cvt_pk_bf16_f32 v16, v64, v65
	v_cvt_pk_bf16_f32 v17, v66, v67
	v_cvt_pk_bf16_f32 v18, v100, v101
	v_cvt_pk_bf16_f32 v19, v102, v55
	global_store_dwordx4 v[106:107], v[16:19], off offset:256
	s_nop 1
	v_cvt_pk_bf16_f32 v16, v44, v45
	v_cvt_pk_bf16_f32 v17, v46, v47
	v_cvt_pk_bf16_f32 v18, v96, v97
	v_cvt_pk_bf16_f32 v19, v98, v99
	global_store_dwordx4 v[52:53], v[16:19], off
	s_nop 1
	v_cvt_pk_bf16_f32 v16, v130, v131
	v_cvt_pk_bf16_f32 v17, v132, v120
	v_cvt_pk_bf16_f32 v18, v121, v122
	v_cvt_pk_bf16_f32 v19, v123, v54
	global_store_dwordx4 v[52:53], v[16:19], off offset:256
	s_nop 1
	v_cvt_pk_bf16_f32 v16, v103, v118
	v_cvt_pk_bf16_f32 v17, v119, v124
	v_cvt_pk_bf16_f32 v18, v110, v111
	v_cvt_pk_bf16_f32 v19, v112, v113
	global_store_dwordx4 v[32:33], v[16:19], off
	s_waitcnt vmcnt(0)
; DI float bflo(unsigned w) { return __uint_as_float(w << 16); }
; DI float bfhi(unsigned w) { return __uint_as_float(w & 0xffff0000u); }
; #define PG8_BAR __builtin_amdgcn_s_barrier()
; template <class Epi, class Sched>
; __device__ __forceinline__ void gemm_phase(PG8_LAS unsigned char* lds, const Gemm g, const Sched& S, const Epi& E) {
;     ...
;         E(acc, cur, wr, wc, fr, fq); S.done(cur);
;         if (!has_next) break;
; #pragma unroll
;         for (int a = 0; a < 2; ++a)
; #pragma unroll
;             for (int b = 0; b < 2; ++b)
; #pragma unroll
;                 for (int m = 0; m < 4; ++m)
; #pragma unroll
;                     for (int n = 0; n < 2; ++n) acc[a][b][m][n] = (f32x4){0.f, 0.f, 0.f, 0.f};
;         cur = nxt; cA = nA; cB = nB; ++ui;
;     }
;     PG8_WAIT_V(0);
;     if (wr == 0) PG8_BAR;
;     DI void operator()(const AccT& acc, const pg8::Unit& u, int wr, int wc, int fr, int fq) const {
;     ...
;             for (int m = 0; m < 4; ++m) { const size_t row = (size_t)u.pm * 256 + wr * 64 + fr + ai * 128 + m * 16;
;                 st[m] = *(const float2*)(stats + (row * 4 + head) * 2);
; #pragma unroll
;                 for (int bj = 0; bj < 2; ++bj) ov[m][bj] = *(const u32x4*)(o + row * 2048 + col0 + bj * 128); }
; #pragma unroll
;             for (int m = 0; m < 4; ++m) { const size_t row = (size_t)u.pm * 256 + wr * 64 + fr + ai * 128 + m * 16;
;                 const float mean = st[m].x * (1.f / 512.f), var = fmaxf(st[m].y * (1.f / 512.f) - mean * mean, 0.f), rstd = rsqrtf(var + 1e-5f);
; #pragma unroll
;                 for (int bj = 0; bj < 2; ++bj) { bf16_t* op = o + row * 2048 + col0 + bj * 128; const u32x4 w = ov[m][bj];
;                     const f32x4 s0 = silu4(acc[ai][bj][m][0]), s1 = silu4(acc[ai][bj][m][1]);
;                     f32x4 y0, y1;
;                     y0[0] = (bflo(w[0]) - mean) * rstd * g0[bj][0] * s0[0]; y0[1] = (bfhi(w[0]) - mean) * rstd * g0[bj][1] * s0[1];
;                     y0[2] = (bflo(w[1]) - mean) * rstd * g0[bj][2] * s0[2]; y0[3] = (bfhi(w[1]) - mean) * rstd * g0[bj][3] * s0[3];
;                     y1[0] = (bflo(w[2]) - mean) * rstd * g1[bj][0] * s1[0]; y1[1] = (bfhi(w[2]) - mean) * rstd * g1[bj][1] * s1[1];
;                     y1[2] = (bflo(w[3]) - mean) * rstd * g1[bj][2] * s1[2]; y1[3] = (bfhi(w[3]) - mean) * rstd * g1[bj][3] * s1[3];
;                     store8(op, y0, y1); } } }
	s_nop 0
	v_pk_mul_f32 v[16:17], v[92:93], s[54:55] op_sel_hi:[1,0]
	v_cvt_pk_bf16_f32 v18, v24, v25
	v_cvt_pk_bf16_f32 v19, v22, v23
	v_cvt_pk_bf16_f32 v20, v20, v21
	v_cvt_pk_bf16_f32 v21, v26, v27
	global_store_dwordx4 v[32:33], v[18:21], off offset:256
	v_fma_f32 v17, -v16, v16, v17
	v_max_f32_e32 v17, 0, v17
	v_add_f32_e32 v17, 0x3727c5ac, v17
	v_mul_f32_e32 v22, 0x4b800000, v17
	v_cmp_gt_f32_e32 vcc, s94, v17
	v_mul_f32_e32 v21, 0xbfb8aa3b, v13
	v_exp_f32_e32 v21, v21
	v_cndmask_b32_e32 v17, v17, v22, vcc
	v_mul_f32_e32 v22, 0xbfb8aa3b, v14
	v_exp_f32_e32 v23, v22
	v_mul_f32_e32 v22, 0xbfb8aa3b, v15
	v_exp_f32_e32 v25, v22
	v_add_f32_e32 v21, 1.0, v21
	v_rcp_f32_e32 v22, v21
	v_add_f32_e32 v21, 1.0, v23
	v_mul_f32_e32 v23, 0xbfb8aa3b, v8
	v_rcp_f32_e32 v24, v21
	v_add_f32_e32 v21, 1.0, v25
	v_exp_f32_e32 v23, v23
	v_mul_f32_e32 v25, 0xbfb8aa3b, v9
	v_exp_f32_e32 v25, v25
	v_mul_f32_e32 v20, 0xbfb8aa3b, v12
	v_rcp_f32_e32 v26, v21
	v_add_f32_e32 v21, 1.0, v23
	v_mul_f32_e32 v23, 0xbfb8aa3b, v10
	v_exp_f32_e32 v20, v20
	v_rcp_f32_e32 v28, v21
	v_add_f32_e32 v21, 1.0, v25
	v_exp_f32_e32 v23, v23
	v_mul_f32_e32 v25, 0xbfb8aa3b, v11
	v_exp_f32_e32 v25, v25
	v_rsq_f32_e32 v17, v17
	v_add_f32_e32 v20, 1.0, v20
	v_rcp_f32_e32 v30, v21
	v_add_f32_e32 v21, 1.0, v23
	v_rcp_f32_e32 v20, v20
	v_rcp_f32_e32 v32, v21
	v_add_f32_e32 v21, 1.0, v25
	v_mul_f32_e32 v18, 0x45800000, v17
	v_rcp_f32_e32 v34, v21
	v_lshlrev_b32_e32 v21, 16, v84
	v_and_b32_e32 v12, 0xffff0000, v84
	v_cndmask_b32_e32 v17, v17, v18, vcc
	v_sub_f32_e32 v21, v21, v16
	v_sub_f32_e32 v12, v12, v16
	v_mul_f32_e32 v21, v21, v17
	v_mul_f32_e32 v23, v12, v17
	v_pk_mul_f32 v[20:21], v[36:37], v[20:21]
	v_pk_mul_f32 v[12:13], v[60:61], v[22:23]
	v_mul_f32_e32 v20, v20, v21
	v_mul_f32_e32 v21, v12, v13
	v_lshlrev_b32_e32 v12, 16, v85
	v_sub_f32_e32 v12, v12, v16
	v_mul_f32_e32 v25, v12, v17
	v_mov_b32_e32 v12, v14
	v_mov_b32_e32 v13, v62
	v_pk_mul_f32 v[12:13], v[12:13], v[24:25]
	v_mov_b32_e32 v62, v15
	v_mul_f32_e32 v14, v12, v13
	v_and_b32_e32 v12, 0xffff0000, v85
	v_sub_f32_e32 v12, v12, v16
	v_mul_f32_e32 v27, v12, v17
	v_pk_mul_f32 v[12:13], v[62:63], v[26:27]
	v_lshl_add_u64 v[18:19], s[96:97], 0, v[104:105]
	v_mul_f32_e32 v15, v12, v13
	v_lshlrev_b32_e32 v12, 16, v86
	v_sub_f32_e32 v12, v12, v16
	v_mul_f32_e32 v29, v12, v17
	v_mov_b32_e32 v12, v8
	v_and_b32_e32 v8, 0xffff0000, v86
	v_sub_f32_e32 v8, v8, v16
	v_mov_b32_e32 v13, v68
	v_mul_f32_e32 v31, v8, v17
	v_mov_b32_e32 v68, v9
	v_pk_mul_f32 v[12:13], v[12:13], v[28:29]
	v_pk_mul_f32 v[8:9], v[68:69], v[30:31]
	v_mul_f32_e32 v12, v12, v13
	v_mul_f32_e32 v13, v8, v9
	v_lshlrev_b32_e32 v8, 16, v87
	v_sub_f32_e32 v8, v8, v16
	v_mul_f32_e32 v33, v8, v17
	v_mov_b32_e32 v8, v10
	v_mov_b32_e32 v9, v70
	v_pk_mul_f32 v[8:9], v[8:9], v[32:33]
	v_mov_b32_e32 v70, v11
	v_mul_f32_e32 v22, v8, v9
	v_and_b32_e32 v8, 0xffff0000, v87
	v_sub_f32_e32 v8, v8, v16
	v_mul_f32_e32 v35, v8, v17
	v_pk_mul_f32 v[8:9], v[70:71], v[34:35]
	v_lshl_add_u64 v[18:19], v[18:19], 0, v[184:185]
	v_mul_f32_e32 v11, v8, v9
	v_cvt_pk_bf16_f32 v8, v20, v21
	v_cvt_pk_bf16_f32 v9, v14, v15
	v_cvt_pk_bf16_f32 v10, v12, v13
	v_mul_f32_e32 v13, 0xbfb8aa3b, v5
	v_exp_f32_e32 v13, v13
	v_cvt_pk_bf16_f32 v11, v22, v11
	global_store_dwordx4 v[18:19], v[8:11], off
	v_mul_f32_e32 v12, 0xbfb8aa3b, v4
	v_exp_f32_e32 v12, v12
	v_mul_f32_e32 v10, 0xbfb8aa3b, v6
	v_exp_f32_e32 v11, v10
	v_mul_f32_e32 v10, 0xbfb8aa3b, v7
	v_add_f32_e32 v9, 1.0, v13
	v_exp_f32_e32 v13, v10
	v_rcp_f32_e32 v10, v9
	v_add_f32_e32 v9, 1.0, v11
	v_mul_f32_e32 v11, 0xbfb8aa3b, v0
	v_add_f32_e32 v8, 1.0, v12
	v_rcp_f32_e32 v12, v9
	v_add_f32_e32 v9, 1.0, v13
	v_exp_f32_e32 v11, v11
	v_mul_f32_e32 v13, 0xbfb8aa3b, v1
	v_exp_f32_e32 v13, v13
	v_rcp_f32_e32 v14, v9
	v_add_f32_e32 v9, 1.0, v11
	v_mul_f32_e32 v11, 0xbfb8aa3b, v2
	v_rcp_f32_e32 v20, v9
	v_add_f32_e32 v9, 1.0, v13
	v_exp_f32_e32 v11, v11
	v_mul_f32_e32 v13, 0xbfb8aa3b, v3
	v_exp_f32_e32 v13, v13
	v_rcp_f32_e32 v22, v9
	v_add_f32_e32 v9, 1.0, v11
	v_rcp_f32_e32 v8, v8
	v_rcp_f32_e32 v24, v9
	v_add_f32_e32 v9, 1.0, v13
	v_rcp_f32_e32 v26, v9
	v_lshlrev_b32_e32 v9, 16, v80
	v_mov_b32_e32 v28, v4
	v_and_b32_e32 v4, 0xffff0000, v80
	v_sub_f32_e32 v9, v9, v16
	v_sub_f32_e32 v4, v4, v16
	v_mul_f32_e32 v9, v9, v17
	v_mov_b32_e32 v29, v56
	v_mul_f32_e32 v11, v4, v17
	v_mov_b32_e32 v56, v5
	v_pk_mul_f32 v[8:9], v[28:29], v[8:9]
	v_pk_mul_f32 v[4:5], v[56:57], v[10:11]
	v_mul_f32_e32 v8, v8, v9
	v_mul_f32_e32 v9, v4, v5
	v_lshlrev_b32_e32 v4, 16, v81
	v_sub_f32_e32 v4, v4, v16
	v_mul_f32_e32 v13, v4, v17
	v_mov_b32_e32 v4, v6
	v_mov_b32_e32 v5, v58
	v_pk_mul_f32 v[4:5], v[4:5], v[12:13]
	v_mov_b32_e32 v58, v7
	v_mul_f32_e32 v6, v4, v5
	v_and_b32_e32 v4, 0xffff0000, v81
	v_sub_f32_e32 v4, v4, v16
	v_mul_f32_e32 v15, v4, v17
	v_pk_mul_f32 v[4:5], v[58:59], v[14:15]
	s_and_b64 vcc, exec, s[4:5]
	v_mul_f32_e32 v7, v4, v5
	v_lshlrev_b32_e32 v4, 16, v82
	v_sub_f32_e32 v4, v4, v16
	v_mul_f32_e32 v21, v4, v17
	v_mov_b32_e32 v4, v0
	v_and_b32_e32 v0, 0xffff0000, v82
	v_sub_f32_e32 v0, v0, v16
	v_mov_b32_e32 v5, v48
	v_mul_f32_e32 v23, v0, v17
	v_mov_b32_e32 v48, v1
	v_pk_mul_f32 v[4:5], v[4:5], v[20:21]
	v_pk_mul_f32 v[0:1], v[48:49], v[22:23]
	v_mul_f32_e32 v4, v4, v5
	v_mul_f32_e32 v5, v0, v1
	v_lshlrev_b32_e32 v0, 16, v83
	v_sub_f32_e32 v0, v0, v16
	v_mul_f32_e32 v25, v0, v17
	v_mov_b32_e32 v0, v2
	v_mov_b32_e32 v1, v50
	v_pk_mul_f32 v[0:1], v[0:1], v[24:25]
	v_mov_b32_e32 v50, v3
	v_mul_f32_e32 v10, v0, v1
	v_and_b32_e32 v0, 0xffff0000, v83
	v_sub_f32_e32 v0, v0, v16
	v_mul_f32_e32 v27, v0, v17
	v_pk_mul_f32 v[0:1], v[50:51], v[26:27]
	s_nop 0
	v_mul_f32_e32 v3, v0, v1
	v_cvt_pk_bf16_f32 v0, v8, v9
	v_cvt_pk_bf16_f32 v1, v6, v7
	v_cvt_pk_bf16_f32 v2, v4, v5
	v_cvt_pk_bf16_f32 v3, v10, v3
	global_store_dwordx4 v[18:19], v[0:3], off offset:256
	s_cbranch_vccz .LBB0_513
	s_waitcnt vmcnt(0)
	v_readlane_b32 s54, v255, 42
	v_readlane_b32 s52, v255, 44
	v_readlane_b32 s64, v255, 53
	v_readlane_b32 s66, v255, 55
	s_cmpk_gt_u32 s47, 0xff
	v_readlane_b32 s55, v255, 43
	v_readlane_b32 s53, v255, 45
	v_readlane_b32 s56, v255, 46
	v_readlane_b32 s57, v255, 47
	v_readlane_b32 s58, v255, 48
	v_readlane_b32 s59, v255, 49
	v_readlane_b32 s65, v255, 54
	v_readlane_b32 s67, v255, 56
	v_readlane_b32 s63, v255, 57
	s_cbranch_scc1 .LBB0_520
	s_barrier

; #define PG8_STAGE(bufoff, gbase, voff) do { _Pragma("unroll") for (int _i = 0; _i < 2; ++_i) \
;         __builtin_amdgcn_global_load_lds((const unsigned*)((const char*)(gbase) + (voff)[_i]), (PG8_LAS unsigned*)(lds + (bufoff) + ldsw + _i * 8192), 16, 0, 0); } while (0)
; #define PG8_LDA(dst, b, h) do { _Pragma("unroll") for (int m = 0; m < 4; ++m) _Pragma("unroll") for (int k = 0; k < 2; ++k) dst[m][k] = *(const PG8_LAS bf16x8*)(lds + PG8_SA(b, h) + aoff + m * 2048 + k * 1024); } while (0)
; #define PG8_LDB(dst, b, h) do { _Pragma("unroll") for (int n = 0; n < 2; ++n) _Pragma("unroll") for (int k = 0; k < 2; ++k) dst[n][k] = *(const PG8_LAS bf16x8*)(lds + PG8_SB(b, h) + boff + n * 2048 + k * 1024); } while (0)
; #define PG8_MMA(ai, bj, At, Bt) do { __builtin_amdgcn_s_setprio(1); _Pragma("unroll") for (int m = 0; m < 4; ++m) _Pragma("unroll") for (int n = 0; n < 2; ++n) _Pragma("unroll") for (int k = 0; k < 2; ++k) \
;         acc[ai][bj][m][n] = __builtin_amdgcn_mfma_f32_16x16x32_bf16(Bt[n][k], At[m][k], acc[ai][bj][m][n], 0, 0, 0); __builtin_amdgcn_s_setprio(0); } while (0)
; #define PG8_WAIT_L(n) asm volatile("s_waitcnt lgkmcnt(" #n ")" ::: "memory")
; #define PG8_BAR __builtin_amdgcn_s_barrier()
; #define PG8_SCHED __builtin_amdgcn_sched_barrier(0)
; template <class Epi, class Sched>
; __device__ __forceinline__ void gemm_phase(PG8_LAS unsigned char* lds, const Gemm g, const Sched& S, const Epi& E) {
;     ...
;             PG8_LDB(B0, 0, 0); PG8_SCHED; PG8_LDA(At, 0, 0); PG8_STAGE(PG8_SA(1, 1), a1 + hstep, voffA);
;             PG8_WAIT_L(8); PG8_BAR; PG8_WAIT_L(0); PG8_MMA(0, 0, At, B0); PG8_BAR; PG8_SCHED;
;             PG8_LDB(B1, 0, 1); PG8_STAGE(PG8_SB(0, 0), b2, voffB);
;             PG8_BAR; PG8_WAIT_L(0); PG8_MMA(0, 1, At, B1); PG8_BAR;
;             PG8_LDA(At, 0, 1); PG8_STAGE(PG8_SA(0, 0), a2, voffA);
;             PG8_BAR; PG8_WAIT_L(0); PG8_MMA(1, 0, At, B0); PG8_BAR; PG8_SCHED;
.LBB0_580:
	s_add_u32 s20, s18, 0xfff80080
	s_addc_u32 s21, s19, -1
	s_add_i32 s69, 0, 0x10000
	v_add_u32_e32 v142, s69, v144
	ds_read_b128 v[146:149], v142
	ds_read_b128 v[150:153], v142 offset:1024
	ds_read_b128 v[154:157], v142 offset:2048
	ds_read_b128 v[158:161], v142 offset:3072
	s_cmp_eq_u32 s88, 28
	s_cselect_b32 s71, s9, s21
	s_cselect_b32 s70, s11, s20
	s_cselect_b32 s21, s7, s83
	s_cselect_b32 s20, s81, s82
	v_lshl_add_u64 v[142:143], s[18:19], 0, v[138:139]
	s_add_i32 m0, s13, 0xc000
	ds_read_b128 v[162:165], v145
	ds_read_b128 v[166:169], v145 offset:1024
	ds_read_b128 v[170:173], v145 offset:2048
	ds_read_b128 v[174:177], v145 offset:3072
	ds_read_b128 v[184:187], v145 offset:4096
	ds_read_b128 v[188:191], v145 offset:5120
	ds_read_b128 v[192:195], v145 offset:6144
	ds_read_b128 v[196:199], v145 offset:7168
	global_load_lds_dwordx4 v[142:143], off
	v_lshl_add_u64 v[142:143], s[18:19], 0, v[140:141]
	s_add_i32 m0, s13, 0xe000
	s_nop 0
	global_load_lds_dwordx4 v[142:143], off
	s_waitcnt lgkmcnt(8)
	s_barrier
	s_waitcnt lgkmcnt(0)
	s_waitcnt lgkmcnt(0)
	v_mfma_f32_16x16x32_bf16 v[124:127], v[146:149], v[162:165], v[124:127]
	v_mfma_f32_16x16x32_bf16 v[120:123], v[154:157], v[162:165], v[120:123]
	v_mfma_f32_16x16x32_bf16 v[116:119], v[146:149], v[170:173], v[116:119]
	v_mfma_f32_16x16x32_bf16 v[108:111], v[154:157], v[170:173], v[108:111]
	v_mfma_f32_16x16x32_bf16 v[100:103], v[146:149], v[184:187], v[100:103]
	v_mfma_f32_16x16x32_bf16 v[92:95], v[154:157], v[184:187], v[92:95]
	v_mfma_f32_16x16x32_bf16 v[84:87], v[146:149], v[192:195], v[84:87]
	v_mfma_f32_16x16x32_bf16 v[76:79], v[154:157], v[192:195], v[76:79]
	v_mfma_f32_16x16x32_bf16 v[124:127], v[150:153], v[166:169], v[124:127]
	v_mfma_f32_16x16x32_bf16 v[120:123], v[158:161], v[166:169], v[120:123]
	v_mfma_f32_16x16x32_bf16 v[116:119], v[150:153], v[174:177], v[116:119]
	v_mfma_f32_16x16x32_bf16 v[108:111], v[158:161], v[174:177], v[108:111]
	v_mfma_f32_16x16x32_bf16 v[100:103], v[150:153], v[188:191], v[100:103]
	v_mfma_f32_16x16x32_bf16 v[92:95], v[158:161], v[188:191], v[92:95]
	v_mfma_f32_16x16x32_bf16 v[84:87], v[150:153], v[196:199], v[84:87]
	v_mfma_f32_16x16x32_bf16 v[76:79], v[158:161], v[196:199], v[76:79]
	s_barrier
	s_add_i32 s89, 0, 0x14000
	v_add_u32_e32 v142, s89, v144
	s_add_i32 s69, s69, s72
	ds_read_b128 v[200:203], v142
	ds_read_b128 v[204:207], v142 offset:1024
	ds_read_b128 v[208:211], v142 offset:2048
	ds_read_b128 v[212:215], v142 offset:3072
	v_lshl_add_u64 v[142:143], s[20:21], 0, v[180:181]
	s_mov_b32 m0, s69
	v_lshl_add_u64 v[178:179], s[20:21], 0, v[128:129]
	global_load_lds_dwordx4 v[142:143], off
	s_add_i32 m0, s69, 0x2000
	s_nop 0
	global_load_lds_dwordx4 v[178:179], off
	s_barrier
	s_waitcnt lgkmcnt(0)
	s_waitcnt lgkmcnt(0)
	v_mfma_f32_16x16x32_bf16 v[112:115], v[200:203], v[162:165], v[112:115]
	v_mfma_f32_16x16x32_bf16 v[104:107], v[208:211], v[162:165], v[104:107]
	v_mfma_f32_16x16x32_bf16 v[96:99], v[200:203], v[170:173], v[96:99]
	v_mfma_f32_16x16x32_bf16 v[88:91], v[208:211], v[170:173], v[88:91]
	v_mfma_f32_16x16x32_bf16 v[80:83], v[200:203], v[184:187], v[80:83]
	v_mfma_f32_16x16x32_bf16 v[72:75], v[208:211], v[184:187], v[72:75]
	v_mfma_f32_16x16x32_bf16 v[68:71], v[200:203], v[192:195], v[68:71]
	v_mfma_f32_16x16x32_bf16 v[64:67], v[208:211], v[192:195], v[64:67]
	v_mfma_f32_16x16x32_bf16 v[112:115], v[204:207], v[166:169], v[112:115]
	v_mfma_f32_16x16x32_bf16 v[104:107], v[212:215], v[166:169], v[104:107]
	v_mfma_f32_16x16x32_bf16 v[96:99], v[204:207], v[174:177], v[96:99]
	v_mfma_f32_16x16x32_bf16 v[88:91], v[212:215], v[174:177], v[88:91]
	v_mfma_f32_16x16x32_bf16 v[80:83], v[204:207], v[188:191], v[80:83]
	v_mfma_f32_16x16x32_bf16 v[72:75], v[212:215], v[188:191], v[72:75]
	v_mfma_f32_16x16x32_bf16 v[68:71], v[204:207], v[196:199], v[68:71]
	v_mfma_f32_16x16x32_bf16 v[64:67], v[212:215], v[196:199], v[64:67]
	s_mov_b32 m0, s13
	v_lshl_add_u64 v[216:217], s[70:71], 0, v[132:133]
	s_barrier
	ds_read_b128 v[162:165], v145 offset:16384
	ds_read_b128 v[166:169], v145 offset:17408
	ds_read_b128 v[170:173], v145 offset:18432
	ds_read_b128 v[174:177], v145 offset:19456
	ds_read_b128 v[184:187], v145 offset:20480
	ds_read_b128 v[188:191], v145 offset:21504
	ds_read_b128 v[192:195], v145 offset:22528
	ds_read_b128 v[196:199], v145 offset:23552
	global_load_lds_dwordx4 v[216:217], off
	v_lshl_add_u64 v[218:219], s[70:71], 0, v[130:131]
	s_mov_b32 m0, s75
	s_nop 0
	global_load_lds_dwordx4 v[218:219], off
	s_barrier
	s_waitcnt lgkmcnt(0)
	s_waitcnt lgkmcnt(0)
	v_mfma_f32_16x16x32_bf16 v[60:63], v[146:149], v[162:165], v[60:63]
	v_mfma_f32_16x16x32_bf16 v[56:59], v[154:157], v[162:165], v[56:59]
	v_mfma_f32_16x16x32_bf16 v[52:55], v[146:149], v[170:173], v[52:55]
	v_mfma_f32_16x16x32_bf16 v[44:47], v[154:157], v[170:173], v[44:47]
	v_mfma_f32_16x16x32_bf16 v[36:39], v[146:149], v[184:187], v[36:39]
	v_mfma_f32_16x16x32_bf16 v[28:31], v[154:157], v[184:187], v[28:31]
	v_mfma_f32_16x16x32_bf16 v[20:23], v[146:149], v[192:195], v[20:23]
	v_mfma_f32_16x16x32_bf16 v[12:15], v[154:157], v[192:195], v[12:15]
	v_mfma_f32_16x16x32_bf16 v[60:63], v[150:153], v[166:169], v[60:63]
	v_mfma_f32_16x16x32_bf16 v[56:59], v[158:161], v[166:169], v[56:59]
	v_mfma_f32_16x16x32_bf16 v[52:55], v[150:153], v[174:177], v[52:55]
	v_mfma_f32_16x16x32_bf16 v[44:47], v[158:161], v[174:177], v[44:47]
	v_mfma_f32_16x16x32_bf16 v[36:39], v[150:153], v[188:191], v[36:39]
	v_mfma_f32_16x16x32_bf16 v[28:31], v[158:161], v[188:191], v[28:31]
	v_mfma_f32_16x16x32_bf16 v[20:23], v[150:153], v[196:199], v[20:23]
	v_mfma_f32_16x16x32_bf16 v[12:15], v[158:161], v[196:199], v[12:15]
	s_barrier
; #define PG8_STAGE(bufoff, gbase, voff) do { _Pragma("unroll") for (int _i = 0; _i < 2; ++_i) \
;         __builtin_amdgcn_global_load_lds((const unsigned*)((const char*)(gbase) + (voff)[_i]), (PG8_LAS unsigned*)(lds + (bufoff) + ldsw + _i * 8192), 16, 0, 0); } while (0)
; #define PG8_LDA(dst, b, h) do { _Pragma("unroll") for (int m = 0; m < 4; ++m) _Pragma("unroll") for (int k = 0; k < 2; ++k) dst[m][k] = *(const PG8_LAS bf16x8*)(lds + PG8_SA(b, h) + aoff + m * 2048 + k * 1024); } while (0)
; #define PG8_LDB(dst, b, h) do { _Pragma("unroll") for (int n = 0; n < 2; ++n) _Pragma("unroll") for (int k = 0; k < 2; ++k) dst[n][k] = *(const PG8_LAS bf16x8*)(lds + PG8_SB(b, h) + boff + n * 2048 + k * 1024); } while (0)
; #define PG8_MMA(ai, bj, At, Bt) do { __builtin_amdgcn_s_setprio(1); _Pragma("unroll") for (int m = 0; m < 4; ++m) _Pragma("unroll") for (int n = 0; n < 2; ++n) _Pragma("unroll") for (int k = 0; k < 2; ++k) \
;         acc[ai][bj][m][n] = __builtin_amdgcn_mfma_f32_16x16x32_bf16(Bt[n][k], At[m][k], acc[ai][bj][m][n], 0, 0, 0); __builtin_amdgcn_s_setprio(0); } while (0)
; #define PG8_WAIT_V(n) asm volatile("s_waitcnt vmcnt(" #n ")" ::: "memory")
; #define PG8_WAIT_L(n) asm volatile("s_waitcnt lgkmcnt(" #n ")" ::: "memory")
; #define PG8_BAR __builtin_amdgcn_s_barrier()
; #define PG8_SCHED __builtin_amdgcn_sched_barrier(0)
; template <class Epi, class Sched>
; __device__ __forceinline__ void gemm_phase(PG8_LAS unsigned char* lds, const Gemm g, const Sched& S, const Epi& E) {
;     ...
;             PG8_STAGE(PG8_SB(0, 1), b2 + hstep, voffB);
;             PG8_WAIT_V(6); PG8_BAR; PG8_MMA(1, 1, At, B1); PG8_BAR;
;             PG8_LDB(B0, 1, 0); PG8_SCHED; PG8_LDA(At, 1, 0); PG8_STAGE(PG8_SA(0, 1), a2 + hstep, voffA);
;             PG8_WAIT_L(8); PG8_BAR; PG8_WAIT_L(0); PG8_MMA(0, 0, At, B0); PG8_BAR; PG8_SCHED;
;             PG8_LDB(B1, 1, 1); PG8_STAGE(PG8_SB(1, 0), b3, voffB);
;             PG8_BAR; PG8_WAIT_L(0); PG8_MMA(0, 1, At, B1); PG8_BAR;
;             PG8_LDA(At, 1, 1); PG8_STAGE(PG8_SA(1, 0), a3, voffA);
	s_add_u32 vcc_lo, s20, 0x80000
	s_addc_u32 vcc_hi, s21, 0
	s_add_i32 s69, s89, s72
	v_lshl_add_u64 v[146:147], vcc, 0, v[180:181]
	s_mov_b32 m0, s69
	s_nop 0
	global_load_lds_dwordx4 v[146:147], off
	v_lshl_add_u64 v[146:147], vcc, 0, v[128:129]
	s_add_i32 m0, s69, 0x2000
	s_nop 0
	global_load_lds_dwordx4 v[146:147], off
	s_waitcnt vmcnt(6)
	s_barrier
	v_mfma_f32_16x16x32_bf16 v[48:51], v[200:203], v[162:165], v[48:51]
	v_mfma_f32_16x16x32_bf16 v[40:43], v[208:211], v[162:165], v[40:43]
	v_mfma_f32_16x16x32_bf16 v[32:35], v[200:203], v[170:173], v[32:35]
	v_mfma_f32_16x16x32_bf16 v[24:27], v[208:211], v[170:173], v[24:27]
	v_mfma_f32_16x16x32_bf16 v[16:19], v[200:203], v[184:187], v[16:19]
	v_mfma_f32_16x16x32_bf16 v[8:11], v[208:211], v[184:187], v[8:11]
	v_mfma_f32_16x16x32_bf16 v[4:7], v[200:203], v[192:195], v[4:7]
	v_mfma_f32_16x16x32_bf16 v[0:3], v[208:211], v[192:195], v[0:3]
	v_mfma_f32_16x16x32_bf16 v[48:51], v[204:207], v[166:169], v[48:51]
	v_mfma_f32_16x16x32_bf16 v[40:43], v[212:215], v[166:169], v[40:43]
	v_mfma_f32_16x16x32_bf16 v[32:35], v[204:207], v[174:177], v[32:35]
	v_mfma_f32_16x16x32_bf16 v[24:27], v[212:215], v[174:177], v[24:27]
	v_mfma_f32_16x16x32_bf16 v[16:19], v[204:207], v[188:191], v[16:19]
	v_mfma_f32_16x16x32_bf16 v[8:11], v[212:215], v[188:191], v[8:11]
	v_mfma_f32_16x16x32_bf16 v[4:7], v[204:207], v[196:199], v[4:7]
	v_mfma_f32_16x16x32_bf16 v[0:3], v[212:215], v[196:199], v[0:3]
	s_add_i32 s69, 0, 0x18000
	v_add_u32_e32 v158, s69, v144
	s_barrier
	ds_read_b128 v[146:149], v158
	ds_read_b128 v[150:153], v158 offset:1024
	ds_read_b128 v[154:157], v158 offset:2048
	ds_read_b128 v[158:161], v158 offset:3072
	s_add_u32 s70, s70, 0x80000
	s_addc_u32 s71, s71, 0
	s_mov_b32 m0, s76
	v_lshl_add_u64 v[200:201], s[70:71], 0, v[132:133]
	ds_read_b128 v[162:165], v145 offset:32768
	ds_read_b128 v[166:169], v145 offset:33792
	ds_read_b128 v[170:173], v145 offset:34816
	ds_read_b128 v[174:177], v145 offset:35840
	ds_read_b128 v[184:187], v145 offset:36864
	ds_read_b128 v[188:191], v145 offset:37888
	ds_read_b128 v[192:195], v145 offset:38912
	ds_read_b128 v[196:199], v145 offset:39936
	global_load_lds_dwordx4 v[200:201], off
	v_lshl_add_u64 v[200:201], s[70:71], 0, v[130:131]
	s_mov_b32 m0, s77
	s_nop 0
	global_load_lds_dwordx4 v[200:201], off
	s_waitcnt lgkmcnt(8)
	s_barrier
	s_waitcnt lgkmcnt(0)
	s_waitcnt lgkmcnt(0)
	v_mfma_f32_16x16x32_bf16 v[124:127], v[146:149], v[162:165], v[124:127]
	v_mfma_f32_16x16x32_bf16 v[120:123], v[154:157], v[162:165], v[120:123]
	v_mfma_f32_16x16x32_bf16 v[116:119], v[146:149], v[170:173], v[116:119]
	v_mfma_f32_16x16x32_bf16 v[108:111], v[154:157], v[170:173], v[108:111]
	v_mfma_f32_16x16x32_bf16 v[100:103], v[146:149], v[184:187], v[100:103]
	v_mfma_f32_16x16x32_bf16 v[92:95], v[154:157], v[184:187], v[92:95]
	v_mfma_f32_16x16x32_bf16 v[84:87], v[146:149], v[192:195], v[84:87]
	v_mfma_f32_16x16x32_bf16 v[76:79], v[154:157], v[192:195], v[76:79]
	v_mfma_f32_16x16x32_bf16 v[124:127], v[150:153], v[166:169], v[124:127]
	v_mfma_f32_16x16x32_bf16 v[120:123], v[158:161], v[166:169], v[120:123]
	v_mfma_f32_16x16x32_bf16 v[116:119], v[150:153], v[174:177], v[116:119]
	v_mfma_f32_16x16x32_bf16 v[108:111], v[158:161], v[174:177], v[108:111]
	v_mfma_f32_16x16x32_bf16 v[100:103], v[150:153], v[188:191], v[100:103]
	v_mfma_f32_16x16x32_bf16 v[92:95], v[158:161], v[188:191], v[92:95]
	v_mfma_f32_16x16x32_bf16 v[84:87], v[150:153], v[196:199], v[84:87]
	v_mfma_f32_16x16x32_bf16 v[76:79], v[158:161], v[196:199], v[76:79]
	s_barrier
	s_add_i32 s70, 0, 0x1c000
	s_add_i32 s69, s69, s72
	v_add_u32_e32 v212, s70, v144
	v_lshl_add_u64 v[142:143], v[142:143], 0, s[38:39]
	s_mov_b32 m0, s69
	ds_read_b128 v[200:203], v212
	ds_read_b128 v[204:207], v212 offset:1024
	ds_read_b128 v[208:211], v212 offset:2048
	ds_read_b128 v[212:215], v212 offset:3072
	global_load_lds_dwordx4 v[142:143], off
	v_lshl_add_u64 v[142:143], v[178:179], 0, s[38:39]
	s_add_i32 m0, s69, 0x2000
	s_nop 0
	global_load_lds_dwordx4 v[142:143], off
	s_barrier
	s_waitcnt lgkmcnt(0)
	s_waitcnt lgkmcnt(0)
	v_mfma_f32_16x16x32_bf16 v[112:115], v[200:203], v[162:165], v[112:115]
	v_mfma_f32_16x16x32_bf16 v[104:107], v[208:211], v[162:165], v[104:107]
	v_mfma_f32_16x16x32_bf16 v[96:99], v[200:203], v[170:173], v[96:99]
	v_mfma_f32_16x16x32_bf16 v[88:91], v[208:211], v[170:173], v[88:91]
	v_mfma_f32_16x16x32_bf16 v[80:83], v[200:203], v[184:187], v[80:83]
	v_mfma_f32_16x16x32_bf16 v[72:75], v[208:211], v[184:187], v[72:75]
	v_mfma_f32_16x16x32_bf16 v[68:71], v[200:203], v[192:195], v[68:71]
	v_mfma_f32_16x16x32_bf16 v[64:67], v[208:211], v[192:195], v[64:67]
	v_mfma_f32_16x16x32_bf16 v[112:115], v[204:207], v[166:169], v[112:115]
	v_mfma_f32_16x16x32_bf16 v[104:107], v[212:215], v[166:169], v[104:107]
	v_mfma_f32_16x16x32_bf16 v[96:99], v[204:207], v[174:177], v[96:99]
	v_mfma_f32_16x16x32_bf16 v[88:91], v[212:215], v[174:177], v[88:91]
	v_mfma_f32_16x16x32_bf16 v[80:83], v[204:207], v[188:191], v[80:83]
	v_mfma_f32_16x16x32_bf16 v[72:75], v[212:215], v[188:191], v[72:75]
	v_mfma_f32_16x16x32_bf16 v[68:71], v[204:207], v[196:199], v[68:71]
	v_mfma_f32_16x16x32_bf16 v[64:67], v[212:215], v[196:199], v[64:67]
	s_mov_b32 m0, s78
	v_lshl_add_u64 v[142:143], v[216:217], 0, s[38:39]
	s_barrier
	ds_read_b128 v[162:165], v145 offset:49152
	ds_read_b128 v[166:169], v145 offset:50176
	ds_read_b128 v[170:173], v145 offset:51200
	ds_read_b128 v[174:177], v145 offset:52224
	ds_read_b128 v[184:187], v145 offset:53248
	ds_read_b128 v[188:191], v145 offset:54272
	ds_read_b128 v[192:195], v145 offset:55296
	ds_read_b128 v[196:199], v145 offset:56320
	global_load_lds_dwordx4 v[142:143], off
	v_lshl_add_u64 v[142:143], v[218:219], 0, s[38:39]
	s_mov_b32 m0, s79
	s_nop 0
	global_load_lds_dwordx4 v[142:143], off
	s_barrier
; #define PG8_STAGE(bufoff, gbase, voff) do { _Pragma("unroll") for (int _i = 0; _i < 2; ++_i) \
;         __builtin_amdgcn_global_load_lds((const unsigned*)((const char*)(gbase) + (voff)[_i]), (PG8_LAS unsigned*)(lds + (bufoff) + ldsw + _i * 8192), 16, 0, 0); } while (0)
; #define PG8_MMA(ai, bj, At, Bt) do { __builtin_amdgcn_s_setprio(1); _Pragma("unroll") for (int m = 0; m < 4; ++m) _Pragma("unroll") for (int n = 0; n < 2; ++n) _Pragma("unroll") for (int k = 0; k < 2; ++k) \
;         acc[ai][bj][m][n] = __builtin_amdgcn_mfma_f32_16x16x32_bf16(Bt[n][k], At[m][k], acc[ai][bj][m][n], 0, 0, 0); __builtin_amdgcn_s_setprio(0); } while (0)
; #define PG8_WAIT_V(n) asm volatile("s_waitcnt vmcnt(" #n ")" ::: "memory")
; #define PG8_WAIT_L(n) asm volatile("s_waitcnt lgkmcnt(" #n ")" ::: "memory")
; #define PG8_BAR __builtin_amdgcn_s_barrier()
; #define PG8_SCHED __builtin_amdgcn_sched_barrier(0)
; DI void store8(bf16_t* p, f32x4 a, f32x4 b) { u32x4 w = {cvt_pk_bf16(a[0], a[1]), cvt_pk_bf16(a[2], a[3]), cvt_pk_bf16(b[0], b[1]), cvt_pk_bf16(b[2], b[3])}; *(u32x4*)p = w; }
; template <class Epi, class Sched>
; __device__ __forceinline__ void gemm_phase(PG8_LAS unsigned char* lds, const Gemm g, const Sched& S, const Epi& E) {
;     ...
;             PG8_BAR; PG8_WAIT_L(0); PG8_MMA(1, 0, At, B0); PG8_BAR; PG8_SCHED;
;             PG8_STAGE(PG8_SB(1, 1), b3 + hstep, voffB);
;             PG8_WAIT_V(6); PG8_BAR; PG8_MMA(1, 1, At, B1); PG8_BAR;
;     DI void operator()(const AccT& acc, const pg8::Unit& u, int wr, int wc, int fr, int fq) const {
;         bf16_t* dst = o + u.pn * 256 + wc * 32 + 8 * fq;
; #pragma unroll
;         for (int ai = 0; ai < 2; ++ai)
; #pragma unroll
;             for (int m = 0; m < 4; ++m) { const size_t row = (size_t)u.pm * 256 + wr * 64 + fr + ai * 128 + m * 16;
; #pragma unroll
;                 for (int bj = 0; bj < 2; ++bj) store8(dst + row * ldc + bj * 128, acc[ai][bj][m][0], acc[ai][bj][m][1]); }
;     }
	s_waitcnt lgkmcnt(0)
	s_waitcnt lgkmcnt(0)
	v_mfma_f32_16x16x32_bf16 v[60:63], v[146:149], v[162:165], v[60:63]
	v_mfma_f32_16x16x32_bf16 v[56:59], v[154:157], v[162:165], v[56:59]
	v_mfma_f32_16x16x32_bf16 v[52:55], v[146:149], v[170:173], v[52:55]
	v_mfma_f32_16x16x32_bf16 v[44:47], v[154:157], v[170:173], v[44:47]
	v_mfma_f32_16x16x32_bf16 v[36:39], v[146:149], v[184:187], v[36:39]
	v_mfma_f32_16x16x32_bf16 v[28:31], v[154:157], v[184:187], v[28:31]
	v_mfma_f32_16x16x32_bf16 v[20:23], v[146:149], v[192:195], v[20:23]
	v_mfma_f32_16x16x32_bf16 v[12:15], v[154:157], v[192:195], v[12:15]
	v_mfma_f32_16x16x32_bf16 v[60:63], v[150:153], v[166:169], v[60:63]
	v_mfma_f32_16x16x32_bf16 v[56:59], v[158:161], v[166:169], v[56:59]
	v_mfma_f32_16x16x32_bf16 v[52:55], v[150:153], v[174:177], v[52:55]
	v_mfma_f32_16x16x32_bf16 v[44:47], v[158:161], v[174:177], v[44:47]
	v_mfma_f32_16x16x32_bf16 v[36:39], v[150:153], v[188:191], v[36:39]
	v_mfma_f32_16x16x32_bf16 v[28:31], v[158:161], v[188:191], v[28:31]
	v_mfma_f32_16x16x32_bf16 v[20:23], v[150:153], v[196:199], v[20:23]
	v_mfma_f32_16x16x32_bf16 v[12:15], v[158:161], v[196:199], v[12:15]
	s_barrier
	s_add_u32 s20, s20, 0x80080
	s_addc_u32 s21, s21, 0
	s_add_i32 s69, s70, s72
	v_lshl_add_u64 v[142:143], s[20:21], 0, v[180:181]
	s_mov_b32 m0, s69
	s_nop 0
	global_load_lds_dwordx4 v[142:143], off
	v_lshl_add_u64 v[142:143], s[20:21], 0, v[128:129]
	s_add_i32 m0, s69, 0x2000
	s_nop 0
	global_load_lds_dwordx4 v[142:143], off
	s_waitcnt vmcnt(6)
	s_barrier
	v_mfma_f32_16x16x32_bf16 v[48:51], v[200:203], v[162:165], v[48:51]
	v_mfma_f32_16x16x32_bf16 v[40:43], v[208:211], v[162:165], v[40:43]
	v_mfma_f32_16x16x32_bf16 v[32:35], v[200:203], v[170:173], v[32:35]
	v_mfma_f32_16x16x32_bf16 v[24:27], v[208:211], v[170:173], v[24:27]
	v_mfma_f32_16x16x32_bf16 v[16:19], v[200:203], v[184:187], v[16:19]
	v_mfma_f32_16x16x32_bf16 v[8:11], v[208:211], v[184:187], v[8:11]
	v_mfma_f32_16x16x32_bf16 v[4:7], v[200:203], v[192:195], v[4:7]
	v_mfma_f32_16x16x32_bf16 v[0:3], v[208:211], v[192:195], v[0:3]
	v_mfma_f32_16x16x32_bf16 v[48:51], v[204:207], v[166:169], v[48:51]
	v_mfma_f32_16x16x32_bf16 v[40:43], v[212:215], v[166:169], v[40:43]
	v_mfma_f32_16x16x32_bf16 v[32:35], v[204:207], v[174:177], v[32:35]
	v_mfma_f32_16x16x32_bf16 v[24:27], v[212:215], v[174:177], v[24:27]
	v_mfma_f32_16x16x32_bf16 v[16:19], v[204:207], v[188:191], v[16:19]
	v_mfma_f32_16x16x32_bf16 v[8:11], v[212:215], v[188:191], v[8:11]
	v_mfma_f32_16x16x32_bf16 v[4:7], v[204:207], v[196:199], v[4:7]
	v_mfma_f32_16x16x32_bf16 v[0:3], v[212:215], v[196:199], v[0:3]
	s_add_i32 s88, s88, 2
	s_add_u32 s18, s18, 0x100
	s_addc_u32 s19, s19, 0
	s_add_u32 s82, s82, 0x100
	s_addc_u32 s83, s83, 0
	s_cmp_gt_u32 s88, 29
	s_barrier
	s_cbranch_scc0 .LBB0_580
	s_lshl_b32 s18, s12, 8
	s_ashr_i32 s19, s18, 31
	s_ashr_i32 s11, s10, 31
	v_lshl_add_u64 v[142:143], s[18:19], 1, v[134:135]
	s_lshl_b64 s[10:11], s[10:11], 19
	v_lshl_add_u64 v[142:143], v[142:143], 0, s[10:11]
	v_lshl_add_u64 v[142:143], v[142:143], 0, v[136:137]
	s_mov_b32 s7, 0x8000
	v_cvt_pk_bf16_f32 v124, v124, v125
	v_cvt_pk_bf16_f32 v125, v126, v127
	v_cvt_pk_bf16_f32 v126, v120, v121
	v_cvt_pk_bf16_f32 v127, v122, v123
	global_store_dwordx4 v[142:143], v[124:127], off
	v_cvt_pk_bf16_f32 v112, v112, v113
	v_cvt_pk_bf16_f32 v113, v114, v115
	v_cvt_pk_bf16_f32 v114, v104, v105
	v_cvt_pk_bf16_f32 v115, v106, v107
	global_store_dwordx4 v[142:143], v[112:115], off offset:256
	v_cvt_pk_bf16_f32 v104, v116, v117
	v_cvt_pk_bf16_f32 v105, v118, v119
	v_cvt_pk_bf16_f32 v106, v108, v109
	v_add_co_u32_e32 v108, vcc, s7, v142
	s_mov_b32 s7, 0x10000
	s_nop 0
	v_addc_co_u32_e32 v109, vcc, 0, v143, vcc
	v_cvt_pk_bf16_f32 v107, v110, v111
	global_store_dwordx4 v[108:109], v[104:107], off
	v_cvt_pk_bf16_f32 v96, v96, v97
	v_cvt_pk_bf16_f32 v97, v98, v99
	v_cvt_pk_bf16_f32 v98, v88, v89
	v_cvt_pk_bf16_f32 v99, v90, v91
	global_store_dwordx4 v[108:109], v[96:99], off offset:256
	v_cvt_pk_bf16_f32 v88, v100, v101
	v_cvt_pk_bf16_f32 v89, v102, v103
	v_cvt_pk_bf16_f32 v90, v92, v93
	v_add_co_u32_e32 v92, vcc, s7, v142
	s_mov_b32 s7, 0x18000
	s_nop 0
	v_addc_co_u32_e32 v93, vcc, 0, v143, vcc
	v_cvt_pk_bf16_f32 v91, v94, v95
	global_store_dwordx4 v[92:93], v[88:91], off
	v_cvt_pk_bf16_f32 v80, v80, v81
	v_cvt_pk_bf16_f32 v81, v82, v83
	v_cvt_pk_bf16_f32 v82, v72, v73
	v_cvt_pk_bf16_f32 v83, v74, v75
	global_store_dwordx4 v[92:93], v[80:83], off offset:256
	v_cvt_pk_bf16_f32 v72, v84, v85
	v_cvt_pk_bf16_f32 v73, v86, v87
	v_cvt_pk_bf16_f32 v74, v76, v77
	v_add_co_u32_e32 v76, vcc, s7, v142
	s_mov_b32 s7, 0x40000
	s_nop 0
	v_addc_co_u32_e32 v77, vcc, 0, v143, vcc
	v_cvt_pk_bf16_f32 v75, v78, v79
	global_store_dwordx4 v[76:77], v[72:75], off
	v_cvt_pk_bf16_f32 v68, v68, v69
	v_cvt_pk_bf16_f32 v69, v70, v71
	v_cvt_pk_bf16_f32 v70, v64, v65
	v_cvt_pk_bf16_f32 v71, v66, v67
	global_store_dwordx4 v[76:77], v[68:71], off offset:256
	v_cvt_pk_bf16_f32 v60, v60, v61
	v_cvt_pk_bf16_f32 v61, v62, v63
	v_cvt_pk_bf16_f32 v62, v56, v57
	v_add_co_u32_e32 v56, vcc, s7, v142
	s_mov_b32 s7, 0x48000
	s_nop 0
	v_addc_co_u32_e32 v57, vcc, 0, v143, vcc
	v_cvt_pk_bf16_f32 v63, v58, v59
	global_store_dwordx4 v[56:57], v[60:63], off
	v_cvt_pk_bf16_f32 v48, v48, v49
	v_cvt_pk_bf16_f32 v49, v50, v51
	v_cvt_pk_bf16_f32 v50, v40, v41
	v_cvt_pk_bf16_f32 v51, v42, v43
	global_store_dwordx4 v[56:57], v[48:51], off offset:256
	v_cvt_pk_bf16_f32 v40, v52, v53
	v_cvt_pk_bf16_f32 v41, v54, v55
	v_cvt_pk_bf16_f32 v42, v44, v45
	v_add_co_u32_e32 v44, vcc, s7, v142
	s_mov_b32 s7, 0x50000
	s_nop 0
	v_addc_co_u32_e32 v45, vcc, 0, v143, vcc
	v_cvt_pk_bf16_f32 v43, v46, v47
	global_store_dwordx4 v[44:45], v[40:43], off
	v_cvt_pk_bf16_f32 v32, v32, v33
	v_cvt_pk_bf16_f32 v33, v34, v35
	v_cvt_pk_bf16_f32 v34, v24, v25
	v_cvt_pk_bf16_f32 v35, v26, v27
	global_store_dwordx4 v[44:45], v[32:35], off offset:256
	v_cvt_pk_bf16_f32 v24, v36, v37
	v_cvt_pk_bf16_f32 v25, v38, v39
	v_cvt_pk_bf16_f32 v26, v28, v29
	v_add_co_u32_e32 v28, vcc, s7, v142
	s_mov_b32 s7, 0x58000
	s_nop 0
	v_addc_co_u32_e32 v29, vcc, 0, v143, vcc
	v_cvt_pk_bf16_f32 v27, v30, v31
	global_store_dwordx4 v[28:29], v[24:27], off
	v_cvt_pk_bf16_f32 v16, v16, v17
	v_cvt_pk_bf16_f32 v17, v18, v19
	v_cvt_pk_bf16_f32 v18, v8, v9
	v_cvt_pk_bf16_f32 v19, v10, v11
	global_store_dwordx4 v[28:29], v[16:19], off offset:256
	v_cvt_pk_bf16_f32 v8, v20, v21
	v_cvt_pk_bf16_f32 v9, v22, v23
	v_cvt_pk_bf16_f32 v10, v12, v13
	v_add_co_u32_e32 v12, vcc, s7, v142
	s_mov_b32 s12, s6
	s_nop 0
	v_addc_co_u32_e32 v13, vcc, 0, v143, vcc
	s_and_b64 vcc, exec, s[0:1]
	s_mov_b32 s10, s8
	s_mov_b64 s[20:21], s[16:17]
	s_mov_b64 s[18:19], s[14:15]
	v_cvt_pk_bf16_f32 v11, v14, v15
	global_store_dwordx4 v[12:13], v[8:11], off
	v_cvt_pk_bf16_f32 v4, v4, v5
	v_cvt_pk_bf16_f32 v5, v6, v7
	v_cvt_pk_bf16_f32 v6, v0, v1
	v_cvt_pk_bf16_f32 v7, v2, v3
	global_store_dwordx4 v[12:13], v[4:7], off offset:256
	s_cbranch_vccz .LBB0_577
	s_waitcnt vmcnt(0)
	s_cmpk_gt_u32 s47, 0xff
	s_cbranch_scc1 .LBB0_584
	s_barrier

; #define PG8_STAGE(bufoff, gbase, voff) do { _Pragma("unroll") for (int _i = 0; _i < 2; ++_i) \
;         __builtin_amdgcn_global_load_lds((const unsigned*)((const char*)(gbase) + (voff)[_i]), (PG8_LAS unsigned*)(lds + (bufoff) + ldsw + _i * 8192), 16, 0, 0); } while (0)
; #define PG8_LDA(dst, b, h) do { _Pragma("unroll") for (int m = 0; m < 4; ++m) _Pragma("unroll") for (int k = 0; k < 2; ++k) dst[m][k] = *(const PG8_LAS bf16x8*)(lds + PG8_SA(b, h) + aoff + m * 2048 + k * 1024); } while (0)
; #define PG8_LDB(dst, b, h) do { _Pragma("unroll") for (int n = 0; n < 2; ++n) _Pragma("unroll") for (int k = 0; k < 2; ++k) dst[n][k] = *(const PG8_LAS bf16x8*)(lds + PG8_SB(b, h) + boff + n * 2048 + k * 1024); } while (0)
; #define PG8_MMA(ai, bj, At, Bt) do { __builtin_amdgcn_s_setprio(1); _Pragma("unroll") for (int m = 0; m < 4; ++m) _Pragma("unroll") for (int n = 0; n < 2; ++n) _Pragma("unroll") for (int k = 0; k < 2; ++k) \
;         acc[ai][bj][m][n] = __builtin_amdgcn_mfma_f32_16x16x32_bf16(Bt[n][k], At[m][k], acc[ai][bj][m][n], 0, 0, 0); __builtin_amdgcn_s_setprio(0); } while (0)
; #define PG8_WAIT_L(n) asm volatile("s_waitcnt lgkmcnt(" #n ")" ::: "memory")
; #define PG8_BAR __builtin_amdgcn_s_barrier()
; #define PG8_SCHED __builtin_amdgcn_sched_barrier(0)
; template <class Epi, class Sched>
; __device__ __forceinline__ void gemm_phase(PG8_LAS unsigned char* lds, const Gemm g, const Sched& S, const Epi& E) {
;     ...
;             PG8_LDB(B0, 0, 0); PG8_SCHED; PG8_LDA(At, 0, 0); PG8_STAGE(PG8_SA(1, 1), a1 + hstep, voffA);
;             PG8_WAIT_L(8); PG8_BAR; PG8_WAIT_L(0); PG8_MMA(0, 0, At, B0); PG8_BAR; PG8_SCHED;
;             PG8_LDB(B1, 0, 1); PG8_STAGE(PG8_SB(0, 0), b2, voffB);
;             PG8_BAR; PG8_WAIT_L(0); PG8_MMA(0, 1, At, B1); PG8_BAR;
;             PG8_LDA(At, 0, 1); PG8_STAGE(PG8_SA(0, 0), a2, voffA);
;             PG8_BAR; PG8_WAIT_L(0); PG8_MMA(1, 0, At, B0); PG8_BAR; PG8_SCHED;
.LBB0_648:
	s_add_u32 s16, s14, 0xfffc0080
	s_addc_u32 s17, s15, -1
	s_add_i32 s80, 0, 0x10000
	v_add_u32_e32 v146, s80, v139
	ds_read_b128 v[150:153], v146
	ds_read_b128 v[154:157], v146 offset:1024
	ds_read_b128 v[158:161], v146 offset:2048
	ds_read_b128 v[162:165], v146 offset:3072
	s_cmp_eq_u32 s79, 12
	s_cselect_b32 s19, s9, s17
	s_cselect_b32 s18, s75, s16
	s_cselect_b32 s17, s1, s78
	s_cselect_b32 s16, s76, s77
	v_lshl_add_u64 v[146:147], s[14:15], 0, v[142:143]
	s_add_i32 m0, s46, 0xc000
	ds_read_b128 v[166:169], v148
	ds_read_b128 v[170:173], v148 offset:1024
	ds_read_b128 v[174:177], v148 offset:2048
	ds_read_b128 v[184:187], v148 offset:3072
	ds_read_b128 v[188:191], v148 offset:4096
	ds_read_b128 v[192:195], v148 offset:5120
	ds_read_b128 v[196:199], v148 offset:6144
	ds_read_b128 v[200:203], v148 offset:7168
	global_load_lds_dwordx4 v[146:147], off
	v_lshl_add_u64 v[146:147], s[14:15], 0, v[144:145]
	s_add_i32 m0, s46, 0xe000
	s_nop 0
	global_load_lds_dwordx4 v[146:147], off
	s_waitcnt lgkmcnt(8)
	s_barrier
	s_waitcnt lgkmcnt(0)
	s_waitcnt lgkmcnt(0)
	v_mfma_f32_16x16x32_bf16 v[124:127], v[150:153], v[166:169], v[124:127]
	v_mfma_f32_16x16x32_bf16 v[120:123], v[158:161], v[166:169], v[120:123]
	v_mfma_f32_16x16x32_bf16 v[108:111], v[150:153], v[174:177], v[108:111]
	v_mfma_f32_16x16x32_bf16 v[104:107], v[158:161], v[174:177], v[104:107]
	v_mfma_f32_16x16x32_bf16 v[92:95], v[150:153], v[188:191], v[92:95]
	v_mfma_f32_16x16x32_bf16 v[88:91], v[158:161], v[188:191], v[88:91]
	v_mfma_f32_16x16x32_bf16 v[76:79], v[150:153], v[196:199], v[76:79]
	v_mfma_f32_16x16x32_bf16 v[72:75], v[158:161], v[196:199], v[72:75]
	v_mfma_f32_16x16x32_bf16 v[124:127], v[154:157], v[170:173], v[124:127]
	v_mfma_f32_16x16x32_bf16 v[120:123], v[162:165], v[170:173], v[120:123]
	v_mfma_f32_16x16x32_bf16 v[108:111], v[154:157], v[184:187], v[108:111]
	v_mfma_f32_16x16x32_bf16 v[104:107], v[162:165], v[184:187], v[104:107]
	v_mfma_f32_16x16x32_bf16 v[92:95], v[154:157], v[192:195], v[92:95]
	v_mfma_f32_16x16x32_bf16 v[88:91], v[162:165], v[192:195], v[88:91]
	v_mfma_f32_16x16x32_bf16 v[76:79], v[154:157], v[200:203], v[76:79]
	v_mfma_f32_16x16x32_bf16 v[72:75], v[162:165], v[200:203], v[72:75]
	s_barrier
	s_add_i32 s82, 0, 0x14000
	v_add_u32_e32 v146, s82, v139
	s_add_i32 s80, s80, s21
	ds_read_b128 v[204:207], v146
	ds_read_b128 v[208:211], v146 offset:1024
	ds_read_b128 v[212:215], v146 offset:2048
	ds_read_b128 v[216:219], v146 offset:3072
	v_lshl_add_u64 v[146:147], s[16:17], 0, v[132:133]
	s_mov_b32 m0, s80
	v_lshl_add_u64 v[178:179], s[16:17], 0, v[128:129]
	global_load_lds_dwordx4 v[146:147], off
	s_add_i32 m0, s80, 0x2000
	s_nop 0
	global_load_lds_dwordx4 v[178:179], off
	s_barrier
	s_waitcnt lgkmcnt(0)
	s_waitcnt lgkmcnt(0)
	v_mfma_f32_16x16x32_bf16 v[116:119], v[204:207], v[166:169], v[116:119]
	v_mfma_f32_16x16x32_bf16 v[112:115], v[212:215], v[166:169], v[112:115]
	v_mfma_f32_16x16x32_bf16 v[100:103], v[204:207], v[174:177], v[100:103]
	v_mfma_f32_16x16x32_bf16 v[96:99], v[212:215], v[174:177], v[96:99]
	v_mfma_f32_16x16x32_bf16 v[84:87], v[204:207], v[188:191], v[84:87]
	v_mfma_f32_16x16x32_bf16 v[80:83], v[212:215], v[188:191], v[80:83]
	v_mfma_f32_16x16x32_bf16 v[68:71], v[204:207], v[196:199], v[68:71]
	v_mfma_f32_16x16x32_bf16 v[64:67], v[212:215], v[196:199], v[64:67]
	v_mfma_f32_16x16x32_bf16 v[116:119], v[208:211], v[170:173], v[116:119]
	v_mfma_f32_16x16x32_bf16 v[112:115], v[216:219], v[170:173], v[112:115]
	v_mfma_f32_16x16x32_bf16 v[100:103], v[208:211], v[184:187], v[100:103]
	v_mfma_f32_16x16x32_bf16 v[96:99], v[216:219], v[184:187], v[96:99]
	v_mfma_f32_16x16x32_bf16 v[84:87], v[208:211], v[192:195], v[84:87]
	v_mfma_f32_16x16x32_bf16 v[80:83], v[216:219], v[192:195], v[80:83]
	v_mfma_f32_16x16x32_bf16 v[68:71], v[208:211], v[200:203], v[68:71]
	v_mfma_f32_16x16x32_bf16 v[64:67], v[216:219], v[200:203], v[64:67]
	s_mov_b32 m0, s46
	v_lshl_add_u64 v[220:221], s[18:19], 0, v[134:135]
	s_barrier
	ds_read_b128 v[166:169], v148 offset:16384
	ds_read_b128 v[170:173], v148 offset:17408
	ds_read_b128 v[174:177], v148 offset:18432
	ds_read_b128 v[184:187], v148 offset:19456
	ds_read_b128 v[188:191], v148 offset:20480
	ds_read_b128 v[192:195], v148 offset:21504
	ds_read_b128 v[196:199], v148 offset:22528
	ds_read_b128 v[200:203], v148 offset:23552
	global_load_lds_dwordx4 v[220:221], off
	v_lshl_add_u64 v[222:223], s[18:19], 0, v[130:131]
	s_mov_b32 m0, s47
	s_nop 0
	global_load_lds_dwordx4 v[222:223], off
	s_barrier
	s_waitcnt lgkmcnt(0)
	s_waitcnt lgkmcnt(0)
	v_mfma_f32_16x16x32_bf16 v[60:63], v[150:153], v[166:169], v[60:63]
	v_mfma_f32_16x16x32_bf16 v[56:59], v[158:161], v[166:169], v[56:59]
	v_mfma_f32_16x16x32_bf16 v[44:47], v[150:153], v[174:177], v[44:47]
	v_mfma_f32_16x16x32_bf16 v[40:43], v[158:161], v[174:177], v[40:43]
	v_mfma_f32_16x16x32_bf16 v[28:31], v[150:153], v[188:191], v[28:31]
	v_mfma_f32_16x16x32_bf16 v[24:27], v[158:161], v[188:191], v[24:27]
	v_mfma_f32_16x16x32_bf16 v[12:15], v[150:153], v[196:199], v[12:15]
	v_mfma_f32_16x16x32_bf16 v[8:11], v[158:161], v[196:199], v[8:11]
	v_mfma_f32_16x16x32_bf16 v[60:63], v[154:157], v[170:173], v[60:63]
	v_mfma_f32_16x16x32_bf16 v[56:59], v[162:165], v[170:173], v[56:59]
	v_mfma_f32_16x16x32_bf16 v[44:47], v[154:157], v[184:187], v[44:47]
	v_mfma_f32_16x16x32_bf16 v[40:43], v[162:165], v[184:187], v[40:43]
	v_mfma_f32_16x16x32_bf16 v[28:31], v[154:157], v[192:195], v[28:31]
	v_mfma_f32_16x16x32_bf16 v[24:27], v[162:165], v[192:195], v[24:27]
	v_mfma_f32_16x16x32_bf16 v[12:15], v[154:157], v[200:203], v[12:15]
	v_mfma_f32_16x16x32_bf16 v[8:11], v[162:165], v[200:203], v[8:11]
	s_barrier
; #define PG8_STAGE(bufoff, gbase, voff) do { _Pragma("unroll") for (int _i = 0; _i < 2; ++_i) \
;         __builtin_amdgcn_global_load_lds((const unsigned*)((const char*)(gbase) + (voff)[_i]), (PG8_LAS unsigned*)(lds + (bufoff) + ldsw + _i * 8192), 16, 0, 0); } while (0)
; #define PG8_LDA(dst, b, h) do { _Pragma("unroll") for (int m = 0; m < 4; ++m) _Pragma("unroll") for (int k = 0; k < 2; ++k) dst[m][k] = *(const PG8_LAS bf16x8*)(lds + PG8_SA(b, h) + aoff + m * 2048 + k * 1024); } while (0)
; #define PG8_LDB(dst, b, h) do { _Pragma("unroll") for (int n = 0; n < 2; ++n) _Pragma("unroll") for (int k = 0; k < 2; ++k) dst[n][k] = *(const PG8_LAS bf16x8*)(lds + PG8_SB(b, h) + boff + n * 2048 + k * 1024); } while (0)
; #define PG8_MMA(ai, bj, At, Bt) do { __builtin_amdgcn_s_setprio(1); _Pragma("unroll") for (int m = 0; m < 4; ++m) _Pragma("unroll") for (int n = 0; n < 2; ++n) _Pragma("unroll") for (int k = 0; k < 2; ++k) \
;         acc[ai][bj][m][n] = __builtin_amdgcn_mfma_f32_16x16x32_bf16(Bt[n][k], At[m][k], acc[ai][bj][m][n], 0, 0, 0); __builtin_amdgcn_s_setprio(0); } while (0)
; #define PG8_WAIT_V(n) asm volatile("s_waitcnt vmcnt(" #n ")" ::: "memory")
; #define PG8_WAIT_L(n) asm volatile("s_waitcnt lgkmcnt(" #n ")" ::: "memory")
; #define PG8_BAR __builtin_amdgcn_s_barrier()
; #define PG8_SCHED __builtin_amdgcn_sched_barrier(0)
; template <class Epi, class Sched>
; __device__ __forceinline__ void gemm_phase(PG8_LAS unsigned char* lds, const Gemm g, const Sched& S, const Epi& E) {
;     ...
;             PG8_STAGE(PG8_SB(0, 1), b2 + hstep, voffB);
;             PG8_WAIT_V(6); PG8_BAR; PG8_MMA(1, 1, At, B1); PG8_BAR;
;             PG8_LDB(B0, 1, 0); PG8_SCHED; PG8_LDA(At, 1, 0); PG8_STAGE(PG8_SA(0, 1), a2 + hstep, voffA);
;             PG8_WAIT_L(8); PG8_BAR; PG8_WAIT_L(0); PG8_MMA(0, 0, At, B0); PG8_BAR; PG8_SCHED;
;             PG8_LDB(B1, 1, 1); PG8_STAGE(PG8_SB(1, 0), b3, voffB);
	s_add_u32 s80, s16, 0x40000
	s_addc_u32 s81, s17, 0
	s_add_i32 s82, s82, s21
	v_lshl_add_u64 v[150:151], s[80:81], 0, v[132:133]
	s_mov_b32 m0, s82
	s_nop 0
	global_load_lds_dwordx4 v[150:151], off
	v_lshl_add_u64 v[150:151], s[80:81], 0, v[128:129]
	s_add_i32 m0, s82, 0x2000
	s_nop 0
	global_load_lds_dwordx4 v[150:151], off
	s_waitcnt vmcnt(6)
	s_barrier
	v_mfma_f32_16x16x32_bf16 v[52:55], v[204:207], v[166:169], v[52:55]
	v_mfma_f32_16x16x32_bf16 v[48:51], v[212:215], v[166:169], v[48:51]
	v_mfma_f32_16x16x32_bf16 v[36:39], v[204:207], v[174:177], v[36:39]
	v_mfma_f32_16x16x32_bf16 v[32:35], v[212:215], v[174:177], v[32:35]
	v_mfma_f32_16x16x32_bf16 v[20:23], v[204:207], v[188:191], v[20:23]
	v_mfma_f32_16x16x32_bf16 v[16:19], v[212:215], v[188:191], v[16:19]
	v_mfma_f32_16x16x32_bf16 v[4:7], v[204:207], v[196:199], v[4:7]
	v_mfma_f32_16x16x32_bf16 v[0:3], v[212:215], v[196:199], v[0:3]
	v_mfma_f32_16x16x32_bf16 v[52:55], v[208:211], v[170:173], v[52:55]
	v_mfma_f32_16x16x32_bf16 v[48:51], v[216:219], v[170:173], v[48:51]
	v_mfma_f32_16x16x32_bf16 v[36:39], v[208:211], v[184:187], v[36:39]
	v_mfma_f32_16x16x32_bf16 v[32:35], v[216:219], v[184:187], v[32:35]
	v_mfma_f32_16x16x32_bf16 v[20:23], v[208:211], v[192:195], v[20:23]
	v_mfma_f32_16x16x32_bf16 v[16:19], v[216:219], v[192:195], v[16:19]
	v_mfma_f32_16x16x32_bf16 v[4:7], v[208:211], v[200:203], v[4:7]
	v_mfma_f32_16x16x32_bf16 v[0:3], v[216:219], v[200:203], v[0:3]
	s_add_i32 s80, 0, 0x18000
	v_add_u32_e32 v149, s80, v139
	s_barrier
	ds_read_b128 v[150:153], v149
	ds_read_b128 v[154:157], v149 offset:1024
	ds_read_b128 v[158:161], v149 offset:2048
	ds_read_b128 v[162:165], v149 offset:3072
	s_add_u32 s18, s18, 0x40000
	s_addc_u32 s19, s19, 0
	s_mov_b32 m0, s70
	v_lshl_add_u64 v[204:205], s[18:19], 0, v[134:135]
	ds_read_b128 v[166:169], v148 offset:32768
	ds_read_b128 v[170:173], v148 offset:33792
	ds_read_b128 v[174:177], v148 offset:34816
	ds_read_b128 v[184:187], v148 offset:35840
	ds_read_b128 v[188:191], v148 offset:36864
	ds_read_b128 v[192:195], v148 offset:37888
	ds_read_b128 v[196:199], v148 offset:38912
	ds_read_b128 v[200:203], v148 offset:39936
	global_load_lds_dwordx4 v[204:205], off
	v_lshl_add_u64 v[204:205], s[18:19], 0, v[130:131]
	s_mov_b32 m0, s71
	s_nop 0
	global_load_lds_dwordx4 v[204:205], off
	s_waitcnt lgkmcnt(8)
	s_barrier
	s_waitcnt lgkmcnt(0)
	s_waitcnt lgkmcnt(0)
	v_mfma_f32_16x16x32_bf16 v[124:127], v[150:153], v[166:169], v[124:127]
	v_mfma_f32_16x16x32_bf16 v[120:123], v[158:161], v[166:169], v[120:123]
	v_mfma_f32_16x16x32_bf16 v[108:111], v[150:153], v[174:177], v[108:111]
	v_mfma_f32_16x16x32_bf16 v[104:107], v[158:161], v[174:177], v[104:107]
	v_mfma_f32_16x16x32_bf16 v[92:95], v[150:153], v[188:191], v[92:95]
	v_mfma_f32_16x16x32_bf16 v[88:91], v[158:161], v[188:191], v[88:91]
	v_mfma_f32_16x16x32_bf16 v[76:79], v[150:153], v[196:199], v[76:79]
	v_mfma_f32_16x16x32_bf16 v[72:75], v[158:161], v[196:199], v[72:75]
	v_mfma_f32_16x16x32_bf16 v[124:127], v[154:157], v[170:173], v[124:127]
	v_mfma_f32_16x16x32_bf16 v[120:123], v[162:165], v[170:173], v[120:123]
	v_mfma_f32_16x16x32_bf16 v[108:111], v[154:157], v[184:187], v[108:111]
	v_mfma_f32_16x16x32_bf16 v[104:107], v[162:165], v[184:187], v[104:107]
	v_mfma_f32_16x16x32_bf16 v[92:95], v[154:157], v[192:195], v[92:95]
	v_mfma_f32_16x16x32_bf16 v[88:91], v[162:165], v[192:195], v[88:91]
	v_mfma_f32_16x16x32_bf16 v[76:79], v[154:157], v[200:203], v[76:79]
	v_mfma_f32_16x16x32_bf16 v[72:75], v[162:165], v[200:203], v[72:75]
	s_barrier
	s_add_i32 s18, 0, 0x1c000
	s_add_i32 s19, s80, s21
	v_add_u32_e32 v149, s18, v139
	v_lshl_add_u64 v[146:147], v[146:147], 0, s[38:39]
	s_mov_b32 m0, s19
	ds_read_b128 v[204:207], v149
	ds_read_b128 v[208:211], v149 offset:1024
	ds_read_b128 v[212:215], v149 offset:2048
	ds_read_b128 v[216:219], v149 offset:3072
	global_load_lds_dwordx4 v[146:147], off
	v_lshl_add_u64 v[146:147], v[178:179], 0, s[38:39]
	s_add_i32 m0, s19, 0x2000
	s_nop 0
	global_load_lds_dwordx4 v[146:147], off
	s_barrier
; #define PG8_STAGE(bufoff, gbase, voff) do { _Pragma("unroll") for (int _i = 0; _i < 2; ++_i) \
;         __builtin_amdgcn_global_load_lds((const unsigned*)((const char*)(gbase) + (voff)[_i]), (PG8_LAS unsigned*)(lds + (bufoff) + ldsw + _i * 8192), 16, 0, 0); } while (0)
; #define PG8_LDA(dst, b, h) do { _Pragma("unroll") for (int m = 0; m < 4; ++m) _Pragma("unroll") for (int k = 0; k < 2; ++k) dst[m][k] = *(const PG8_LAS bf16x8*)(lds + PG8_SA(b, h) + aoff + m * 2048 + k * 1024); } while (0)
; #define PG8_MMA(ai, bj, At, Bt) do { __builtin_amdgcn_s_setprio(1); _Pragma("unroll") for (int m = 0; m < 4; ++m) _Pragma("unroll") for (int n = 0; n < 2; ++n) _Pragma("unroll") for (int k = 0; k < 2; ++k) \
;         acc[ai][bj][m][n] = __builtin_amdgcn_mfma_f32_16x16x32_bf16(Bt[n][k], At[m][k], acc[ai][bj][m][n], 0, 0, 0); __builtin_amdgcn_s_setprio(0); } while (0)
; #define PG8_WAIT_V(n) asm volatile("s_waitcnt vmcnt(" #n ")" ::: "memory")
; #define PG8_WAIT_L(n) asm volatile("s_waitcnt lgkmcnt(" #n ")" ::: "memory")
; #define PG8_BAR __builtin_amdgcn_s_barrier()
; #define PG8_SCHED __builtin_amdgcn_sched_barrier(0)
; template <class Epi, class Sched>
; __device__ __forceinline__ void gemm_phase(PG8_LAS unsigned char* lds, const Gemm g, const Sched& S, const Epi& E) {
;     ...
;             PG8_BAR; PG8_WAIT_L(0); PG8_MMA(0, 1, At, B1); PG8_BAR;
;             PG8_LDA(At, 1, 1); PG8_STAGE(PG8_SA(1, 0), a3, voffA);
;             PG8_BAR; PG8_WAIT_L(0); PG8_MMA(1, 0, At, B0); PG8_BAR; PG8_SCHED;
;             PG8_STAGE(PG8_SB(1, 1), b3 + hstep, voffB);
;             PG8_WAIT_V(6); PG8_BAR; PG8_MMA(1, 1, At, B1); PG8_BAR;
;     DI void operator()(const AccT& acc, const pg8::Unit& u, int wr, int wc, int fr, int fq) const {
;     ...
;         if (pn < 8) {
;     ...
;             bf16_t* dst = (pn == 8 ? kb : vb) + cl;
;             const int kvbase = pm < 128 ? (pm >> 4) * KVS + (pm & 15) * 256 : (pm - 128) * KVS + SEQ;
	s_waitcnt lgkmcnt(0)
	s_waitcnt lgkmcnt(0)
	v_mfma_f32_16x16x32_bf16 v[116:119], v[204:207], v[166:169], v[116:119]
	v_mfma_f32_16x16x32_bf16 v[112:115], v[212:215], v[166:169], v[112:115]
	v_mfma_f32_16x16x32_bf16 v[100:103], v[204:207], v[174:177], v[100:103]
	v_mfma_f32_16x16x32_bf16 v[96:99], v[212:215], v[174:177], v[96:99]
	v_mfma_f32_16x16x32_bf16 v[84:87], v[204:207], v[188:191], v[84:87]
	v_mfma_f32_16x16x32_bf16 v[80:83], v[212:215], v[188:191], v[80:83]
	v_mfma_f32_16x16x32_bf16 v[68:71], v[204:207], v[196:199], v[68:71]
	v_mfma_f32_16x16x32_bf16 v[64:67], v[212:215], v[196:199], v[64:67]
	v_mfma_f32_16x16x32_bf16 v[116:119], v[208:211], v[170:173], v[116:119]
	v_mfma_f32_16x16x32_bf16 v[112:115], v[216:219], v[170:173], v[112:115]
	v_mfma_f32_16x16x32_bf16 v[100:103], v[208:211], v[184:187], v[100:103]
	v_mfma_f32_16x16x32_bf16 v[96:99], v[216:219], v[184:187], v[96:99]
	v_mfma_f32_16x16x32_bf16 v[84:87], v[208:211], v[192:195], v[84:87]
	v_mfma_f32_16x16x32_bf16 v[80:83], v[216:219], v[192:195], v[80:83]
	v_mfma_f32_16x16x32_bf16 v[68:71], v[208:211], v[200:203], v[68:71]
	v_mfma_f32_16x16x32_bf16 v[64:67], v[216:219], v[200:203], v[64:67]
	s_mov_b32 m0, s72
	v_lshl_add_u64 v[146:147], v[220:221], 0, s[38:39]
	s_barrier
	ds_read_b128 v[166:169], v148 offset:49152
	ds_read_b128 v[170:173], v148 offset:50176
	ds_read_b128 v[174:177], v148 offset:51200
	ds_read_b128 v[184:187], v148 offset:52224
	ds_read_b128 v[188:191], v148 offset:53248
	ds_read_b128 v[192:195], v148 offset:54272
	ds_read_b128 v[196:199], v148 offset:55296
	ds_read_b128 v[200:203], v148 offset:56320
	global_load_lds_dwordx4 v[146:147], off
	v_lshl_add_u64 v[146:147], v[222:223], 0, s[38:39]
	s_mov_b32 m0, s73
	s_nop 0
	global_load_lds_dwordx4 v[146:147], off
	s_barrier
	s_waitcnt lgkmcnt(0)
	s_waitcnt lgkmcnt(0)
	v_mfma_f32_16x16x32_bf16 v[60:63], v[150:153], v[166:169], v[60:63]
	v_mfma_f32_16x16x32_bf16 v[56:59], v[158:161], v[166:169], v[56:59]
	v_mfma_f32_16x16x32_bf16 v[44:47], v[150:153], v[174:177], v[44:47]
	v_mfma_f32_16x16x32_bf16 v[40:43], v[158:161], v[174:177], v[40:43]
	v_mfma_f32_16x16x32_bf16 v[28:31], v[150:153], v[188:191], v[28:31]
	v_mfma_f32_16x16x32_bf16 v[24:27], v[158:161], v[188:191], v[24:27]
	v_mfma_f32_16x16x32_bf16 v[12:15], v[150:153], v[196:199], v[12:15]
	v_mfma_f32_16x16x32_bf16 v[8:11], v[158:161], v[196:199], v[8:11]
	v_mfma_f32_16x16x32_bf16 v[60:63], v[154:157], v[170:173], v[60:63]
	v_mfma_f32_16x16x32_bf16 v[56:59], v[162:165], v[170:173], v[56:59]
	v_mfma_f32_16x16x32_bf16 v[44:47], v[154:157], v[184:187], v[44:47]
	v_mfma_f32_16x16x32_bf16 v[40:43], v[162:165], v[184:187], v[40:43]
	v_mfma_f32_16x16x32_bf16 v[28:31], v[154:157], v[192:195], v[28:31]
	v_mfma_f32_16x16x32_bf16 v[24:27], v[162:165], v[192:195], v[24:27]
	v_mfma_f32_16x16x32_bf16 v[12:15], v[154:157], v[200:203], v[12:15]
	v_mfma_f32_16x16x32_bf16 v[8:11], v[162:165], v[200:203], v[8:11]
	s_barrier
	s_add_u32 s16, s16, 0x40080
	s_addc_u32 s17, s17, 0
	s_add_i32 s18, s18, s21
	v_lshl_add_u64 v[146:147], s[16:17], 0, v[132:133]
	s_mov_b32 m0, s18
	s_nop 0
	global_load_lds_dwordx4 v[146:147], off
	v_lshl_add_u64 v[146:147], s[16:17], 0, v[128:129]
	s_add_i32 m0, s18, 0x2000
	s_nop 0
	global_load_lds_dwordx4 v[146:147], off
	s_waitcnt vmcnt(6)
	s_barrier
	v_mfma_f32_16x16x32_bf16 v[52:55], v[204:207], v[166:169], v[52:55]
	v_mfma_f32_16x16x32_bf16 v[48:51], v[212:215], v[166:169], v[48:51]
	v_mfma_f32_16x16x32_bf16 v[36:39], v[204:207], v[174:177], v[36:39]
	v_mfma_f32_16x16x32_bf16 v[32:35], v[212:215], v[174:177], v[32:35]
	v_mfma_f32_16x16x32_bf16 v[20:23], v[204:207], v[188:191], v[20:23]
	v_mfma_f32_16x16x32_bf16 v[16:19], v[212:215], v[188:191], v[16:19]
	v_mfma_f32_16x16x32_bf16 v[4:7], v[204:207], v[196:199], v[4:7]
	v_mfma_f32_16x16x32_bf16 v[0:3], v[212:215], v[196:199], v[0:3]
	v_mfma_f32_16x16x32_bf16 v[52:55], v[208:211], v[170:173], v[52:55]
	v_mfma_f32_16x16x32_bf16 v[48:51], v[216:219], v[170:173], v[48:51]
	v_mfma_f32_16x16x32_bf16 v[36:39], v[208:211], v[184:187], v[36:39]
	v_mfma_f32_16x16x32_bf16 v[32:35], v[216:219], v[184:187], v[32:35]
	v_mfma_f32_16x16x32_bf16 v[20:23], v[208:211], v[192:195], v[20:23]
	v_mfma_f32_16x16x32_bf16 v[16:19], v[216:219], v[192:195], v[16:19]
	v_mfma_f32_16x16x32_bf16 v[4:7], v[208:211], v[200:203], v[4:7]
	v_mfma_f32_16x16x32_bf16 v[0:3], v[216:219], v[200:203], v[0:3]
	s_add_i32 s79, s79, 2
	s_add_u32 s14, s14, 0x100
	s_addc_u32 s15, s15, 0
	s_add_u32 s77, s77, 0x100
	s_addc_u32 s78, s78, 0
	s_cmp_gt_u32 s79, 13
	s_barrier
	s_cbranch_scc0 .LBB0_648
	s_cmp_gt_i32 s7, 7
	s_mov_b64 s[14:15], -1
	s_cbranch_scc0 .LBB0_655
	s_cmpk_gt_i32 s6, 0x7f
	s_mov_b64 s[16:17], -1
	s_cbranch_scc0 .LBB0_652
	s_mul_i32 s1, s6, 0x1100
	s_add_i32 s14, s1, 0xfff79000
	s_mov_b64 s[16:17], 0

; #define PG8_STAGE(bufoff, gbase, voff) do { _Pragma("unroll") for (int _i = 0; _i < 2; ++_i) \
;         __builtin_amdgcn_global_load_lds((const unsigned*)((const char*)(gbase) + (voff)[_i]), (PG8_LAS unsigned*)(lds + (bufoff) + ldsw + _i * 8192), 16, 0, 0); } while (0)
; #define PG8_LDA(dst, b, h) do { _Pragma("unroll") for (int m = 0; m < 4; ++m) _Pragma("unroll") for (int k = 0; k < 2; ++k) dst[m][k] = *(const PG8_LAS bf16x8*)(lds + PG8_SA(b, h) + aoff + m * 2048 + k * 1024); } while (0)
; #define PG8_LDB(dst, b, h) do { _Pragma("unroll") for (int n = 0; n < 2; ++n) _Pragma("unroll") for (int k = 0; k < 2; ++k) dst[n][k] = *(const PG8_LAS bf16x8*)(lds + PG8_SB(b, h) + boff + n * 2048 + k * 1024); } while (0)
; #define PG8_MMA(ai, bj, At, Bt) do { __builtin_amdgcn_s_setprio(1); _Pragma("unroll") for (int m = 0; m < 4; ++m) _Pragma("unroll") for (int n = 0; n < 2; ++n) _Pragma("unroll") for (int k = 0; k < 2; ++k) \
;         acc[ai][bj][m][n] = __builtin_amdgcn_mfma_f32_16x16x32_bf16(Bt[n][k], At[m][k], acc[ai][bj][m][n], 0, 0, 0); __builtin_amdgcn_s_setprio(0); } while (0)
; #define PG8_WAIT_L(n) asm volatile("s_waitcnt lgkmcnt(" #n ")" ::: "memory")
; #define PG8_BAR __builtin_amdgcn_s_barrier()
; #define PG8_SCHED __builtin_amdgcn_sched_barrier(0)
; template <class Epi, class Sched>
; __device__ __forceinline__ void gemm_phase(PG8_LAS unsigned char* lds, const Gemm g, const Sched& S, const Epi& E) {
;     ...
;             PG8_LDB(B0, 0, 0); PG8_SCHED; PG8_LDA(At, 0, 0); PG8_STAGE(PG8_SA(1, 1), a1 + hstep, voffA);
;             PG8_WAIT_L(8); PG8_BAR; PG8_WAIT_L(0); PG8_MMA(0, 0, At, B0); PG8_BAR; PG8_SCHED;
;             PG8_LDB(B1, 0, 1); PG8_STAGE(PG8_SB(0, 0), b2, voffB);
;             PG8_BAR; PG8_WAIT_L(0); PG8_MMA(0, 1, At, B1); PG8_BAR;
;             PG8_LDA(At, 0, 1); PG8_STAGE(PG8_SA(0, 0), a2, voffA);
;             PG8_BAR; PG8_WAIT_L(0); PG8_MMA(1, 0, At, B0); PG8_BAR; PG8_SCHED;
.LBB0_912:
	s_add_u32 s16, s14, 0xfffc0080
	s_addc_u32 s17, s15, -1
	s_add_i32 s79, 0, 0x10000
	v_add_u32_e32 v142, s79, v144
	ds_read_b128 v[146:149], v142
	ds_read_b128 v[150:153], v142 offset:1024
	ds_read_b128 v[154:157], v142 offset:2048
	ds_read_b128 v[158:161], v142 offset:3072
	s_cmp_eq_u32 s78, 12
	s_cselect_b32 s19, s7, s17
	s_cselect_b32 s18, s74, s16
	s_cselect_b32 s17, s5, s77
	s_cselect_b32 s16, s75, s76
	v_lshl_add_u64 v[142:143], s[14:15], 0, v[138:139]
	s_add_i32 m0, s46, 0xc000
	ds_read_b128 v[162:165], v145
	ds_read_b128 v[166:169], v145 offset:1024
	ds_read_b128 v[170:173], v145 offset:2048
	ds_read_b128 v[174:177], v145 offset:3072
	ds_read_b128 v[184:187], v145 offset:4096
	ds_read_b128 v[188:191], v145 offset:5120
	ds_read_b128 v[192:195], v145 offset:6144
	ds_read_b128 v[196:199], v145 offset:7168
	global_load_lds_dwordx4 v[142:143], off
	v_lshl_add_u64 v[142:143], s[14:15], 0, v[140:141]
	s_add_i32 m0, s46, 0xe000
	s_nop 0
	global_load_lds_dwordx4 v[142:143], off
	s_waitcnt lgkmcnt(8)
	s_barrier
	s_waitcnt lgkmcnt(0)
	s_waitcnt lgkmcnt(0)
	v_mfma_f32_16x16x32_bf16 v[124:127], v[146:149], v[162:165], v[124:127]
	v_mfma_f32_16x16x32_bf16 v[120:123], v[154:157], v[162:165], v[120:123]
	v_mfma_f32_16x16x32_bf16 v[116:119], v[146:149], v[170:173], v[116:119]
	v_mfma_f32_16x16x32_bf16 v[108:111], v[154:157], v[170:173], v[108:111]
	v_mfma_f32_16x16x32_bf16 v[100:103], v[146:149], v[184:187], v[100:103]
	v_mfma_f32_16x16x32_bf16 v[92:95], v[154:157], v[184:187], v[92:95]
	v_mfma_f32_16x16x32_bf16 v[84:87], v[146:149], v[192:195], v[84:87]
	v_mfma_f32_16x16x32_bf16 v[76:79], v[154:157], v[192:195], v[76:79]
	v_mfma_f32_16x16x32_bf16 v[124:127], v[150:153], v[166:169], v[124:127]
	v_mfma_f32_16x16x32_bf16 v[120:123], v[158:161], v[166:169], v[120:123]
	v_mfma_f32_16x16x32_bf16 v[116:119], v[150:153], v[174:177], v[116:119]
	v_mfma_f32_16x16x32_bf16 v[108:111], v[158:161], v[174:177], v[108:111]
	v_mfma_f32_16x16x32_bf16 v[100:103], v[150:153], v[188:191], v[100:103]
	v_mfma_f32_16x16x32_bf16 v[92:95], v[158:161], v[188:191], v[92:95]
	v_mfma_f32_16x16x32_bf16 v[84:87], v[150:153], v[196:199], v[84:87]
	v_mfma_f32_16x16x32_bf16 v[76:79], v[158:161], v[196:199], v[76:79]
	s_barrier
	s_add_i32 s82, 0, 0x14000
	v_add_u32_e32 v142, s82, v144
	s_add_i32 s79, s79, s21
	ds_read_b128 v[200:203], v142
	ds_read_b128 v[204:207], v142 offset:1024
	ds_read_b128 v[208:211], v142 offset:2048
	ds_read_b128 v[212:215], v142 offset:3072
	v_lshl_add_u64 v[142:143], s[16:17], 0, v[180:181]
	s_mov_b32 m0, s79
	v_lshl_add_u64 v[178:179], s[16:17], 0, v[128:129]
	global_load_lds_dwordx4 v[142:143], off
	s_add_i32 m0, s79, 0x2000
	s_nop 0
	global_load_lds_dwordx4 v[178:179], off
	s_barrier
	s_waitcnt lgkmcnt(0)
	s_waitcnt lgkmcnt(0)
	v_mfma_f32_16x16x32_bf16 v[112:115], v[200:203], v[162:165], v[112:115]
	v_mfma_f32_16x16x32_bf16 v[104:107], v[208:211], v[162:165], v[104:107]
	v_mfma_f32_16x16x32_bf16 v[96:99], v[200:203], v[170:173], v[96:99]
	v_mfma_f32_16x16x32_bf16 v[88:91], v[208:211], v[170:173], v[88:91]
	v_mfma_f32_16x16x32_bf16 v[80:83], v[200:203], v[184:187], v[80:83]
	v_mfma_f32_16x16x32_bf16 v[72:75], v[208:211], v[184:187], v[72:75]
	v_mfma_f32_16x16x32_bf16 v[68:71], v[200:203], v[192:195], v[68:71]
	v_mfma_f32_16x16x32_bf16 v[64:67], v[208:211], v[192:195], v[64:67]
	v_mfma_f32_16x16x32_bf16 v[112:115], v[204:207], v[166:169], v[112:115]
	v_mfma_f32_16x16x32_bf16 v[104:107], v[212:215], v[166:169], v[104:107]
	v_mfma_f32_16x16x32_bf16 v[96:99], v[204:207], v[174:177], v[96:99]
	v_mfma_f32_16x16x32_bf16 v[88:91], v[212:215], v[174:177], v[88:91]
	v_mfma_f32_16x16x32_bf16 v[80:83], v[204:207], v[188:191], v[80:83]
	v_mfma_f32_16x16x32_bf16 v[72:75], v[212:215], v[188:191], v[72:75]
	v_mfma_f32_16x16x32_bf16 v[68:71], v[204:207], v[196:199], v[68:71]
	v_mfma_f32_16x16x32_bf16 v[64:67], v[212:215], v[196:199], v[64:67]
	s_mov_b32 m0, s46
	v_lshl_add_u64 v[216:217], s[18:19], 0, v[132:133]
	s_barrier
	ds_read_b128 v[162:165], v145 offset:16384
	ds_read_b128 v[166:169], v145 offset:17408
	ds_read_b128 v[170:173], v145 offset:18432
	ds_read_b128 v[174:177], v145 offset:19456
	ds_read_b128 v[184:187], v145 offset:20480
	ds_read_b128 v[188:191], v145 offset:21504
	ds_read_b128 v[192:195], v145 offset:22528
	ds_read_b128 v[196:199], v145 offset:23552
	global_load_lds_dwordx4 v[216:217], off
	v_lshl_add_u64 v[218:219], s[18:19], 0, v[130:131]
	s_mov_b32 m0, s47
	s_nop 0
	global_load_lds_dwordx4 v[218:219], off
	s_barrier
	s_waitcnt lgkmcnt(0)
	s_waitcnt lgkmcnt(0)
	v_mfma_f32_16x16x32_bf16 v[60:63], v[146:149], v[162:165], v[60:63]
	v_mfma_f32_16x16x32_bf16 v[56:59], v[154:157], v[162:165], v[56:59]
	v_mfma_f32_16x16x32_bf16 v[52:55], v[146:149], v[170:173], v[52:55]
	v_mfma_f32_16x16x32_bf16 v[44:47], v[154:157], v[170:173], v[44:47]
	v_mfma_f32_16x16x32_bf16 v[36:39], v[146:149], v[184:187], v[36:39]
	v_mfma_f32_16x16x32_bf16 v[28:31], v[154:157], v[184:187], v[28:31]
	v_mfma_f32_16x16x32_bf16 v[20:23], v[146:149], v[192:195], v[20:23]
	v_mfma_f32_16x16x32_bf16 v[12:15], v[154:157], v[192:195], v[12:15]
	v_mfma_f32_16x16x32_bf16 v[60:63], v[150:153], v[166:169], v[60:63]
	v_mfma_f32_16x16x32_bf16 v[56:59], v[158:161], v[166:169], v[56:59]
	v_mfma_f32_16x16x32_bf16 v[52:55], v[150:153], v[174:177], v[52:55]
	v_mfma_f32_16x16x32_bf16 v[44:47], v[158:161], v[174:177], v[44:47]
	v_mfma_f32_16x16x32_bf16 v[36:39], v[150:153], v[188:191], v[36:39]
	v_mfma_f32_16x16x32_bf16 v[28:31], v[158:161], v[188:191], v[28:31]
	v_mfma_f32_16x16x32_bf16 v[20:23], v[150:153], v[196:199], v[20:23]
	v_mfma_f32_16x16x32_bf16 v[12:15], v[158:161], v[196:199], v[12:15]
	s_barrier
; #define PG8_STAGE(bufoff, gbase, voff) do { _Pragma("unroll") for (int _i = 0; _i < 2; ++_i) \
;         __builtin_amdgcn_global_load_lds((const unsigned*)((const char*)(gbase) + (voff)[_i]), (PG8_LAS unsigned*)(lds + (bufoff) + ldsw + _i * 8192), 16, 0, 0); } while (0)
; #define PG8_LDA(dst, b, h) do { _Pragma("unroll") for (int m = 0; m < 4; ++m) _Pragma("unroll") for (int k = 0; k < 2; ++k) dst[m][k] = *(const PG8_LAS bf16x8*)(lds + PG8_SA(b, h) + aoff + m * 2048 + k * 1024); } while (0)
; #define PG8_LDB(dst, b, h) do { _Pragma("unroll") for (int n = 0; n < 2; ++n) _Pragma("unroll") for (int k = 0; k < 2; ++k) dst[n][k] = *(const PG8_LAS bf16x8*)(lds + PG8_SB(b, h) + boff + n * 2048 + k * 1024); } while (0)
; #define PG8_MMA(ai, bj, At, Bt) do { __builtin_amdgcn_s_setprio(1); _Pragma("unroll") for (int m = 0; m < 4; ++m) _Pragma("unroll") for (int n = 0; n < 2; ++n) _Pragma("unroll") for (int k = 0; k < 2; ++k) \
;         acc[ai][bj][m][n] = __builtin_amdgcn_mfma_f32_16x16x32_bf16(Bt[n][k], At[m][k], acc[ai][bj][m][n], 0, 0, 0); __builtin_amdgcn_s_setprio(0); } while (0)
; #define PG8_WAIT_V(n) asm volatile("s_waitcnt vmcnt(" #n ")" ::: "memory")
; #define PG8_WAIT_L(n) asm volatile("s_waitcnt lgkmcnt(" #n ")" ::: "memory")
; #define PG8_BAR __builtin_amdgcn_s_barrier()
; #define PG8_SCHED __builtin_amdgcn_sched_barrier(0)
; template <class Epi, class Sched>
; __device__ __forceinline__ void gemm_phase(PG8_LAS unsigned char* lds, const Gemm g, const Sched& S, const Epi& E) {
;     ...
;             PG8_STAGE(PG8_SB(0, 1), b2 + hstep, voffB);
;             PG8_WAIT_V(6); PG8_BAR; PG8_MMA(1, 1, At, B1); PG8_BAR;
;             PG8_LDB(B0, 1, 0); PG8_SCHED; PG8_LDA(At, 1, 0); PG8_STAGE(PG8_SA(0, 1), a2 + hstep, voffA);
;             PG8_WAIT_L(8); PG8_BAR; PG8_WAIT_L(0); PG8_MMA(0, 0, At, B0); PG8_BAR; PG8_SCHED;
;             PG8_LDB(B1, 1, 1); PG8_STAGE(PG8_SB(1, 0), b3, voffB);
;             PG8_BAR; PG8_WAIT_L(0); PG8_MMA(0, 1, At, B1); PG8_BAR;
;             PG8_LDA(At, 1, 1); PG8_STAGE(PG8_SA(1, 0), a3, voffA);
	s_add_u32 s80, s16, 0x40000
	s_addc_u32 s81, s17, 0
	s_add_i32 s79, s82, s21
	v_lshl_add_u64 v[146:147], s[80:81], 0, v[180:181]
	s_mov_b32 m0, s79
	s_nop 0
	global_load_lds_dwordx4 v[146:147], off
	v_lshl_add_u64 v[146:147], s[80:81], 0, v[128:129]
	s_add_i32 m0, s79, 0x2000
	s_nop 0
	global_load_lds_dwordx4 v[146:147], off
	s_waitcnt vmcnt(6)
	s_barrier
	v_mfma_f32_16x16x32_bf16 v[48:51], v[200:203], v[162:165], v[48:51]
	v_mfma_f32_16x16x32_bf16 v[40:43], v[208:211], v[162:165], v[40:43]
	v_mfma_f32_16x16x32_bf16 v[32:35], v[200:203], v[170:173], v[32:35]
	v_mfma_f32_16x16x32_bf16 v[24:27], v[208:211], v[170:173], v[24:27]
	v_mfma_f32_16x16x32_bf16 v[16:19], v[200:203], v[184:187], v[16:19]
	v_mfma_f32_16x16x32_bf16 v[8:11], v[208:211], v[184:187], v[8:11]
	v_mfma_f32_16x16x32_bf16 v[4:7], v[200:203], v[192:195], v[4:7]
	v_mfma_f32_16x16x32_bf16 v[0:3], v[208:211], v[192:195], v[0:3]
	v_mfma_f32_16x16x32_bf16 v[48:51], v[204:207], v[166:169], v[48:51]
	v_mfma_f32_16x16x32_bf16 v[40:43], v[212:215], v[166:169], v[40:43]
	v_mfma_f32_16x16x32_bf16 v[32:35], v[204:207], v[174:177], v[32:35]
	v_mfma_f32_16x16x32_bf16 v[24:27], v[212:215], v[174:177], v[24:27]
	v_mfma_f32_16x16x32_bf16 v[16:19], v[204:207], v[188:191], v[16:19]
	v_mfma_f32_16x16x32_bf16 v[8:11], v[212:215], v[188:191], v[8:11]
	v_mfma_f32_16x16x32_bf16 v[4:7], v[204:207], v[196:199], v[4:7]
	v_mfma_f32_16x16x32_bf16 v[0:3], v[212:215], v[196:199], v[0:3]
	s_add_i32 s79, 0, 0x18000
	v_add_u32_e32 v158, s79, v144
	s_barrier
	ds_read_b128 v[146:149], v158
	ds_read_b128 v[150:153], v158 offset:1024
	ds_read_b128 v[154:157], v158 offset:2048
	ds_read_b128 v[158:161], v158 offset:3072
	s_add_u32 s18, s18, 0x40000
	s_addc_u32 s19, s19, 0
	s_mov_b32 m0, s69
	v_lshl_add_u64 v[200:201], s[18:19], 0, v[132:133]
	ds_read_b128 v[162:165], v145 offset:32768
	ds_read_b128 v[166:169], v145 offset:33792
	ds_read_b128 v[170:173], v145 offset:34816
	ds_read_b128 v[174:177], v145 offset:35840
	ds_read_b128 v[184:187], v145 offset:36864
	ds_read_b128 v[188:191], v145 offset:37888
	ds_read_b128 v[192:195], v145 offset:38912
	ds_read_b128 v[196:199], v145 offset:39936
	global_load_lds_dwordx4 v[200:201], off
	v_lshl_add_u64 v[200:201], s[18:19], 0, v[130:131]
	s_mov_b32 m0, s70
	s_nop 0
	global_load_lds_dwordx4 v[200:201], off
	s_waitcnt lgkmcnt(8)
	s_barrier
	s_waitcnt lgkmcnt(0)
	s_waitcnt lgkmcnt(0)
	v_mfma_f32_16x16x32_bf16 v[124:127], v[146:149], v[162:165], v[124:127]
	v_mfma_f32_16x16x32_bf16 v[120:123], v[154:157], v[162:165], v[120:123]
	v_mfma_f32_16x16x32_bf16 v[116:119], v[146:149], v[170:173], v[116:119]
	v_mfma_f32_16x16x32_bf16 v[108:111], v[154:157], v[170:173], v[108:111]
	v_mfma_f32_16x16x32_bf16 v[100:103], v[146:149], v[184:187], v[100:103]
	v_mfma_f32_16x16x32_bf16 v[92:95], v[154:157], v[184:187], v[92:95]
	v_mfma_f32_16x16x32_bf16 v[84:87], v[146:149], v[192:195], v[84:87]
	v_mfma_f32_16x16x32_bf16 v[76:79], v[154:157], v[192:195], v[76:79]
	v_mfma_f32_16x16x32_bf16 v[124:127], v[150:153], v[166:169], v[124:127]
	v_mfma_f32_16x16x32_bf16 v[120:123], v[158:161], v[166:169], v[120:123]
	v_mfma_f32_16x16x32_bf16 v[116:119], v[150:153], v[174:177], v[116:119]
	v_mfma_f32_16x16x32_bf16 v[108:111], v[158:161], v[174:177], v[108:111]
	v_mfma_f32_16x16x32_bf16 v[100:103], v[150:153], v[188:191], v[100:103]
	v_mfma_f32_16x16x32_bf16 v[92:95], v[158:161], v[188:191], v[92:95]
	v_mfma_f32_16x16x32_bf16 v[84:87], v[150:153], v[196:199], v[84:87]
	v_mfma_f32_16x16x32_bf16 v[76:79], v[158:161], v[196:199], v[76:79]
	s_barrier
	s_add_i32 s18, 0, 0x1c000
	s_add_i32 s19, s79, s21
	v_add_u32_e32 v212, s18, v144
	v_lshl_add_u64 v[142:143], v[142:143], 0, s[38:39]
	s_mov_b32 m0, s19
	ds_read_b128 v[200:203], v212
	ds_read_b128 v[204:207], v212 offset:1024
	ds_read_b128 v[208:211], v212 offset:2048
	ds_read_b128 v[212:215], v212 offset:3072
	global_load_lds_dwordx4 v[142:143], off
	v_lshl_add_u64 v[142:143], v[178:179], 0, s[38:39]
	s_add_i32 m0, s19, 0x2000
	s_nop 0
	global_load_lds_dwordx4 v[142:143], off
	s_barrier
	s_waitcnt lgkmcnt(0)
	s_waitcnt lgkmcnt(0)
	v_mfma_f32_16x16x32_bf16 v[112:115], v[200:203], v[162:165], v[112:115]
	v_mfma_f32_16x16x32_bf16 v[104:107], v[208:211], v[162:165], v[104:107]
	v_mfma_f32_16x16x32_bf16 v[96:99], v[200:203], v[170:173], v[96:99]
	v_mfma_f32_16x16x32_bf16 v[88:91], v[208:211], v[170:173], v[88:91]
	v_mfma_f32_16x16x32_bf16 v[80:83], v[200:203], v[184:187], v[80:83]
	v_mfma_f32_16x16x32_bf16 v[72:75], v[208:211], v[184:187], v[72:75]
	v_mfma_f32_16x16x32_bf16 v[68:71], v[200:203], v[192:195], v[68:71]
	v_mfma_f32_16x16x32_bf16 v[64:67], v[208:211], v[192:195], v[64:67]
	v_mfma_f32_16x16x32_bf16 v[112:115], v[204:207], v[166:169], v[112:115]
	v_mfma_f32_16x16x32_bf16 v[104:107], v[212:215], v[166:169], v[104:107]
	v_mfma_f32_16x16x32_bf16 v[96:99], v[204:207], v[174:177], v[96:99]
	v_mfma_f32_16x16x32_bf16 v[88:91], v[212:215], v[174:177], v[88:91]
	v_mfma_f32_16x16x32_bf16 v[80:83], v[204:207], v[188:191], v[80:83]
	v_mfma_f32_16x16x32_bf16 v[72:75], v[212:215], v[188:191], v[72:75]
	v_mfma_f32_16x16x32_bf16 v[68:71], v[204:207], v[196:199], v[68:71]
	v_mfma_f32_16x16x32_bf16 v[64:67], v[212:215], v[196:199], v[64:67]
	s_mov_b32 m0, s71
	v_lshl_add_u64 v[142:143], v[216:217], 0, s[38:39]
	s_barrier
	ds_read_b128 v[162:165], v145 offset:49152
	ds_read_b128 v[166:169], v145 offset:50176
	ds_read_b128 v[170:173], v145 offset:51200
	ds_read_b128 v[174:177], v145 offset:52224
	ds_read_b128 v[184:187], v145 offset:53248
	ds_read_b128 v[188:191], v145 offset:54272
	ds_read_b128 v[192:195], v145 offset:55296
	ds_read_b128 v[196:199], v145 offset:56320
	global_load_lds_dwordx4 v[142:143], off
	v_lshl_add_u64 v[142:143], v[218:219], 0, s[38:39]
	s_mov_b32 m0, s72
	s_nop 0
	global_load_lds_dwordx4 v[142:143], off
	s_barrier
; #define PG8_STAGE(bufoff, gbase, voff) do { _Pragma("unroll") for (int _i = 0; _i < 2; ++_i) \
;         __builtin_amdgcn_global_load_lds((const unsigned*)((const char*)(gbase) + (voff)[_i]), (PG8_LAS unsigned*)(lds + (bufoff) + ldsw + _i * 8192), 16, 0, 0); } while (0)
; #define PG8_MMA(ai, bj, At, Bt) do { __builtin_amdgcn_s_setprio(1); _Pragma("unroll") for (int m = 0; m < 4; ++m) _Pragma("unroll") for (int n = 0; n < 2; ++n) _Pragma("unroll") for (int k = 0; k < 2; ++k) \
;         acc[ai][bj][m][n] = __builtin_amdgcn_mfma_f32_16x16x32_bf16(Bt[n][k], At[m][k], acc[ai][bj][m][n], 0, 0, 0); __builtin_amdgcn_s_setprio(0); } while (0)
; #define PG8_WAIT_V(n) asm volatile("s_waitcnt vmcnt(" #n ")" ::: "memory")
; #define PG8_WAIT_L(n) asm volatile("s_waitcnt lgkmcnt(" #n ")" ::: "memory")
; #define PG8_BAR __builtin_amdgcn_s_barrier()
; #define PG8_SCHED __builtin_amdgcn_sched_barrier(0)
; DI void store8(bf16_t* p, f32x4 a, f32x4 b) { u32x4 w = {cvt_pk_bf16(a[0], a[1]), cvt_pk_bf16(a[2], a[3]), cvt_pk_bf16(b[0], b[1]), cvt_pk_bf16(b[2], b[3])}; *(u32x4*)p = w; }
; template <class Epi, class Sched>
; __device__ __forceinline__ void gemm_phase(PG8_LAS unsigned char* lds, const Gemm g, const Sched& S, const Epi& E) {
;     ...
;             PG8_BAR; PG8_WAIT_L(0); PG8_MMA(1, 0, At, B0); PG8_BAR; PG8_SCHED;
;             PG8_STAGE(PG8_SB(1, 1), b3 + hstep, voffB);
;             PG8_WAIT_V(6); PG8_BAR; PG8_MMA(1, 1, At, B1); PG8_BAR;
;     DI void operator()(const AccT& acc, const pg8::Unit& u, int wr, int wc, int fr, int fq) const {
;         bf16_t* dst = o + u.pn * 256 + wc * 32 + 8 * fq;
; #pragma unroll
;         for (int ai = 0; ai < 2; ++ai)
; #pragma unroll
;             for (int m = 0; m < 4; ++m) { const size_t row = (size_t)u.pm * 256 + wr * 64 + fr + ai * 128 + m * 16;
; #pragma unroll
;                 for (int bj = 0; bj < 2; ++bj) store8(dst + row * ldc + bj * 128, acc[ai][bj][m][0], acc[ai][bj][m][1]); }
;     }
	s_waitcnt lgkmcnt(0)
	s_waitcnt lgkmcnt(0)
	v_mfma_f32_16x16x32_bf16 v[60:63], v[146:149], v[162:165], v[60:63]
	v_mfma_f32_16x16x32_bf16 v[56:59], v[154:157], v[162:165], v[56:59]
	v_mfma_f32_16x16x32_bf16 v[52:55], v[146:149], v[170:173], v[52:55]
	v_mfma_f32_16x16x32_bf16 v[44:47], v[154:157], v[170:173], v[44:47]
	v_mfma_f32_16x16x32_bf16 v[36:39], v[146:149], v[184:187], v[36:39]
	v_mfma_f32_16x16x32_bf16 v[28:31], v[154:157], v[184:187], v[28:31]
	v_mfma_f32_16x16x32_bf16 v[20:23], v[146:149], v[192:195], v[20:23]
	v_mfma_f32_16x16x32_bf16 v[12:15], v[154:157], v[192:195], v[12:15]
	v_mfma_f32_16x16x32_bf16 v[60:63], v[150:153], v[166:169], v[60:63]
	v_mfma_f32_16x16x32_bf16 v[56:59], v[158:161], v[166:169], v[56:59]
	v_mfma_f32_16x16x32_bf16 v[52:55], v[150:153], v[174:177], v[52:55]
	v_mfma_f32_16x16x32_bf16 v[44:47], v[158:161], v[174:177], v[44:47]
	v_mfma_f32_16x16x32_bf16 v[36:39], v[150:153], v[188:191], v[36:39]
	v_mfma_f32_16x16x32_bf16 v[28:31], v[158:161], v[188:191], v[28:31]
	v_mfma_f32_16x16x32_bf16 v[20:23], v[150:153], v[196:199], v[20:23]
	v_mfma_f32_16x16x32_bf16 v[12:15], v[158:161], v[196:199], v[12:15]
	s_barrier
	s_add_u32 s16, s16, 0x40080
	s_addc_u32 s17, s17, 0
	s_add_i32 s18, s18, s21
	v_lshl_add_u64 v[142:143], s[16:17], 0, v[180:181]
	s_mov_b32 m0, s18
	s_nop 0
	global_load_lds_dwordx4 v[142:143], off
	v_lshl_add_u64 v[142:143], s[16:17], 0, v[128:129]
	s_add_i32 m0, s18, 0x2000
	s_nop 0
	global_load_lds_dwordx4 v[142:143], off
	s_waitcnt vmcnt(6)
	s_barrier
	v_mfma_f32_16x16x32_bf16 v[48:51], v[200:203], v[162:165], v[48:51]
	v_mfma_f32_16x16x32_bf16 v[40:43], v[208:211], v[162:165], v[40:43]
	v_mfma_f32_16x16x32_bf16 v[32:35], v[200:203], v[170:173], v[32:35]
	v_mfma_f32_16x16x32_bf16 v[24:27], v[208:211], v[170:173], v[24:27]
	v_mfma_f32_16x16x32_bf16 v[16:19], v[200:203], v[184:187], v[16:19]
	v_mfma_f32_16x16x32_bf16 v[8:11], v[208:211], v[184:187], v[8:11]
	v_mfma_f32_16x16x32_bf16 v[4:7], v[200:203], v[192:195], v[4:7]
	v_mfma_f32_16x16x32_bf16 v[0:3], v[208:211], v[192:195], v[0:3]
	v_mfma_f32_16x16x32_bf16 v[48:51], v[204:207], v[166:169], v[48:51]
	v_mfma_f32_16x16x32_bf16 v[40:43], v[212:215], v[166:169], v[40:43]
	v_mfma_f32_16x16x32_bf16 v[32:35], v[204:207], v[174:177], v[32:35]
	v_mfma_f32_16x16x32_bf16 v[24:27], v[212:215], v[174:177], v[24:27]
	v_mfma_f32_16x16x32_bf16 v[16:19], v[204:207], v[188:191], v[16:19]
	v_mfma_f32_16x16x32_bf16 v[8:11], v[212:215], v[188:191], v[8:11]
	v_mfma_f32_16x16x32_bf16 v[4:7], v[204:207], v[196:199], v[4:7]
	v_mfma_f32_16x16x32_bf16 v[0:3], v[212:215], v[196:199], v[0:3]
	s_add_i32 s78, s78, 2
	s_add_u32 s14, s14, 0x100
	s_addc_u32 s15, s15, 0
	s_add_u32 s76, s76, 0x100
	s_addc_u32 s77, s77, 0
	s_cmp_gt_u32 s78, 13
	s_barrier
	s_cbranch_scc0 .LBB0_912
	s_lshl_b32 s14, s13, 8
	s_ashr_i32 s15, s14, 31
	s_ashr_i32 s13, s12, 31
	v_lshl_add_u64 v[142:143], s[14:15], 1, v[134:135]
	s_lshl_b64 s[12:13], s[12:13], 19
	v_lshl_add_u64 v[142:143], v[142:143], 0, s[12:13]
	v_lshl_add_u64 v[142:143], v[142:143], 0, v[136:137]
	s_mov_b32 s5, 0x8000
	v_cvt_pk_bf16_f32 v124, v124, v125
	v_cvt_pk_bf16_f32 v125, v126, v127
	v_cvt_pk_bf16_f32 v126, v120, v121
	v_cvt_pk_bf16_f32 v127, v122, v123
	global_store_dwordx4 v[142:143], v[124:127], off
	v_cvt_pk_bf16_f32 v112, v112, v113
	v_cvt_pk_bf16_f32 v113, v114, v115
	v_cvt_pk_bf16_f32 v114, v104, v105
	v_cvt_pk_bf16_f32 v115, v106, v107
	global_store_dwordx4 v[142:143], v[112:115], off offset:256
	v_cvt_pk_bf16_f32 v104, v116, v117
	v_cvt_pk_bf16_f32 v105, v118, v119
	v_cvt_pk_bf16_f32 v106, v108, v109
	v_add_co_u32_e32 v108, vcc, s5, v142
	s_mov_b32 s5, 0x10000
	s_nop 0
	v_addc_co_u32_e32 v109, vcc, 0, v143, vcc
	v_cvt_pk_bf16_f32 v107, v110, v111
	global_store_dwordx4 v[108:109], v[104:107], off
	v_cvt_pk_bf16_f32 v96, v96, v97
	v_cvt_pk_bf16_f32 v97, v98, v99
	v_cvt_pk_bf16_f32 v98, v88, v89
	v_cvt_pk_bf16_f32 v99, v90, v91
	global_store_dwordx4 v[108:109], v[96:99], off offset:256
	v_cvt_pk_bf16_f32 v88, v100, v101
	v_cvt_pk_bf16_f32 v89, v102, v103
	v_cvt_pk_bf16_f32 v90, v92, v93
	v_add_co_u32_e32 v92, vcc, s5, v142
	s_mov_b32 s5, 0x18000
	s_nop 0
	v_addc_co_u32_e32 v93, vcc, 0, v143, vcc
	v_cvt_pk_bf16_f32 v91, v94, v95
	global_store_dwordx4 v[92:93], v[88:91], off
	v_cvt_pk_bf16_f32 v80, v80, v81
	v_cvt_pk_bf16_f32 v81, v82, v83
	v_cvt_pk_bf16_f32 v82, v72, v73
	v_cvt_pk_bf16_f32 v83, v74, v75
	global_store_dwordx4 v[92:93], v[80:83], off offset:256
	v_cvt_pk_bf16_f32 v72, v84, v85
	v_cvt_pk_bf16_f32 v73, v86, v87
	v_cvt_pk_bf16_f32 v74, v76, v77
	v_add_co_u32_e32 v76, vcc, s5, v142
	s_mov_b32 s5, 0x40000
	s_nop 0
	v_addc_co_u32_e32 v77, vcc, 0, v143, vcc
	v_cvt_pk_bf16_f32 v75, v78, v79
	global_store_dwordx4 v[76:77], v[72:75], off
	v_cvt_pk_bf16_f32 v68, v68, v69
	v_cvt_pk_bf16_f32 v69, v70, v71
	v_cvt_pk_bf16_f32 v70, v64, v65
	v_cvt_pk_bf16_f32 v71, v66, v67
	global_store_dwordx4 v[76:77], v[68:71], off offset:256
	v_cvt_pk_bf16_f32 v60, v60, v61
	v_cvt_pk_bf16_f32 v61, v62, v63
	v_cvt_pk_bf16_f32 v62, v56, v57
	v_add_co_u32_e32 v56, vcc, s5, v142
	s_mov_b32 s5, 0x48000
	s_nop 0
	v_addc_co_u32_e32 v57, vcc, 0, v143, vcc
	v_cvt_pk_bf16_f32 v63, v58, v59
	global_store_dwordx4 v[56:57], v[60:63], off
	v_cvt_pk_bf16_f32 v48, v48, v49
	v_cvt_pk_bf16_f32 v49, v50, v51
	v_cvt_pk_bf16_f32 v50, v40, v41
	v_cvt_pk_bf16_f32 v51, v42, v43
	global_store_dwordx4 v[56:57], v[48:51], off offset:256
	v_cvt_pk_bf16_f32 v40, v52, v53
	v_cvt_pk_bf16_f32 v41, v54, v55
	v_cvt_pk_bf16_f32 v42, v44, v45
	v_add_co_u32_e32 v44, vcc, s5, v142
	s_mov_b32 s5, 0x50000
	s_nop 0
	v_addc_co_u32_e32 v45, vcc, 0, v143, vcc
	v_cvt_pk_bf16_f32 v43, v46, v47
	global_store_dwordx4 v[44:45], v[40:43], off
	v_cvt_pk_bf16_f32 v32, v32, v33
	v_cvt_pk_bf16_f32 v33, v34, v35
	v_cvt_pk_bf16_f32 v34, v24, v25
	v_cvt_pk_bf16_f32 v35, v26, v27
	global_store_dwordx4 v[44:45], v[32:35], off offset:256
	v_cvt_pk_bf16_f32 v24, v36, v37
	v_cvt_pk_bf16_f32 v25, v38, v39
	v_cvt_pk_bf16_f32 v26, v28, v29
	v_add_co_u32_e32 v28, vcc, s5, v142
	s_mov_b32 s5, 0x58000
	s_nop 0
	v_addc_co_u32_e32 v29, vcc, 0, v143, vcc
	v_cvt_pk_bf16_f32 v27, v30, v31
	global_store_dwordx4 v[28:29], v[24:27], off
	v_cvt_pk_bf16_f32 v16, v16, v17
	v_cvt_pk_bf16_f32 v17, v18, v19
	v_cvt_pk_bf16_f32 v18, v8, v9
	v_cvt_pk_bf16_f32 v19, v10, v11
	global_store_dwordx4 v[28:29], v[16:19], off offset:256
	v_cvt_pk_bf16_f32 v8, v20, v21
	v_cvt_pk_bf16_f32 v9, v22, v23
	v_cvt_pk_bf16_f32 v10, v12, v13
	v_add_co_u32_e32 v12, vcc, s5, v142
	s_mov_b32 s13, s4
	s_nop 0
	v_addc_co_u32_e32 v13, vcc, 0, v143, vcc
	s_and_b64 vcc, exec, s[0:1]
	s_mov_b32 s12, s6
	s_mov_b64 s[16:17], s[10:11]
	s_mov_b64 s[14:15], s[8:9]
	v_cvt_pk_bf16_f32 v11, v14, v15
	global_store_dwordx4 v[12:13], v[8:11], off
	v_cvt_pk_bf16_f32 v4, v4, v5
	v_cvt_pk_bf16_f32 v5, v6, v7
	v_cvt_pk_bf16_f32 v6, v0, v1
	v_cvt_pk_bf16_f32 v7, v2, v3
	global_store_dwordx4 v[12:13], v[4:7], off offset:256
	s_cbranch_vccz .LBB0_909
	s_waitcnt vmcnt(0)
	s_cmpk_gt_u32 s20, 0xff
	s_cbranch_scc1 .LBB0_916
	s_barrier
